# all GEMM epilogue stores (z, qkv, hb, ssq, act) write-through sc1
# baseline (speedup 1.0000x reference)
;     __device__ __forceinline__ void operator()(const f32x4 (&acc)[2][2][4][2], const Unit& u, int wr, int wc, int fr, int fq) const {
;     ...
;         int colt = u.pn * BM; bf16_t* base = O; float sc = 1.f;
;         if (split_cols) { const int t = colt / split_cols; base += (size_t)t * split_stride; colt -= t * split_cols; if (t == 0) sc = scale0; }
;         const int col0 = colt + wc * 32 + 8 * fq;
;         float rsv[2][4];
; #pragma unroll
;         for (int ai = 0; ai < 2; ++ai)
; #pragma unroll
;             for (int m = 0; m < 4; ++m) rsv[ai][m] = row_rstd(ssq, row0 + ai * HALF + m * 16 + row_off) * sc;
.LBB0_188:
	v_add_u32_e32 v233, s46, v1
	v_lshlrev_b32_e32 v233, 4, v233
	v_add_u32_e32 v233, 0x21000, v233
	s_lshl_b32 s5, s5, 8
	v_mov_b32_e32 v155, v149
	v_mov_b32_e32 v130, v1
	s_add_i32 s5, s5, s46
	s_cmp_lg_u32 s4, 12
	v_add_u32_e32 v146, s5, v130
	s_mov_b64 s[28:29], -1
	s_cbranch_scc0 .LBB0_191
	s_ashr_i32 s21, s4, 31
	s_lshr_b32 s21, s21, 30
	s_add_i32 s21, s4, s21
	s_ashr_i32 s30, s21, 2
	s_ashr_i32 s31, s30, 31
	s_lshl_b32 s5, s4, 8
	s_lshl_b64 s[28:29], s[30:31], 26
	s_add_u32 s28, s44, s28
	s_addc_u32 s29, s45, s29
	s_add_i32 s4, s4, 3
	s_cmp_lt_u32 s4, 7
	s_cselect_b64 vcc, -1, 0
	v_mov_b32_e32 v130, 0x3e38aa3b
	v_ashrrev_i32_e32 v147, 31, v146
	v_cndmask_b32_e32 v157, 1.0, v130, vcc
	ds_read_b128 v[130:133], v233
	v_add_u32_e32 v180, 16, v146
	v_ashrrev_i32_e32 v181, 31, v180
	v_add_u32_e32 v172, 32, v146
	v_ashrrev_i32_e32 v173, 31, v172
	v_add_u32_e32 v170, 48, v146
	v_ashrrev_i32_e32 v171, 31, v170
	v_add_u32_e32 v168, 0x80, v146
	v_ashrrev_i32_e32 v169, 31, v168
	v_add_u32_e32 v166, 0x90, v146
	v_ashrrev_i32_e32 v167, 31, v166
	v_add_u32_e32 v164, 0xa0, v146
	v_ashrrev_i32_e32 v165, 31, v164
	s_or_b32 s4, s5, s47
	s_lshl_b32 s5, s30, 10
	s_sub_i32 s4, s4, s5
	s_waitcnt lgkmcnt(0)
	v_mov_b32_e32 v158, v131
	v_mov_b32_e32 v159, v132
	v_mov_b32_e32 v131, v133
	v_pk_add_f32 v[130:131], v[158:159], v[130:131]
	s_nop 0
	v_add_f32_e32 v130, v130, v131
	v_fmamk_f32 v130, v130, 0x3a800000, v175
	v_rsq_f32_e32 v130, v130
	s_nop 0
	v_mul_f32_e32 v160, v157, v130
	ds_read_b128 v[130:133], v233 offset:256
	v_pk_mul_f32 v[184:185], v[72:73], v[160:161] op_sel_hi:[1,0]
	v_pk_mul_f32 v[188:189], v[68:69], v[160:161] op_sel_hi:[1,0]
	v_pk_mul_f32 v[190:191], v[66:67], v[160:161] op_sel_hi:[1,0]
	v_pk_mul_f32 v[128:129], v[128:129], v[160:161] op_sel_hi:[1,0]
	v_pk_mul_f32 v[126:127], v[126:127], v[160:161] op_sel_hi:[1,0]
	s_waitcnt lgkmcnt(0)
	v_mov_b32_e32 v158, v131
	v_mov_b32_e32 v159, v132
	v_mov_b32_e32 v131, v133
	v_pk_add_f32 v[130:131], v[158:159], v[130:131]
	s_nop 0
	v_add_f32_e32 v130, v130, v131
	v_fmamk_f32 v130, v130, 0x3a800000, v175
	v_rsq_f32_e32 v130, v130
	s_nop 0
	v_mul_f32_e32 v162, v157, v130
	ds_read_b128 v[130:133], v233 offset:512
	v_pk_mul_f32 v[120:121], v[120:121], v[162:163] op_sel_hi:[1,0]
	v_pk_mul_f32 v[118:119], v[118:119], v[162:163] op_sel_hi:[1,0]
	s_waitcnt lgkmcnt(0)
	v_mov_b32_e32 v158, v131
	v_mov_b32_e32 v159, v132
	v_mov_b32_e32 v131, v133
	v_pk_add_f32 v[130:131], v[158:159], v[130:131]
	s_nop 0
	v_add_f32_e32 v130, v130, v131
	v_fmamk_f32 v130, v130, 0x3a800000, v175
	v_rsq_f32_e32 v130, v130
	s_nop 0
	v_mul_f32_e32 v154, v157, v130
	ds_read_b128 v[130:133], v233 offset:768
	v_pk_mul_f32 v[112:113], v[112:113], v[154:155] op_sel_hi:[1,0]
	v_pk_mul_f32 v[110:111], v[110:111], v[154:155] op_sel_hi:[1,0]
	s_waitcnt lgkmcnt(0)
	v_mov_b32_e32 v158, v131
	v_mov_b32_e32 v159, v132
	v_mov_b32_e32 v131, v133
	v_pk_add_f32 v[130:131], v[158:159], v[130:131]
	s_nop 0
	v_add_f32_e32 v130, v130, v131
	v_fmamk_f32 v130, v130, 0x3a800000, v175
	v_rsq_f32_e32 v130, v130
	s_nop 0
	v_mul_f32_e32 v156, v157, v130
	ds_read_b128 v[130:133], v233 offset:2048
	v_pk_mul_f32 v[104:105], v[104:105], v[156:157] op_sel_hi:[1,0]
	v_pk_mul_f32 v[102:103], v[102:103], v[156:157] op_sel_hi:[1,0]
	s_waitcnt lgkmcnt(0)
	v_mov_b32_e32 v158, v131
	v_mov_b32_e32 v159, v132
	v_mov_b32_e32 v131, v133
	v_pk_add_f32 v[130:131], v[158:159], v[130:131]
	s_nop 0
	v_add_f32_e32 v130, v130, v131
	v_fmamk_f32 v130, v130, 0x3a800000, v175
	v_rsq_f32_e32 v130, v130
	s_nop 0
	v_mul_f32_e32 v152, v157, v130
	ds_read_b128 v[130:133], v233 offset:2304
	v_pk_mul_f32 v[96:97], v[96:97], v[152:153] op_sel_hi:[1,0]
	v_pk_mul_f32 v[94:95], v[94:95], v[152:153] op_sel_hi:[1,0]
	s_waitcnt lgkmcnt(0)
	v_mov_b32_e32 v158, v131
	v_mov_b32_e32 v159, v132
	v_mov_b32_e32 v131, v133
	v_pk_add_f32 v[130:131], v[158:159], v[130:131]
	s_nop 0
	v_add_f32_e32 v130, v130, v131
	v_fmamk_f32 v130, v130, 0x3a800000, v175
	v_rsq_f32_e32 v130, v130
	s_nop 0
	v_mul_f32_e32 v150, v157, v130
	ds_read_b128 v[130:133], v233 offset:2560
	v_pk_mul_f32 v[88:89], v[88:89], v[150:151] op_sel_hi:[1,0]
	v_pk_mul_f32 v[86:87], v[86:87], v[150:151] op_sel_hi:[1,0]
	s_waitcnt lgkmcnt(0)
	v_mov_b32_e32 v158, v131
	v_mov_b32_e32 v159, v132
	v_mov_b32_e32 v131, v133
	v_pk_add_f32 v[130:131], v[158:159], v[130:131]
	v_add_u32_e32 v158, 0xb0, v146
	v_add_f32_e32 v130, v130, v131
	v_fmamk_f32 v130, v130, 0x3a800000, v175
	v_rsq_f32_e32 v130, v130
	v_ashrrev_i32_e32 v159, 31, v158
	v_mul_f32_e32 v148, v157, v130
	ds_read_b128 v[130:133], v233 offset:2816
	v_pk_mul_f32 v[80:81], v[80:81], v[148:149] op_sel_hi:[1,0]
	v_pk_mul_f32 v[78:79], v[78:79], v[148:149] op_sel_hi:[1,0]
	s_waitcnt lgkmcnt(0)
; __device__ __forceinline__ unsigned cvt_pk_bf16(float lo, float hi) { unsigned r; asm volatile("v_cvt_pk_bf16_f32 %0, %1, %2" : "=v"(r) : "v"(lo), "v"(hi)); return r; }
;     __device__ __forceinline__ void operator()(const f32x4 (&acc)[2][2][4][2], const Unit& u, int wr, int wc, int fr, int fq) const {
;     ...
;             for (int m = 0; m < 4; ++m) rsv[ai][m] = row_rstd(ssq, row0 + ai * HALF + m * 16 + row_off) * sc;
; #pragma unroll
;         for (int ai = 0; ai < 2; ++ai)
; #pragma unroll
;             for (int m = 0; m < 4; ++m) { const int row = row0 + ai * HALF + m * 16; const float rs = rsv[ai][m]; bf16_t* rowp = base + (size_t)row * ldc + col0;
; #pragma unroll
;                 for (int bj = 0; bj < 2; ++bj) { const f32x4 v0 = acc[ai][bj][m][0] * rs, v1 = acc[ai][bj][m][1] * rs;
;                     u32x4 w; w.x = cvt_pk_bf16(v0[0], v0[1]); w.y = cvt_pk_bf16(v0[2], v0[3]); w.z = cvt_pk_bf16(v1[0], v1[1]); w.w = cvt_pk_bf16(v1[2], v1[3]);
;                     *(u32x4*)(rowp + bj * HALF) = w; } asm volatile("" ::: "memory"); }
	v_mov_b32_e32 v183, v132
	v_lshl_add_u32 v132, v155, 3, s4
	v_mov_b32_e32 v182, v131
	v_mov_b32_e32 v131, v133
	v_ashrrev_i32_e32 v133, 31, v132
	v_pk_add_f32 v[130:131], v[182:183], v[130:131]
	v_lshl_add_u64 v[132:133], v[132:133], 1, s[28:29]
	v_lshlrev_b64 v[182:183], 11, v[146:147]
	v_lshl_add_u64 v[186:187], v[132:133], 0, v[182:183]
	v_pk_mul_f32 v[182:183], v[70:71], v[160:161] op_sel_hi:[1,0]
	v_add_f32_e32 v130, v130, v131
	v_cvt_pk_bf16_f32 v182, v182, v183
	v_cvt_pk_bf16_f32 v183, v184, v185
	v_cvt_pk_bf16_f32 v184, v190, v191
	v_cvt_pk_bf16_f32 v185, v188, v189
	global_store_dwordx4 v[186:187], v[182:185], off sc1
	v_fmamk_f32 v130, v130, 0x3a800000, v175
	v_rsq_f32_e32 v130, v130
	v_pk_mul_f32 v[182:183], v[124:125], v[160:161] op_sel_hi:[1,0]
	v_pk_mul_f32 v[124:125], v[122:123], v[160:161] op_sel_hi:[1,0]
	v_cvt_pk_bf16_f32 v122, v126, v127
	v_cvt_pk_bf16_f32 v123, v128, v129
	v_pk_mul_f32 v[128:129], v[60:61], v[162:163] op_sel_hi:[1,0]
	v_cvt_pk_bf16_f32 v124, v124, v125
	v_cvt_pk_bf16_f32 v125, v182, v183
	global_store_dwordx4 v[186:187], v[122:125], off offset:256 sc1
	v_pk_mul_f32 v[160:161], v[58:59], v[162:163] op_sel_hi:[1,0]
	v_mul_f32_e32 v130, v157, v130
	v_lshlrev_b64 v[122:123], 11, v[180:181]
	v_lshl_add_u64 v[126:127], v[132:133], 0, v[122:123]
	v_pk_mul_f32 v[122:123], v[62:63], v[162:163] op_sel_hi:[1,0]
	v_pk_mul_f32 v[124:125], v[64:65], v[162:163] op_sel_hi:[1,0]
	v_cvt_pk_bf16_f32 v122, v122, v123
	v_pk_mul_f32 v[40:41], v[40:41], v[130:131] op_sel_hi:[1,0]
	v_cvt_pk_bf16_f32 v123, v124, v125
	v_cvt_pk_bf16_f32 v124, v160, v161
	v_cvt_pk_bf16_f32 v125, v128, v129
	global_store_dwordx4 v[126:127], v[122:125], off sc1
	v_pk_mul_f32 v[38:39], v[38:39], v[130:131] op_sel_hi:[1,0]
	s_nop 0
	v_pk_mul_f32 v[122:123], v[116:117], v[162:163] op_sel_hi:[1,0]
	v_pk_mul_f32 v[116:117], v[114:115], v[162:163] op_sel_hi:[1,0]
	v_cvt_pk_bf16_f32 v114, v118, v119
	v_cvt_pk_bf16_f32 v115, v120, v121
	v_pk_mul_f32 v[120:121], v[52:53], v[154:155] op_sel_hi:[1,0]
	v_cvt_pk_bf16_f32 v116, v116, v117
	v_cvt_pk_bf16_f32 v117, v122, v123
	global_store_dwordx4 v[126:127], v[114:117], off offset:256 sc1
	v_pk_mul_f32 v[122:123], v[50:51], v[154:155] op_sel_hi:[1,0]
	s_nop 0
	v_lshlrev_b64 v[114:115], 11, v[172:173]
	v_lshl_add_u64 v[118:119], v[132:133], 0, v[114:115]
	v_pk_mul_f32 v[114:115], v[54:55], v[154:155] op_sel_hi:[1,0]
	v_pk_mul_f32 v[116:117], v[56:57], v[154:155] op_sel_hi:[1,0]
	v_cvt_pk_bf16_f32 v114, v114, v115
	s_nop 0
	v_cvt_pk_bf16_f32 v115, v116, v117
	v_cvt_pk_bf16_f32 v116, v122, v123
	v_cvt_pk_bf16_f32 v117, v120, v121
	global_store_dwordx4 v[118:119], v[114:117], off sc1
	s_nop 1
	v_pk_mul_f32 v[114:115], v[108:109], v[154:155] op_sel_hi:[1,0]
	v_pk_mul_f32 v[108:109], v[106:107], v[154:155] op_sel_hi:[1,0]
	v_cvt_pk_bf16_f32 v106, v110, v111
	v_cvt_pk_bf16_f32 v107, v112, v113
	v_pk_mul_f32 v[112:113], v[44:45], v[156:157] op_sel_hi:[1,0]
	v_cvt_pk_bf16_f32 v108, v108, v109
	v_cvt_pk_bf16_f32 v109, v114, v115
	global_store_dwordx4 v[118:119], v[106:109], off offset:256 sc1
	v_pk_mul_f32 v[114:115], v[42:43], v[156:157] op_sel_hi:[1,0]
	s_nop 0
	v_lshlrev_b64 v[106:107], 11, v[170:171]
	v_lshl_add_u64 v[110:111], v[132:133], 0, v[106:107]
	v_pk_mul_f32 v[106:107], v[46:47], v[156:157] op_sel_hi:[1,0]
	v_pk_mul_f32 v[108:109], v[48:49], v[156:157] op_sel_hi:[1,0]
	v_cvt_pk_bf16_f32 v106, v106, v107
	s_nop 0
	v_cvt_pk_bf16_f32 v107, v108, v109
	v_cvt_pk_bf16_f32 v108, v114, v115
	v_cvt_pk_bf16_f32 v109, v112, v113
	global_store_dwordx4 v[110:111], v[106:109], off sc1
	s_nop 1
	v_pk_mul_f32 v[106:107], v[100:101], v[156:157] op_sel_hi:[1,0]
	v_pk_mul_f32 v[100:101], v[98:99], v[156:157] op_sel_hi:[1,0]
; __device__ __forceinline__ unsigned cvt_pk_bf16(float lo, float hi) { unsigned r; asm volatile("v_cvt_pk_bf16_f32 %0, %1, %2" : "=v"(r) : "v"(lo), "v"(hi)); return r; }
;     __device__ __forceinline__ void operator()(const f32x4 (&acc)[2][2][4][2], const Unit& u, int wr, int wc, int fr, int fq) const {
;     ...
; #pragma unroll
;         for (int ai = 0; ai < 2; ++ai)
; #pragma unroll
;             for (int m = 0; m < 4; ++m) { const int row = row0 + ai * HALF + m * 16; const float rs = rsv[ai][m]; bf16_t* rowp = base + (size_t)row * ldc + col0;
; #pragma unroll
;                 for (int bj = 0; bj < 2; ++bj) { const f32x4 v0 = acc[ai][bj][m][0] * rs, v1 = acc[ai][bj][m][1] * rs;
;                     u32x4 w; w.x = cvt_pk_bf16(v0[0], v0[1]); w.y = cvt_pk_bf16(v0[2], v0[3]); w.z = cvt_pk_bf16(v1[0], v1[1]); w.w = cvt_pk_bf16(v1[2], v1[3]);
;                     *(u32x4*)(rowp + bj * HALF) = w; } asm volatile("" ::: "memory"); }
	v_cvt_pk_bf16_f32 v98, v102, v103
	v_cvt_pk_bf16_f32 v99, v104, v105
	v_pk_mul_f32 v[104:105], v[28:29], v[152:153] op_sel_hi:[1,0]
	v_cvt_pk_bf16_f32 v100, v100, v101
	v_cvt_pk_bf16_f32 v101, v106, v107
	global_store_dwordx4 v[110:111], v[98:101], off offset:256 sc1
	v_pk_mul_f32 v[106:107], v[26:27], v[152:153] op_sel_hi:[1,0]
	s_nop 0
	v_lshlrev_b64 v[98:99], 11, v[168:169]
	v_lshl_add_u64 v[102:103], v[132:133], 0, v[98:99]
	v_pk_mul_f32 v[98:99], v[30:31], v[152:153] op_sel_hi:[1,0]
	v_pk_mul_f32 v[100:101], v[32:33], v[152:153] op_sel_hi:[1,0]
	v_cvt_pk_bf16_f32 v98, v98, v99
	s_nop 0
	v_cvt_pk_bf16_f32 v99, v100, v101
	v_cvt_pk_bf16_f32 v100, v106, v107
	v_cvt_pk_bf16_f32 v101, v104, v105
	global_store_dwordx4 v[102:103], v[98:101], off sc1
	s_nop 1
	v_pk_mul_f32 v[98:99], v[92:93], v[152:153] op_sel_hi:[1,0]
	v_pk_mul_f32 v[92:93], v[90:91], v[152:153] op_sel_hi:[1,0]
	v_cvt_pk_bf16_f32 v90, v94, v95
	v_cvt_pk_bf16_f32 v91, v96, v97
	v_pk_mul_f32 v[96:97], v[20:21], v[150:151] op_sel_hi:[1,0]
	v_cvt_pk_bf16_f32 v92, v92, v93
	v_cvt_pk_bf16_f32 v93, v98, v99
	global_store_dwordx4 v[102:103], v[90:93], off offset:256 sc1
	v_pk_mul_f32 v[98:99], v[18:19], v[150:151] op_sel_hi:[1,0]
	s_nop 0
	v_lshlrev_b64 v[90:91], 11, v[166:167]
	v_lshl_add_u64 v[94:95], v[132:133], 0, v[90:91]
	v_pk_mul_f32 v[90:91], v[22:23], v[150:151] op_sel_hi:[1,0]
	v_pk_mul_f32 v[92:93], v[24:25], v[150:151] op_sel_hi:[1,0]
	v_cvt_pk_bf16_f32 v90, v90, v91
	s_nop 0
	v_cvt_pk_bf16_f32 v91, v92, v93
	v_cvt_pk_bf16_f32 v92, v98, v99
	v_cvt_pk_bf16_f32 v93, v96, v97
	global_store_dwordx4 v[94:95], v[90:93], off sc1
	s_nop 1
	v_pk_mul_f32 v[90:91], v[84:85], v[150:151] op_sel_hi:[1,0]
	v_pk_mul_f32 v[84:85], v[82:83], v[150:151] op_sel_hi:[1,0]
	v_cvt_pk_bf16_f32 v82, v86, v87
	v_cvt_pk_bf16_f32 v83, v88, v89
	v_pk_mul_f32 v[88:89], v[12:13], v[148:149] op_sel_hi:[1,0]
	v_cvt_pk_bf16_f32 v84, v84, v85
	v_cvt_pk_bf16_f32 v85, v90, v91
	global_store_dwordx4 v[94:95], v[82:85], off offset:256 sc1
	v_pk_mul_f32 v[90:91], v[10:11], v[148:149] op_sel_hi:[1,0]
	s_nop 0
	v_lshlrev_b64 v[82:83], 11, v[164:165]
	v_lshl_add_u64 v[86:87], v[132:133], 0, v[82:83]
	v_pk_mul_f32 v[82:83], v[14:15], v[148:149] op_sel_hi:[1,0]
	v_pk_mul_f32 v[84:85], v[16:17], v[148:149] op_sel_hi:[1,0]
	v_cvt_pk_bf16_f32 v82, v82, v83
	s_nop 0
	v_cvt_pk_bf16_f32 v83, v84, v85
	v_cvt_pk_bf16_f32 v84, v90, v91
	v_cvt_pk_bf16_f32 v85, v88, v89
	global_store_dwordx4 v[86:87], v[82:85], off sc1
	s_nop 1
	v_pk_mul_f32 v[82:83], v[76:77], v[148:149] op_sel_hi:[1,0]
	v_pk_mul_f32 v[76:77], v[74:75], v[148:149] op_sel_hi:[1,0]
	v_cvt_pk_bf16_f32 v74, v78, v79
	v_cvt_pk_bf16_f32 v75, v80, v81
	v_pk_mul_f32 v[80:81], v[4:5], v[130:131] op_sel_hi:[1,0]
	v_cvt_pk_bf16_f32 v76, v76, v77
	v_cvt_pk_bf16_f32 v77, v82, v83
	global_store_dwordx4 v[86:87], v[74:77], off offset:256 sc1
	v_pk_mul_f32 v[82:83], v[2:3], v[130:131] op_sel_hi:[1,0]
	s_nop 0
	v_lshlrev_b64 v[74:75], 11, v[158:159]
	v_lshl_add_u64 v[78:79], v[132:133], 0, v[74:75]
	v_pk_mul_f32 v[74:75], v[6:7], v[130:131] op_sel_hi:[1,0]
	v_pk_mul_f32 v[76:77], v[8:9], v[130:131] op_sel_hi:[1,0]
	v_cvt_pk_bf16_f32 v74, v74, v75
	s_nop 0
	v_cvt_pk_bf16_f32 v75, v76, v77
	v_cvt_pk_bf16_f32 v76, v82, v83
	v_cvt_pk_bf16_f32 v77, v80, v81
	global_store_dwordx4 v[78:79], v[74:77], off sc1
	s_nop 1
	v_pk_mul_f32 v[74:75], v[36:37], v[130:131] op_sel_hi:[1,0]
	v_pk_mul_f32 v[36:37], v[34:35], v[130:131] op_sel_hi:[1,0]
	v_cvt_pk_bf16_f32 v34, v38, v39
	v_cvt_pk_bf16_f32 v35, v40, v41
	s_nop 0
	v_cvt_pk_bf16_f32 v36, v36, v37
	v_cvt_pk_bf16_f32 v37, v74, v75
	global_store_dwordx4 v[78:79], v[34:37], off offset:256 sc1
	s_cbranch_execz .LBB0_192

; __device__ __forceinline__ unsigned cvt_pk_bf16(float lo, float hi) { unsigned r; asm volatile("v_cvt_pk_bf16_f32 %0, %1, %2" : "=v"(r) : "v"(lo), "v"(hi)); return r; }
;     __device__ __forceinline__ void operator()(const f32x4 (&acc)[2][2][4][2], const Unit& u, int wr, int wc, int fr, int fq) const {
;     ...
;             for (int m = 0; m < 4; ++m) { const int row = row0 + ai * HALF + m * 16; const size_t off = (size_t)row * 1024 + col0; float s = 0.f;
; #pragma unroll
;                 for (int bj = 0; bj < 2; ++bj) { f32x4 b0, b1;
;                     if (base32) { b0 = *(const f32x4*)(base32 + off + bj * HALF); b1 = *(const f32x4*)(base32 + off + bj * HALF + 4); }
;                     else { const u32x4 hv = hv4[m][bj];
;                         b0 = (f32x4){__builtin_bit_cast(float, hv.x << 16), __builtin_bit_cast(float, hv.x & 0xffff0000u), __builtin_bit_cast(float, hv.y << 16), __builtin_bit_cast(float, hv.y & 0xffff0000u)};
;                         b1 = (f32x4){__builtin_bit_cast(float, hv.z << 16), __builtin_bit_cast(float, hv.z & 0xffff0000u), __builtin_bit_cast(float, hv.w << 16), __builtin_bit_cast(float, hv.w & 0xffff0000u)}; }
;                     const f32x4 o0 = b0 + acc[ai][bj][m][0], o1 = b1 + acc[ai][bj][m][1];
;                     s += ((o0[0] * o0[0] + o0[1] * o0[1]) + (o0[2] * o0[2] + o0[3] * o0[3])) + ((o1[0] * o1[0] + o1[1] * o1[1]) + (o1[2] * o1[2] + o1[3] * o1[3]));
;                     u32x4 w; w.x = cvt_pk_bf16(o0[0], o0[1]); w.y = cvt_pk_bf16(o0[2], o0[3]); w.z = cvt_pk_bf16(o1[0], o1[1]); w.w = cvt_pk_bf16(o1[2], o1[3]); *(u32x4*)(hb + off + bj * HALF) = w; }
.LBB0_644:
	s_waitcnt vmcnt(0)
	v_pk_add_f32 v[196:197], v[160:161], v[164:165]
	v_pk_add_f32 v[200:201], v[158:159], v[162:163]
	v_pk_add_f32 v[164:165], v[156:157], v[168:169]
	v_pk_add_f32 v[166:167], v[154:155], v[166:167]
	v_lshl_add_u64 v[162:163], v[198:199], 1, s[14:15]
	s_and_b64 vcc, exec, s[10:11]
	v_cvt_pk_bf16_f32 v154, v200, v201
	v_cvt_pk_bf16_f32 v155, v196, v197
	v_cvt_pk_bf16_f32 v156, v166, v167
	v_cvt_pk_bf16_f32 v157, v164, v165
	global_store_dwordx4 v[162:163], v[154:157], off sc1
	s_cbranch_vccnz .LBB0_714
	global_load_dwordx4 v[158:161], v[194:195], off offset:528
	global_load_dwordx4 v[154:157], v[194:195], off offset:512
	s_cbranch_execnz .LBB0_647

; __device__ __forceinline__ unsigned cvt_pk_bf16(float lo, float hi) { unsigned r; asm volatile("v_cvt_pk_bf16_f32 %0, %1, %2" : "=v"(r) : "v"(lo), "v"(hi)); return r; }
;     __device__ __forceinline__ void operator()(const f32x4 (&acc)[2][2][4][2], const Unit& u, int wr, int wc, int fr, int fq) const {
;     ...
;             for (int m = 0; m < 4; ++m) { const int row = row0 + ai * HALF + m * 16; const size_t off = (size_t)row * 1024 + col0; float s = 0.f;
; #pragma unroll
;                 for (int bj = 0; bj < 2; ++bj) { f32x4 b0, b1;
;                     if (base32) { b0 = *(const f32x4*)(base32 + off + bj * HALF); b1 = *(const f32x4*)(base32 + off + bj * HALF + 4); }
;                     else { const u32x4 hv = hv4[m][bj];
;                         b0 = (f32x4){__builtin_bit_cast(float, hv.x << 16), __builtin_bit_cast(float, hv.x & 0xffff0000u), __builtin_bit_cast(float, hv.y << 16), __builtin_bit_cast(float, hv.y & 0xffff0000u)};
;                         b1 = (f32x4){__builtin_bit_cast(float, hv.z << 16), __builtin_bit_cast(float, hv.z & 0xffff0000u), __builtin_bit_cast(float, hv.w << 16), __builtin_bit_cast(float, hv.w & 0xffff0000u)}; }
;                     const f32x4 o0 = b0 + acc[ai][bj][m][0], o1 = b1 + acc[ai][bj][m][1];
;                     s += ((o0[0] * o0[0] + o0[1] * o0[1]) + (o0[2] * o0[2] + o0[3] * o0[3])) + ((o1[0] * o1[0] + o1[1] * o1[1]) + (o1[2] * o1[2] + o1[3] * o1[3]));
;                     u32x4 w; w.x = cvt_pk_bf16(o0[0], o0[1]); w.y = cvt_pk_bf16(o0[2], o0[3]); w.z = cvt_pk_bf16(o1[0], o1[1]); w.w = cvt_pk_bf16(o1[2], o1[3]); *(u32x4*)(hb + off + bj * HALF) = w; }
;                 s += __shfl_xor(s, 16); s += __shfl_xor(s, 32);
;                 if (fq == 0) P[(wr * 64 + ai * HALF + m * 16 + fr) * 4 + wc] = s;
;                 asm volatile("" ::: "memory"); }
.LBB0_647:
	s_waitcnt vmcnt(0)
	v_pk_add_f32 v[152:153], v[152:153], v[156:157]
	v_pk_add_f32 v[150:151], v[150:151], v[154:155]
	v_pk_add_f32 v[156:157], v[146:147], v[158:159]
	v_mul_f32_e32 v146, v151, v151
	v_mul_f32_e32 v147, v153, v153
	v_pk_add_f32 v[154:155], v[148:149], v[160:161]
	v_fmac_f32_e32 v146, v150, v150
	v_fmac_f32_e32 v147, v152, v152
	v_add_f32_e32 v146, v146, v147
	v_mul_f32_e32 v147, v157, v157
	v_mul_f32_e32 v148, v155, v155
	v_fmac_f32_e32 v147, v156, v156
	v_fmac_f32_e32 v148, v154, v154
	v_mul_f32_e32 v168, v201, v201
	v_mul_f32_e32 v169, v197, v197
	v_mul_f32_e32 v167, v167, v167
	v_mul_f32_e32 v165, v165, v165
	v_add_f32_e32 v147, v147, v148
	v_and_b32_e32 v148, 64, v225
	v_fmac_f32_e32 v168, v200, v200
	v_fmac_f32_e32 v169, v196, v196
	v_fmac_f32_e32 v167, v166, v166
	v_fmac_f32_e32 v165, v164, v164
	v_add_f32_e32 v146, v147, v146
	v_xor_b32_e32 v147, 16, v225
	v_add_u32_e32 v158, 64, v148
	v_add_f32_e32 v168, v168, v169
	v_add_f32_e32 v164, v167, v165
	v_cmp_lt_i32_e32 vcc, v147, v158
	v_add_f32_e32 v164, v164, v168
	v_add_f32_e32 v146, v164, v146
	v_cndmask_b32_e32 v147, v225, v147, vcc
	v_lshlrev_b32_e32 v164, 2, v147
	ds_bpermute_b32 v147, v164, v146
	v_cmp_eq_u32_e64 s[12:13], 0, v206
	v_cvt_pk_bf16_f32 v148, v150, v151
	v_cvt_pk_bf16_f32 v149, v152, v153
	v_cvt_pk_bf16_f32 v150, v156, v157
	s_waitcnt lgkmcnt(0)
	v_add_f32_e32 v146, v146, v147
	v_xor_b32_e32 v147, 32, v225
	v_cmp_lt_i32_e32 vcc, v147, v158
	v_cvt_pk_bf16_f32 v151, v154, v155
	global_store_dwordx4 v[162:163], v[148:151], off offset:256 sc1
	v_lshl_add_u32 v162, v207, 4, s53
	v_cndmask_b32_e32 v147, v225, v147, vcc
	v_lshlrev_b32_e32 v165, 2, v147
	ds_bpermute_b32 v147, v165, v146
	s_and_saveexec_b64 s[36:37], s[12:13]
	s_cbranch_execz .LBB0_649
	s_waitcnt lgkmcnt(0)
	v_add_f32_e32 v146, v146, v147
	ds_write_b32 v162, v146

; __device__ __forceinline__ unsigned cvt_pk_bf16(float lo, float hi) { unsigned r; asm volatile("v_cvt_pk_bf16_f32 %0, %1, %2" : "=v"(r) : "v"(lo), "v"(hi)); return r; }
;     __device__ __forceinline__ void operator()(const f32x4 (&acc)[2][2][4][2], const Unit& u, int wr, int wc, int fr, int fq) const {
;     ...
;             for (int m = 0; m < 4; ++m) { const int row = row0 + ai * HALF + m * 16; const size_t off = (size_t)row * 1024 + col0; float s = 0.f;
; #pragma unroll
;                 for (int bj = 0; bj < 2; ++bj) { f32x4 b0, b1;
;                     if (base32) { b0 = *(const f32x4*)(base32 + off + bj * HALF); b1 = *(const f32x4*)(base32 + off + bj * HALF + 4); }
;                     else { const u32x4 hv = hv4[m][bj];
;                         b0 = (f32x4){__builtin_bit_cast(float, hv.x << 16), __builtin_bit_cast(float, hv.x & 0xffff0000u), __builtin_bit_cast(float, hv.y << 16), __builtin_bit_cast(float, hv.y & 0xffff0000u)};
;                         b1 = (f32x4){__builtin_bit_cast(float, hv.z << 16), __builtin_bit_cast(float, hv.z & 0xffff0000u), __builtin_bit_cast(float, hv.w << 16), __builtin_bit_cast(float, hv.w & 0xffff0000u)}; }
;                     const f32x4 o0 = b0 + acc[ai][bj][m][0], o1 = b1 + acc[ai][bj][m][1];
;                     s += ((o0[0] * o0[0] + o0[1] * o0[1]) + (o0[2] * o0[2] + o0[3] * o0[3])) + ((o1[0] * o1[0] + o1[1] * o1[1]) + (o1[2] * o1[2] + o1[3] * o1[3]));
;                     u32x4 w; w.x = cvt_pk_bf16(o0[0], o0[1]); w.y = cvt_pk_bf16(o0[2], o0[3]); w.z = cvt_pk_bf16(o1[0], o1[1]); w.w = cvt_pk_bf16(o1[2], o1[3]); *(u32x4*)(hb + off + bj * HALF) = w; }
.LBB0_652:
	s_waitcnt vmcnt(0)
	v_pk_add_f32 v[156:157], v[144:145], v[148:149]
	v_pk_add_f32 v[160:161], v[142:143], v[146:147]
	v_pk_add_f32 v[148:149], v[140:141], v[152:153]
	v_pk_add_f32 v[150:151], v[138:139], v[150:151]
	v_lshl_add_u64 v[146:147], v[158:159], 1, s[14:15]
	s_and_b64 vcc, exec, s[10:11]
	v_cvt_pk_bf16_f32 v138, v160, v161
	v_cvt_pk_bf16_f32 v139, v156, v157
	v_cvt_pk_bf16_f32 v140, v150, v151
	v_cvt_pk_bf16_f32 v141, v148, v149
	global_store_dwordx4 v[146:147], v[138:141], off sc1
	s_cbranch_vccnz .LBB0_716
	global_load_dwordx4 v[142:145], v[154:155], off offset:528
	global_load_dwordx4 v[138:141], v[154:155], off offset:512
	s_cbranch_execnz .LBB0_655

; __device__ __forceinline__ unsigned cvt_pk_bf16(float lo, float hi) { unsigned r; asm volatile("v_cvt_pk_bf16_f32 %0, %1, %2" : "=v"(r) : "v"(lo), "v"(hi)); return r; }
;     __device__ __forceinline__ void operator()(const f32x4 (&acc)[2][2][4][2], const Unit& u, int wr, int wc, int fr, int fq) const {
;     ...
;             for (int m = 0; m < 4; ++m) { const int row = row0 + ai * HALF + m * 16; const size_t off = (size_t)row * 1024 + col0; float s = 0.f;
; #pragma unroll
;                 for (int bj = 0; bj < 2; ++bj) { f32x4 b0, b1;
;                     if (base32) { b0 = *(const f32x4*)(base32 + off + bj * HALF); b1 = *(const f32x4*)(base32 + off + bj * HALF + 4); }
;                     else { const u32x4 hv = hv4[m][bj];
;                         b0 = (f32x4){__builtin_bit_cast(float, hv.x << 16), __builtin_bit_cast(float, hv.x & 0xffff0000u), __builtin_bit_cast(float, hv.y << 16), __builtin_bit_cast(float, hv.y & 0xffff0000u)};
;                         b1 = (f32x4){__builtin_bit_cast(float, hv.z << 16), __builtin_bit_cast(float, hv.z & 0xffff0000u), __builtin_bit_cast(float, hv.w << 16), __builtin_bit_cast(float, hv.w & 0xffff0000u)}; }
;                     const f32x4 o0 = b0 + acc[ai][bj][m][0], o1 = b1 + acc[ai][bj][m][1];
;                     s += ((o0[0] * o0[0] + o0[1] * o0[1]) + (o0[2] * o0[2] + o0[3] * o0[3])) + ((o1[0] * o1[0] + o1[1] * o1[1]) + (o1[2] * o1[2] + o1[3] * o1[3]));
;                     u32x4 w; w.x = cvt_pk_bf16(o0[0], o0[1]); w.y = cvt_pk_bf16(o0[2], o0[3]); w.z = cvt_pk_bf16(o1[0], o1[1]); w.w = cvt_pk_bf16(o1[2], o1[3]); *(u32x4*)(hb + off + bj * HALF) = w; }
;                 s += __shfl_xor(s, 16); s += __shfl_xor(s, 32);
;                 if (fq == 0) P[(wr * 64 + ai * HALF + m * 16 + fr) * 4 + wc] = s;
;                 asm volatile("" ::: "memory"); }
.LBB0_655:
	s_waitcnt vmcnt(0)
	v_pk_add_f32 v[128:129], v[128:129], v[140:141]
	v_pk_add_f32 v[126:127], v[126:127], v[138:139]
	v_pk_add_f32 v[140:141], v[122:123], v[142:143]
	v_mul_f32_e32 v122, v127, v127
	v_mul_f32_e32 v123, v129, v129
	v_pk_add_f32 v[138:139], v[124:125], v[144:145]
	v_fmac_f32_e32 v122, v126, v126
	v_fmac_f32_e32 v123, v128, v128
	v_mul_f32_e32 v152, v161, v161
	v_mul_f32_e32 v153, v157, v157
	v_mul_f32_e32 v151, v151, v151
	v_mul_f32_e32 v149, v149, v149
	v_add_f32_e32 v122, v122, v123
	v_mul_f32_e32 v123, v141, v141
	v_mul_f32_e32 v124, v139, v139
	v_fmac_f32_e32 v152, v160, v160
	v_fmac_f32_e32 v153, v156, v156
	v_fmac_f32_e32 v151, v150, v150
	v_fmac_f32_e32 v149, v148, v148
	v_fmac_f32_e32 v123, v140, v140
	v_fmac_f32_e32 v124, v138, v138
	v_add_f32_e32 v152, v152, v153
	v_add_f32_e32 v148, v151, v149
	v_add_f32_e32 v123, v123, v124
	v_add_f32_e32 v148, v148, v152
	v_add_f32_e32 v122, v123, v122
	v_add_f32_e32 v122, v148, v122
	ds_bpermute_b32 v123, v164, v122
	v_cvt_pk_bf16_f32 v124, v126, v127
	v_cvt_pk_bf16_f32 v125, v128, v129
	v_cvt_pk_bf16_f32 v126, v140, v141
	v_cvt_pk_bf16_f32 v127, v138, v139
	s_waitcnt lgkmcnt(0)
	v_add_f32_e32 v122, v122, v123
	ds_bpermute_b32 v123, v165, v122
	global_store_dwordx4 v[146:147], v[124:127], off offset:256 sc1
	s_and_saveexec_b64 s[36:37], s[12:13]
	s_cbranch_execz .LBB0_657
	s_waitcnt lgkmcnt(0)
	v_add_f32_e32 v122, v122, v123
	ds_write_b32 v162, v122 offset:256

; __device__ __forceinline__ unsigned cvt_pk_bf16(float lo, float hi) { unsigned r; asm volatile("v_cvt_pk_bf16_f32 %0, %1, %2" : "=v"(r) : "v"(lo), "v"(hi)); return r; }
;     __device__ __forceinline__ void operator()(const f32x4 (&acc)[2][2][4][2], const Unit& u, int wr, int wc, int fr, int fq) const {
;     ...
;             for (int m = 0; m < 4; ++m) { const int row = row0 + ai * HALF + m * 16; const size_t off = (size_t)row * 1024 + col0; float s = 0.f;
; #pragma unroll
;                 for (int bj = 0; bj < 2; ++bj) { f32x4 b0, b1;
;                     if (base32) { b0 = *(const f32x4*)(base32 + off + bj * HALF); b1 = *(const f32x4*)(base32 + off + bj * HALF + 4); }
;                     else { const u32x4 hv = hv4[m][bj];
;                         b0 = (f32x4){__builtin_bit_cast(float, hv.x << 16), __builtin_bit_cast(float, hv.x & 0xffff0000u), __builtin_bit_cast(float, hv.y << 16), __builtin_bit_cast(float, hv.y & 0xffff0000u)};
;                         b1 = (f32x4){__builtin_bit_cast(float, hv.z << 16), __builtin_bit_cast(float, hv.z & 0xffff0000u), __builtin_bit_cast(float, hv.w << 16), __builtin_bit_cast(float, hv.w & 0xffff0000u)}; }
;                     const f32x4 o0 = b0 + acc[ai][bj][m][0], o1 = b1 + acc[ai][bj][m][1];
;                     s += ((o0[0] * o0[0] + o0[1] * o0[1]) + (o0[2] * o0[2] + o0[3] * o0[3])) + ((o1[0] * o1[0] + o1[1] * o1[1]) + (o1[2] * o1[2] + o1[3] * o1[3]));
;                     u32x4 w; w.x = cvt_pk_bf16(o0[0], o0[1]); w.y = cvt_pk_bf16(o0[2], o0[3]); w.z = cvt_pk_bf16(o1[0], o1[1]); w.w = cvt_pk_bf16(o1[2], o1[3]); *(u32x4*)(hb + off + bj * HALF) = w; }
.LBB0_660:
	s_waitcnt vmcnt(0)
	v_pk_add_f32 v[140:141], v[116:117], v[124:125]
	v_pk_add_f32 v[144:145], v[114:115], v[122:123]
	v_pk_add_f32 v[124:125], v[112:113], v[128:129]
	v_pk_add_f32 v[126:127], v[110:111], v[126:127]
	v_lshl_add_u64 v[122:123], v[142:143], 1, s[14:15]
	s_and_b64 vcc, exec, s[10:11]
	v_cvt_pk_bf16_f32 v110, v144, v145
	v_cvt_pk_bf16_f32 v111, v140, v141
	v_cvt_pk_bf16_f32 v112, v126, v127
	v_cvt_pk_bf16_f32 v113, v124, v125
	global_store_dwordx4 v[122:123], v[110:113], off sc1
	s_cbranch_vccnz .LBB0_718
	global_load_dwordx4 v[114:117], v[138:139], off offset:528
	global_load_dwordx4 v[110:113], v[138:139], off offset:512
	s_cbranch_execnz .LBB0_663

; __device__ __forceinline__ unsigned cvt_pk_bf16(float lo, float hi) { unsigned r; asm volatile("v_cvt_pk_bf16_f32 %0, %1, %2" : "=v"(r) : "v"(lo), "v"(hi)); return r; }
;     __device__ __forceinline__ void operator()(const f32x4 (&acc)[2][2][4][2], const Unit& u, int wr, int wc, int fr, int fq) const {
;     ...
;             for (int m = 0; m < 4; ++m) { const int row = row0 + ai * HALF + m * 16; const size_t off = (size_t)row * 1024 + col0; float s = 0.f;
; #pragma unroll
;                 for (int bj = 0; bj < 2; ++bj) { f32x4 b0, b1;
;                     if (base32) { b0 = *(const f32x4*)(base32 + off + bj * HALF); b1 = *(const f32x4*)(base32 + off + bj * HALF + 4); }
;                     else { const u32x4 hv = hv4[m][bj];
;                         b0 = (f32x4){__builtin_bit_cast(float, hv.x << 16), __builtin_bit_cast(float, hv.x & 0xffff0000u), __builtin_bit_cast(float, hv.y << 16), __builtin_bit_cast(float, hv.y & 0xffff0000u)};
;                         b1 = (f32x4){__builtin_bit_cast(float, hv.z << 16), __builtin_bit_cast(float, hv.z & 0xffff0000u), __builtin_bit_cast(float, hv.w << 16), __builtin_bit_cast(float, hv.w & 0xffff0000u)}; }
;                     const f32x4 o0 = b0 + acc[ai][bj][m][0], o1 = b1 + acc[ai][bj][m][1];
;                     s += ((o0[0] * o0[0] + o0[1] * o0[1]) + (o0[2] * o0[2] + o0[3] * o0[3])) + ((o1[0] * o1[0] + o1[1] * o1[1]) + (o1[2] * o1[2] + o1[3] * o1[3]));
;                     u32x4 w; w.x = cvt_pk_bf16(o0[0], o0[1]); w.y = cvt_pk_bf16(o0[2], o0[3]); w.z = cvt_pk_bf16(o1[0], o1[1]); w.w = cvt_pk_bf16(o1[2], o1[3]); *(u32x4*)(hb + off + bj * HALF) = w; }
;                 s += __shfl_xor(s, 16); s += __shfl_xor(s, 32);
;                 if (fq == 0) P[(wr * 64 + ai * HALF + m * 16 + fr) * 4 + wc] = s;
;                 asm volatile("" ::: "memory"); }
.LBB0_663:
	s_waitcnt vmcnt(0)
	v_pk_add_f32 v[104:105], v[104:105], v[112:113]
	v_pk_add_f32 v[102:103], v[102:103], v[110:111]
	v_pk_add_f32 v[112:113], v[98:99], v[114:115]
	v_mul_f32_e32 v98, v103, v103
	v_mul_f32_e32 v99, v105, v105
	v_pk_add_f32 v[110:111], v[100:101], v[116:117]
	v_fmac_f32_e32 v98, v102, v102
	v_fmac_f32_e32 v99, v104, v104
	v_mul_f32_e32 v128, v145, v145
	v_mul_f32_e32 v129, v141, v141
	v_mul_f32_e32 v127, v127, v127
	v_mul_f32_e32 v125, v125, v125
	v_add_f32_e32 v98, v98, v99
	v_mul_f32_e32 v99, v113, v113
	v_mul_f32_e32 v100, v111, v111
	v_fmac_f32_e32 v128, v144, v144
	v_fmac_f32_e32 v129, v140, v140
	v_fmac_f32_e32 v127, v126, v126
	v_fmac_f32_e32 v125, v124, v124
	v_fmac_f32_e32 v99, v112, v112
	v_fmac_f32_e32 v100, v110, v110
	v_add_f32_e32 v128, v128, v129
	v_add_f32_e32 v124, v127, v125
	v_add_f32_e32 v99, v99, v100
	v_add_f32_e32 v124, v124, v128
	v_add_f32_e32 v98, v99, v98
	v_add_f32_e32 v98, v124, v98
	ds_bpermute_b32 v99, v164, v98
	v_cvt_pk_bf16_f32 v100, v102, v103
	v_cvt_pk_bf16_f32 v101, v104, v105
	v_cvt_pk_bf16_f32 v102, v112, v113
	v_cvt_pk_bf16_f32 v103, v110, v111
	s_waitcnt lgkmcnt(0)
	v_add_f32_e32 v98, v98, v99
	ds_bpermute_b32 v99, v165, v98
	global_store_dwordx4 v[122:123], v[100:103], off offset:256 sc1
	s_and_saveexec_b64 s[36:37], s[12:13]
	s_cbranch_execz .LBB0_665
	s_waitcnt lgkmcnt(0)
	v_add_f32_e32 v98, v98, v99
	ds_write_b32 v162, v98 offset:512

; __device__ __forceinline__ unsigned cvt_pk_bf16(float lo, float hi) { unsigned r; asm volatile("v_cvt_pk_bf16_f32 %0, %1, %2" : "=v"(r) : "v"(lo), "v"(hi)); return r; }
;     __device__ __forceinline__ void operator()(const f32x4 (&acc)[2][2][4][2], const Unit& u, int wr, int wc, int fr, int fq) const {
;     ...
;             for (int m = 0; m < 4; ++m) { const int row = row0 + ai * HALF + m * 16; const size_t off = (size_t)row * 1024 + col0; float s = 0.f;
; #pragma unroll
;                 for (int bj = 0; bj < 2; ++bj) { f32x4 b0, b1;
;                     if (base32) { b0 = *(const f32x4*)(base32 + off + bj * HALF); b1 = *(const f32x4*)(base32 + off + bj * HALF + 4); }
;                     else { const u32x4 hv = hv4[m][bj];
;                         b0 = (f32x4){__builtin_bit_cast(float, hv.x << 16), __builtin_bit_cast(float, hv.x & 0xffff0000u), __builtin_bit_cast(float, hv.y << 16), __builtin_bit_cast(float, hv.y & 0xffff0000u)};
;                         b1 = (f32x4){__builtin_bit_cast(float, hv.z << 16), __builtin_bit_cast(float, hv.z & 0xffff0000u), __builtin_bit_cast(float, hv.w << 16), __builtin_bit_cast(float, hv.w & 0xffff0000u)}; }
;                     const f32x4 o0 = b0 + acc[ai][bj][m][0], o1 = b1 + acc[ai][bj][m][1];
;                     s += ((o0[0] * o0[0] + o0[1] * o0[1]) + (o0[2] * o0[2] + o0[3] * o0[3])) + ((o1[0] * o1[0] + o1[1] * o1[1]) + (o1[2] * o1[2] + o1[3] * o1[3]));
;                     u32x4 w; w.x = cvt_pk_bf16(o0[0], o0[1]); w.y = cvt_pk_bf16(o0[2], o0[3]); w.z = cvt_pk_bf16(o1[0], o1[1]); w.w = cvt_pk_bf16(o1[2], o1[3]); *(u32x4*)(hb + off + bj * HALF) = w; }
.LBB0_668:
	s_waitcnt vmcnt(0)
	v_pk_add_f32 v[112:113], v[92:93], v[100:101]
	v_pk_add_f32 v[116:117], v[90:91], v[98:99]
	v_pk_add_f32 v[100:101], v[88:89], v[104:105]
	v_pk_add_f32 v[102:103], v[86:87], v[102:103]
	v_lshl_add_u64 v[98:99], v[114:115], 1, s[14:15]
	s_and_b64 vcc, exec, s[10:11]
	v_cvt_pk_bf16_f32 v86, v116, v117
	v_cvt_pk_bf16_f32 v87, v112, v113
	v_cvt_pk_bf16_f32 v88, v102, v103
	v_cvt_pk_bf16_f32 v89, v100, v101
	global_store_dwordx4 v[98:99], v[86:89], off sc1
	s_cbranch_vccnz .LBB0_720
	global_load_dwordx4 v[90:93], v[110:111], off offset:528
	global_load_dwordx4 v[86:89], v[110:111], off offset:512
	s_cbranch_execnz .LBB0_671

; __device__ __forceinline__ unsigned cvt_pk_bf16(float lo, float hi) { unsigned r; asm volatile("v_cvt_pk_bf16_f32 %0, %1, %2" : "=v"(r) : "v"(lo), "v"(hi)); return r; }
;     __device__ __forceinline__ void operator()(const f32x4 (&acc)[2][2][4][2], const Unit& u, int wr, int wc, int fr, int fq) const {
;     ...
;             for (int m = 0; m < 4; ++m) { const int row = row0 + ai * HALF + m * 16; const size_t off = (size_t)row * 1024 + col0; float s = 0.f;
; #pragma unroll
;                 for (int bj = 0; bj < 2; ++bj) { f32x4 b0, b1;
;                     if (base32) { b0 = *(const f32x4*)(base32 + off + bj * HALF); b1 = *(const f32x4*)(base32 + off + bj * HALF + 4); }
;                     else { const u32x4 hv = hv4[m][bj];
;                         b0 = (f32x4){__builtin_bit_cast(float, hv.x << 16), __builtin_bit_cast(float, hv.x & 0xffff0000u), __builtin_bit_cast(float, hv.y << 16), __builtin_bit_cast(float, hv.y & 0xffff0000u)};
;                         b1 = (f32x4){__builtin_bit_cast(float, hv.z << 16), __builtin_bit_cast(float, hv.z & 0xffff0000u), __builtin_bit_cast(float, hv.w << 16), __builtin_bit_cast(float, hv.w & 0xffff0000u)}; }
;                     const f32x4 o0 = b0 + acc[ai][bj][m][0], o1 = b1 + acc[ai][bj][m][1];
;                     s += ((o0[0] * o0[0] + o0[1] * o0[1]) + (o0[2] * o0[2] + o0[3] * o0[3])) + ((o1[0] * o1[0] + o1[1] * o1[1]) + (o1[2] * o1[2] + o1[3] * o1[3]));
;                     u32x4 w; w.x = cvt_pk_bf16(o0[0], o0[1]); w.y = cvt_pk_bf16(o0[2], o0[3]); w.z = cvt_pk_bf16(o1[0], o1[1]); w.w = cvt_pk_bf16(o1[2], o1[3]); *(u32x4*)(hb + off + bj * HALF) = w; }
;                 s += __shfl_xor(s, 16); s += __shfl_xor(s, 32);
;                 if (fq == 0) P[(wr * 64 + ai * HALF + m * 16 + fr) * 4 + wc] = s;
;                 asm volatile("" ::: "memory"); }
.LBB0_671:
	s_waitcnt vmcnt(0)
	v_pk_add_f32 v[80:81], v[80:81], v[88:89]
	v_pk_add_f32 v[78:79], v[78:79], v[86:87]
	v_pk_add_f32 v[88:89], v[74:75], v[90:91]
	v_mul_f32_e32 v74, v79, v79
	v_mul_f32_e32 v75, v81, v81
	v_pk_add_f32 v[86:87], v[76:77], v[92:93]
	v_fmac_f32_e32 v74, v78, v78
	v_fmac_f32_e32 v75, v80, v80
	v_mul_f32_e32 v104, v117, v117
	v_mul_f32_e32 v105, v113, v113
	v_mul_f32_e32 v103, v103, v103
	v_mul_f32_e32 v101, v101, v101
	v_add_f32_e32 v74, v74, v75
	v_mul_f32_e32 v75, v89, v89
	v_mul_f32_e32 v76, v87, v87
	v_fmac_f32_e32 v104, v116, v116
	v_fmac_f32_e32 v105, v112, v112
	v_fmac_f32_e32 v103, v102, v102
	v_fmac_f32_e32 v101, v100, v100
	v_fmac_f32_e32 v75, v88, v88
	v_fmac_f32_e32 v76, v86, v86
	v_add_f32_e32 v104, v104, v105
	v_add_f32_e32 v100, v103, v101
	v_add_f32_e32 v75, v75, v76
	v_add_f32_e32 v100, v100, v104
	v_add_f32_e32 v74, v75, v74
	v_add_f32_e32 v74, v100, v74
	ds_bpermute_b32 v75, v164, v74
	v_cvt_pk_bf16_f32 v76, v78, v79
	v_cvt_pk_bf16_f32 v77, v80, v81
	v_cvt_pk_bf16_f32 v78, v88, v89
	v_cvt_pk_bf16_f32 v79, v86, v87
	s_waitcnt lgkmcnt(0)
	v_add_f32_e32 v74, v74, v75
	ds_bpermute_b32 v75, v165, v74
	global_store_dwordx4 v[98:99], v[76:79], off offset:256 sc1
	s_and_saveexec_b64 s[36:37], s[12:13]
	s_cbranch_execz .LBB0_673
	s_waitcnt lgkmcnt(0)
	v_add_f32_e32 v74, v74, v75
	ds_write_b32 v162, v74 offset:768

; __device__ __forceinline__ unsigned cvt_pk_bf16(float lo, float hi) { unsigned r; asm volatile("v_cvt_pk_bf16_f32 %0, %1, %2" : "=v"(r) : "v"(lo), "v"(hi)); return r; }
;     __device__ __forceinline__ void operator()(const f32x4 (&acc)[2][2][4][2], const Unit& u, int wr, int wc, int fr, int fq) const {
;     ...
;             for (int m = 0; m < 4; ++m) { const int row = row0 + ai * HALF + m * 16; const size_t off = (size_t)row * 1024 + col0; float s = 0.f;
; #pragma unroll
;                 for (int bj = 0; bj < 2; ++bj) { f32x4 b0, b1;
;                     if (base32) { b0 = *(const f32x4*)(base32 + off + bj * HALF); b1 = *(const f32x4*)(base32 + off + bj * HALF + 4); }
;                     else { const u32x4 hv = hv4[m][bj];
;                         b0 = (f32x4){__builtin_bit_cast(float, hv.x << 16), __builtin_bit_cast(float, hv.x & 0xffff0000u), __builtin_bit_cast(float, hv.y << 16), __builtin_bit_cast(float, hv.y & 0xffff0000u)};
;                         b1 = (f32x4){__builtin_bit_cast(float, hv.z << 16), __builtin_bit_cast(float, hv.z & 0xffff0000u), __builtin_bit_cast(float, hv.w << 16), __builtin_bit_cast(float, hv.w & 0xffff0000u)}; }
;                     const f32x4 o0 = b0 + acc[ai][bj][m][0], o1 = b1 + acc[ai][bj][m][1];
;                     s += ((o0[0] * o0[0] + o0[1] * o0[1]) + (o0[2] * o0[2] + o0[3] * o0[3])) + ((o1[0] * o1[0] + o1[1] * o1[1]) + (o1[2] * o1[2] + o1[3] * o1[3]));
;                     u32x4 w; w.x = cvt_pk_bf16(o0[0], o0[1]); w.y = cvt_pk_bf16(o0[2], o0[3]); w.z = cvt_pk_bf16(o1[0], o1[1]); w.w = cvt_pk_bf16(o1[2], o1[3]); *(u32x4*)(hb + off + bj * HALF) = w; }
.LBB0_679:
	s_waitcnt vmcnt(0)
	v_pk_add_f32 v[88:89], v[64:65], v[76:77]
	v_pk_add_f32 v[92:93], v[62:63], v[74:75]
	v_pk_add_f32 v[76:77], v[60:61], v[80:81]
	v_pk_add_f32 v[78:79], v[58:59], v[78:79]
	v_lshl_add_u64 v[74:75], v[90:91], 1, s[14:15]
	s_and_b64 vcc, exec, s[10:11]
	v_cvt_pk_bf16_f32 v58, v92, v93
	v_cvt_pk_bf16_f32 v59, v88, v89
	v_cvt_pk_bf16_f32 v60, v78, v79
	v_cvt_pk_bf16_f32 v61, v76, v77
	global_store_dwordx4 v[74:75], v[58:61], off sc1
	s_cbranch_vccnz .LBB0_723
	global_load_dwordx4 v[62:65], v[86:87], off offset:528
	global_load_dwordx4 v[58:61], v[86:87], off offset:512
	s_cbranch_execnz .LBB0_682

; __device__ __forceinline__ unsigned cvt_pk_bf16(float lo, float hi) { unsigned r; asm volatile("v_cvt_pk_bf16_f32 %0, %1, %2" : "=v"(r) : "v"(lo), "v"(hi)); return r; }
;     __device__ __forceinline__ void operator()(const f32x4 (&acc)[2][2][4][2], const Unit& u, int wr, int wc, int fr, int fq) const {
;     ...
;             for (int m = 0; m < 4; ++m) { const int row = row0 + ai * HALF + m * 16; const size_t off = (size_t)row * 1024 + col0; float s = 0.f;
; #pragma unroll
;                 for (int bj = 0; bj < 2; ++bj) { f32x4 b0, b1;
;                     if (base32) { b0 = *(const f32x4*)(base32 + off + bj * HALF); b1 = *(const f32x4*)(base32 + off + bj * HALF + 4); }
;                     else { const u32x4 hv = hv4[m][bj];
;                         b0 = (f32x4){__builtin_bit_cast(float, hv.x << 16), __builtin_bit_cast(float, hv.x & 0xffff0000u), __builtin_bit_cast(float, hv.y << 16), __builtin_bit_cast(float, hv.y & 0xffff0000u)};
;                         b1 = (f32x4){__builtin_bit_cast(float, hv.z << 16), __builtin_bit_cast(float, hv.z & 0xffff0000u), __builtin_bit_cast(float, hv.w << 16), __builtin_bit_cast(float, hv.w & 0xffff0000u)}; }
;                     const f32x4 o0 = b0 + acc[ai][bj][m][0], o1 = b1 + acc[ai][bj][m][1];
;                     s += ((o0[0] * o0[0] + o0[1] * o0[1]) + (o0[2] * o0[2] + o0[3] * o0[3])) + ((o1[0] * o1[0] + o1[1] * o1[1]) + (o1[2] * o1[2] + o1[3] * o1[3]));
;                     u32x4 w; w.x = cvt_pk_bf16(o0[0], o0[1]); w.y = cvt_pk_bf16(o0[2], o0[3]); w.z = cvt_pk_bf16(o1[0], o1[1]); w.w = cvt_pk_bf16(o1[2], o1[3]); *(u32x4*)(hb + off + bj * HALF) = w; }
;                 s += __shfl_xor(s, 16); s += __shfl_xor(s, 32);
;                 if (fq == 0) P[(wr * 64 + ai * HALF + m * 16 + fr) * 4 + wc] = s;
;                 asm volatile("" ::: "memory"); }
.LBB0_682:
	s_waitcnt vmcnt(0)
	v_pk_add_f32 v[56:57], v[56:57], v[60:61]
	v_pk_add_f32 v[54:55], v[54:55], v[58:59]
	v_pk_add_f32 v[60:61], v[50:51], v[62:63]
	v_mul_f32_e32 v50, v55, v55
	v_mul_f32_e32 v51, v57, v57
	v_pk_add_f32 v[58:59], v[52:53], v[64:65]
	v_fmac_f32_e32 v50, v54, v54
	v_fmac_f32_e32 v51, v56, v56
	v_mul_f32_e32 v80, v93, v93
	v_mul_f32_e32 v81, v89, v89
	v_mul_f32_e32 v79, v79, v79
	v_mul_f32_e32 v77, v77, v77
	v_add_f32_e32 v50, v50, v51
	v_mul_f32_e32 v51, v61, v61
	v_mul_f32_e32 v52, v59, v59
	v_fmac_f32_e32 v80, v92, v92
	v_fmac_f32_e32 v81, v88, v88
	v_fmac_f32_e32 v79, v78, v78
	v_fmac_f32_e32 v77, v76, v76
	v_fmac_f32_e32 v51, v60, v60
	v_fmac_f32_e32 v52, v58, v58
	v_add_f32_e32 v80, v80, v81
	v_add_f32_e32 v76, v79, v77
	v_add_f32_e32 v51, v51, v52
	v_add_f32_e32 v76, v76, v80
	v_add_f32_e32 v50, v51, v50
	v_add_f32_e32 v50, v76, v50
	ds_bpermute_b32 v51, v164, v50
	v_cvt_pk_bf16_f32 v52, v54, v55
	v_cvt_pk_bf16_f32 v53, v56, v57
	v_cvt_pk_bf16_f32 v54, v60, v61
	v_cvt_pk_bf16_f32 v55, v58, v59
	s_waitcnt lgkmcnt(0)
	v_add_f32_e32 v50, v50, v51
	ds_bpermute_b32 v51, v165, v50
	global_store_dwordx4 v[74:75], v[52:55], off offset:256 sc1
	s_and_saveexec_b64 s[36:37], s[12:13]
	s_cbranch_execz .LBB0_684
	s_waitcnt lgkmcnt(0)
	v_add_f32_e32 v50, v50, v51
	ds_write_b32 v162, v50 offset:2048

; __device__ __forceinline__ unsigned cvt_pk_bf16(float lo, float hi) { unsigned r; asm volatile("v_cvt_pk_bf16_f32 %0, %1, %2" : "=v"(r) : "v"(lo), "v"(hi)); return r; }
;     __device__ __forceinline__ void operator()(const f32x4 (&acc)[2][2][4][2], const Unit& u, int wr, int wc, int fr, int fq) const {
;     ...
;             for (int m = 0; m < 4; ++m) { const int row = row0 + ai * HALF + m * 16; const size_t off = (size_t)row * 1024 + col0; float s = 0.f;
; #pragma unroll
;                 for (int bj = 0; bj < 2; ++bj) { f32x4 b0, b1;
;                     if (base32) { b0 = *(const f32x4*)(base32 + off + bj * HALF); b1 = *(const f32x4*)(base32 + off + bj * HALF + 4); }
;                     else { const u32x4 hv = hv4[m][bj];
;                         b0 = (f32x4){__builtin_bit_cast(float, hv.x << 16), __builtin_bit_cast(float, hv.x & 0xffff0000u), __builtin_bit_cast(float, hv.y << 16), __builtin_bit_cast(float, hv.y & 0xffff0000u)};
;                         b1 = (f32x4){__builtin_bit_cast(float, hv.z << 16), __builtin_bit_cast(float, hv.z & 0xffff0000u), __builtin_bit_cast(float, hv.w << 16), __builtin_bit_cast(float, hv.w & 0xffff0000u)}; }
;                     const f32x4 o0 = b0 + acc[ai][bj][m][0], o1 = b1 + acc[ai][bj][m][1];
;                     s += ((o0[0] * o0[0] + o0[1] * o0[1]) + (o0[2] * o0[2] + o0[3] * o0[3])) + ((o1[0] * o1[0] + o1[1] * o1[1]) + (o1[2] * o1[2] + o1[3] * o1[3]));
;                     u32x4 w; w.x = cvt_pk_bf16(o0[0], o0[1]); w.y = cvt_pk_bf16(o0[2], o0[3]); w.z = cvt_pk_bf16(o1[0], o1[1]); w.w = cvt_pk_bf16(o1[2], o1[3]); *(u32x4*)(hb + off + bj * HALF) = w; }
.LBB0_687:
	s_waitcnt vmcnt(0)
	v_pk_add_f32 v[60:61], v[48:49], v[52:53]
	v_pk_add_f32 v[64:65], v[46:47], v[50:51]
	v_pk_add_f32 v[52:53], v[44:45], v[56:57]
	v_pk_add_f32 v[54:55], v[42:43], v[54:55]
	v_lshl_add_u64 v[50:51], v[62:63], 1, s[14:15]
	s_and_b64 vcc, exec, s[10:11]
	v_cvt_pk_bf16_f32 v42, v64, v65
	v_cvt_pk_bf16_f32 v43, v60, v61
	v_cvt_pk_bf16_f32 v44, v54, v55
	v_cvt_pk_bf16_f32 v45, v52, v53
	global_store_dwordx4 v[50:51], v[42:45], off sc1
	s_cbranch_vccnz .LBB0_725
	global_load_dwordx4 v[46:49], v[58:59], off offset:528
	global_load_dwordx4 v[42:45], v[58:59], off offset:512
	s_cbranch_execnz .LBB0_690

; __device__ __forceinline__ unsigned cvt_pk_bf16(float lo, float hi) { unsigned r; asm volatile("v_cvt_pk_bf16_f32 %0, %1, %2" : "=v"(r) : "v"(lo), "v"(hi)); return r; }
;     __device__ __forceinline__ void operator()(const f32x4 (&acc)[2][2][4][2], const Unit& u, int wr, int wc, int fr, int fq) const {
;     ...
;             for (int m = 0; m < 4; ++m) { const int row = row0 + ai * HALF + m * 16; const size_t off = (size_t)row * 1024 + col0; float s = 0.f;
; #pragma unroll
;                 for (int bj = 0; bj < 2; ++bj) { f32x4 b0, b1;
;                     if (base32) { b0 = *(const f32x4*)(base32 + off + bj * HALF); b1 = *(const f32x4*)(base32 + off + bj * HALF + 4); }
;                     else { const u32x4 hv = hv4[m][bj];
;                         b0 = (f32x4){__builtin_bit_cast(float, hv.x << 16), __builtin_bit_cast(float, hv.x & 0xffff0000u), __builtin_bit_cast(float, hv.y << 16), __builtin_bit_cast(float, hv.y & 0xffff0000u)};
;                         b1 = (f32x4){__builtin_bit_cast(float, hv.z << 16), __builtin_bit_cast(float, hv.z & 0xffff0000u), __builtin_bit_cast(float, hv.w << 16), __builtin_bit_cast(float, hv.w & 0xffff0000u)}; }
;                     const f32x4 o0 = b0 + acc[ai][bj][m][0], o1 = b1 + acc[ai][bj][m][1];
;                     s += ((o0[0] * o0[0] + o0[1] * o0[1]) + (o0[2] * o0[2] + o0[3] * o0[3])) + ((o1[0] * o1[0] + o1[1] * o1[1]) + (o1[2] * o1[2] + o1[3] * o1[3]));
;                     u32x4 w; w.x = cvt_pk_bf16(o0[0], o0[1]); w.y = cvt_pk_bf16(o0[2], o0[3]); w.z = cvt_pk_bf16(o1[0], o1[1]); w.w = cvt_pk_bf16(o1[2], o1[3]); *(u32x4*)(hb + off + bj * HALF) = w; }
;                 s += __shfl_xor(s, 16); s += __shfl_xor(s, 32);
;                 if (fq == 0) P[(wr * 64 + ai * HALF + m * 16 + fr) * 4 + wc] = s;
;                 asm volatile("" ::: "memory"); }
.LBB0_690:
	s_waitcnt vmcnt(0)
	v_pk_add_f32 v[40:41], v[40:41], v[44:45]
	v_pk_add_f32 v[38:39], v[38:39], v[42:43]
	v_pk_add_f32 v[44:45], v[34:35], v[46:47]
	v_mul_f32_e32 v34, v39, v39
	v_mul_f32_e32 v35, v41, v41
	v_pk_add_f32 v[42:43], v[36:37], v[48:49]
	v_fmac_f32_e32 v34, v38, v38
	v_fmac_f32_e32 v35, v40, v40
	v_mul_f32_e32 v56, v65, v65
	v_mul_f32_e32 v57, v61, v61
	v_mul_f32_e32 v55, v55, v55
	v_mul_f32_e32 v53, v53, v53
	v_add_f32_e32 v34, v34, v35
	v_mul_f32_e32 v35, v45, v45
	v_mul_f32_e32 v36, v43, v43
	v_fmac_f32_e32 v56, v64, v64
	v_fmac_f32_e32 v57, v60, v60
	v_fmac_f32_e32 v55, v54, v54
	v_fmac_f32_e32 v53, v52, v52
	v_fmac_f32_e32 v35, v44, v44
	v_fmac_f32_e32 v36, v42, v42
	v_add_f32_e32 v56, v56, v57
	v_add_f32_e32 v52, v55, v53
	v_add_f32_e32 v35, v35, v36
	v_add_f32_e32 v52, v52, v56
	v_add_f32_e32 v34, v35, v34
	v_add_f32_e32 v34, v52, v34
	ds_bpermute_b32 v35, v164, v34
	v_cvt_pk_bf16_f32 v36, v38, v39
	v_cvt_pk_bf16_f32 v37, v40, v41
	v_cvt_pk_bf16_f32 v38, v44, v45
	v_cvt_pk_bf16_f32 v39, v42, v43
	s_waitcnt lgkmcnt(0)
	v_add_f32_e32 v34, v34, v35
	ds_bpermute_b32 v35, v165, v34
	global_store_dwordx4 v[50:51], v[36:39], off offset:256 sc1
	s_and_saveexec_b64 s[36:37], s[12:13]
	s_cbranch_execz .LBB0_692
	s_waitcnt lgkmcnt(0)
	v_add_f32_e32 v34, v34, v35
	ds_write_b32 v162, v34 offset:2304

; __device__ __forceinline__ unsigned cvt_pk_bf16(float lo, float hi) { unsigned r; asm volatile("v_cvt_pk_bf16_f32 %0, %1, %2" : "=v"(r) : "v"(lo), "v"(hi)); return r; }
;     __device__ __forceinline__ void operator()(const f32x4 (&acc)[2][2][4][2], const Unit& u, int wr, int wc, int fr, int fq) const {
;     ...
;             for (int m = 0; m < 4; ++m) { const int row = row0 + ai * HALF + m * 16; const size_t off = (size_t)row * 1024 + col0; float s = 0.f;
; #pragma unroll
;                 for (int bj = 0; bj < 2; ++bj) { f32x4 b0, b1;
;                     if (base32) { b0 = *(const f32x4*)(base32 + off + bj * HALF); b1 = *(const f32x4*)(base32 + off + bj * HALF + 4); }
;                     else { const u32x4 hv = hv4[m][bj];
;                         b0 = (f32x4){__builtin_bit_cast(float, hv.x << 16), __builtin_bit_cast(float, hv.x & 0xffff0000u), __builtin_bit_cast(float, hv.y << 16), __builtin_bit_cast(float, hv.y & 0xffff0000u)};
;                         b1 = (f32x4){__builtin_bit_cast(float, hv.z << 16), __builtin_bit_cast(float, hv.z & 0xffff0000u), __builtin_bit_cast(float, hv.w << 16), __builtin_bit_cast(float, hv.w & 0xffff0000u)}; }
;                     const f32x4 o0 = b0 + acc[ai][bj][m][0], o1 = b1 + acc[ai][bj][m][1];
;                     s += ((o0[0] * o0[0] + o0[1] * o0[1]) + (o0[2] * o0[2] + o0[3] * o0[3])) + ((o1[0] * o1[0] + o1[1] * o1[1]) + (o1[2] * o1[2] + o1[3] * o1[3]));
;                     u32x4 w; w.x = cvt_pk_bf16(o0[0], o0[1]); w.y = cvt_pk_bf16(o0[2], o0[3]); w.z = cvt_pk_bf16(o1[0], o1[1]); w.w = cvt_pk_bf16(o1[2], o1[3]); *(u32x4*)(hb + off + bj * HALF) = w; }
.LBB0_695:
	s_waitcnt vmcnt(0)
	v_pk_add_f32 v[44:45], v[32:33], v[36:37]
	v_pk_add_f32 v[48:49], v[30:31], v[34:35]
	v_pk_add_f32 v[36:37], v[28:29], v[40:41]
	v_pk_add_f32 v[38:39], v[26:27], v[38:39]
	v_lshl_add_u64 v[34:35], v[46:47], 1, s[14:15]
	s_and_b64 vcc, exec, s[10:11]
	v_cvt_pk_bf16_f32 v26, v48, v49
	v_cvt_pk_bf16_f32 v27, v44, v45
	v_cvt_pk_bf16_f32 v28, v38, v39
	v_cvt_pk_bf16_f32 v29, v36, v37
	global_store_dwordx4 v[34:35], v[26:29], off sc1
	s_cbranch_vccnz .LBB0_727
	global_load_dwordx4 v[30:33], v[42:43], off offset:528
	global_load_dwordx4 v[26:29], v[42:43], off offset:512
	s_cbranch_execnz .LBB0_698

; __device__ __forceinline__ unsigned cvt_pk_bf16(float lo, float hi) { unsigned r; asm volatile("v_cvt_pk_bf16_f32 %0, %1, %2" : "=v"(r) : "v"(lo), "v"(hi)); return r; }
;     __device__ __forceinline__ void operator()(const f32x4 (&acc)[2][2][4][2], const Unit& u, int wr, int wc, int fr, int fq) const {
;     ...
;             for (int m = 0; m < 4; ++m) { const int row = row0 + ai * HALF + m * 16; const size_t off = (size_t)row * 1024 + col0; float s = 0.f;
; #pragma unroll
;                 for (int bj = 0; bj < 2; ++bj) { f32x4 b0, b1;
;                     if (base32) { b0 = *(const f32x4*)(base32 + off + bj * HALF); b1 = *(const f32x4*)(base32 + off + bj * HALF + 4); }
;                     else { const u32x4 hv = hv4[m][bj];
;                         b0 = (f32x4){__builtin_bit_cast(float, hv.x << 16), __builtin_bit_cast(float, hv.x & 0xffff0000u), __builtin_bit_cast(float, hv.y << 16), __builtin_bit_cast(float, hv.y & 0xffff0000u)};
;                         b1 = (f32x4){__builtin_bit_cast(float, hv.z << 16), __builtin_bit_cast(float, hv.z & 0xffff0000u), __builtin_bit_cast(float, hv.w << 16), __builtin_bit_cast(float, hv.w & 0xffff0000u)}; }
;                     const f32x4 o0 = b0 + acc[ai][bj][m][0], o1 = b1 + acc[ai][bj][m][1];
;                     s += ((o0[0] * o0[0] + o0[1] * o0[1]) + (o0[2] * o0[2] + o0[3] * o0[3])) + ((o1[0] * o1[0] + o1[1] * o1[1]) + (o1[2] * o1[2] + o1[3] * o1[3]));
;                     u32x4 w; w.x = cvt_pk_bf16(o0[0], o0[1]); w.y = cvt_pk_bf16(o0[2], o0[3]); w.z = cvt_pk_bf16(o1[0], o1[1]); w.w = cvt_pk_bf16(o1[2], o1[3]); *(u32x4*)(hb + off + bj * HALF) = w; }
;                 s += __shfl_xor(s, 16); s += __shfl_xor(s, 32);
;                 if (fq == 0) P[(wr * 64 + ai * HALF + m * 16 + fr) * 4 + wc] = s;
;                 asm volatile("" ::: "memory"); }
.LBB0_698:
	s_waitcnt vmcnt(0)
	v_pk_add_f32 v[24:25], v[24:25], v[28:29]
	v_pk_add_f32 v[22:23], v[22:23], v[26:27]
	v_pk_add_f32 v[28:29], v[18:19], v[30:31]
	v_mul_f32_e32 v18, v23, v23
	v_mul_f32_e32 v19, v25, v25
	v_pk_add_f32 v[26:27], v[20:21], v[32:33]
	v_fmac_f32_e32 v18, v22, v22
	v_fmac_f32_e32 v19, v24, v24
	v_mul_f32_e32 v40, v49, v49
	v_mul_f32_e32 v41, v45, v45
	v_mul_f32_e32 v39, v39, v39
	v_mul_f32_e32 v37, v37, v37
	v_add_f32_e32 v18, v18, v19
	v_mul_f32_e32 v19, v29, v29
	v_mul_f32_e32 v20, v27, v27
	v_fmac_f32_e32 v40, v48, v48
	v_fmac_f32_e32 v41, v44, v44
	v_fmac_f32_e32 v39, v38, v38
	v_fmac_f32_e32 v37, v36, v36
	v_fmac_f32_e32 v19, v28, v28
	v_fmac_f32_e32 v20, v26, v26
	v_add_f32_e32 v40, v40, v41
	v_add_f32_e32 v36, v39, v37
	v_add_f32_e32 v19, v19, v20
	v_add_f32_e32 v36, v36, v40
	v_add_f32_e32 v18, v19, v18
	v_add_f32_e32 v18, v36, v18
	ds_bpermute_b32 v19, v164, v18
	v_cvt_pk_bf16_f32 v20, v22, v23
	v_cvt_pk_bf16_f32 v21, v24, v25
	v_cvt_pk_bf16_f32 v22, v28, v29
	v_cvt_pk_bf16_f32 v23, v26, v27
	s_waitcnt lgkmcnt(0)
	v_add_f32_e32 v18, v18, v19
	ds_bpermute_b32 v19, v165, v18
	global_store_dwordx4 v[34:35], v[20:23], off offset:256 sc1
	s_and_saveexec_b64 s[36:37], s[12:13]
	s_cbranch_execz .LBB0_700
	s_waitcnt lgkmcnt(0)
	v_add_f32_e32 v18, v18, v19
	ds_write_b32 v162, v18 offset:2560

; __device__ __forceinline__ unsigned cvt_pk_bf16(float lo, float hi) { unsigned r; asm volatile("v_cvt_pk_bf16_f32 %0, %1, %2" : "=v"(r) : "v"(lo), "v"(hi)); return r; }
;     __device__ __forceinline__ void operator()(const f32x4 (&acc)[2][2][4][2], const Unit& u, int wr, int wc, int fr, int fq) const {
;     ...
;             for (int m = 0; m < 4; ++m) { const int row = row0 + ai * HALF + m * 16; const size_t off = (size_t)row * 1024 + col0; float s = 0.f;
; #pragma unroll
;                 for (int bj = 0; bj < 2; ++bj) { f32x4 b0, b1;
;                     if (base32) { b0 = *(const f32x4*)(base32 + off + bj * HALF); b1 = *(const f32x4*)(base32 + off + bj * HALF + 4); }
;                     else { const u32x4 hv = hv4[m][bj];
;                         b0 = (f32x4){__builtin_bit_cast(float, hv.x << 16), __builtin_bit_cast(float, hv.x & 0xffff0000u), __builtin_bit_cast(float, hv.y << 16), __builtin_bit_cast(float, hv.y & 0xffff0000u)};
;                         b1 = (f32x4){__builtin_bit_cast(float, hv.z << 16), __builtin_bit_cast(float, hv.z & 0xffff0000u), __builtin_bit_cast(float, hv.w << 16), __builtin_bit_cast(float, hv.w & 0xffff0000u)}; }
;                     const f32x4 o0 = b0 + acc[ai][bj][m][0], o1 = b1 + acc[ai][bj][m][1];
;                     s += ((o0[0] * o0[0] + o0[1] * o0[1]) + (o0[2] * o0[2] + o0[3] * o0[3])) + ((o1[0] * o1[0] + o1[1] * o1[1]) + (o1[2] * o1[2] + o1[3] * o1[3]));
;                     u32x4 w; w.x = cvt_pk_bf16(o0[0], o0[1]); w.y = cvt_pk_bf16(o0[2], o0[3]); w.z = cvt_pk_bf16(o1[0], o1[1]); w.w = cvt_pk_bf16(o1[2], o1[3]); *(u32x4*)(hb + off + bj * HALF) = w; }
.LBB0_703:
	s_waitcnt vmcnt(0)
	v_pk_add_f32 v[28:29], v[16:17], v[20:21]
	v_pk_add_f32 v[32:33], v[14:15], v[18:19]
	v_pk_add_f32 v[20:21], v[12:13], v[24:25]
	v_pk_add_f32 v[22:23], v[10:11], v[22:23]
	v_lshl_add_u64 v[18:19], v[30:31], 1, s[14:15]
	s_and_b64 vcc, exec, s[10:11]
	v_cvt_pk_bf16_f32 v10, v32, v33
	v_cvt_pk_bf16_f32 v11, v28, v29
	v_cvt_pk_bf16_f32 v12, v22, v23
	v_cvt_pk_bf16_f32 v13, v20, v21
	global_store_dwordx4 v[18:19], v[10:13], off sc1
	s_cbranch_vccnz .LBB0_729
	global_load_dwordx4 v[14:17], v[26:27], off offset:528
	global_load_dwordx4 v[10:13], v[26:27], off offset:512
	s_cbranch_execnz .LBB0_706

; #define PG8_LAS __attribute__((address_space(3)))
; __device__ __forceinline__ unsigned cvt_pk_bf16(float lo, float hi) { unsigned r; asm volatile("v_cvt_pk_bf16_f32 %0, %1, %2" : "=v"(r) : "v"(lo), "v"(hi)); return r; }
;     __device__ __forceinline__ void operator()(const f32x4 (&acc)[2][2][4][2], const Unit& u, int wr, int wc, int fr, int fq) const {
;     ...
;             for (int m = 0; m < 4; ++m) { const int row = row0 + ai * HALF + m * 16; const size_t off = (size_t)row * 1024 + col0; float s = 0.f;
; #pragma unroll
;                 for (int bj = 0; bj < 2; ++bj) { f32x4 b0, b1;
;                     if (base32) { b0 = *(const f32x4*)(base32 + off + bj * HALF); b1 = *(const f32x4*)(base32 + off + bj * HALF + 4); }
;                     else { const u32x4 hv = hv4[m][bj];
;                         b0 = (f32x4){__builtin_bit_cast(float, hv.x << 16), __builtin_bit_cast(float, hv.x & 0xffff0000u), __builtin_bit_cast(float, hv.y << 16), __builtin_bit_cast(float, hv.y & 0xffff0000u)};
;                         b1 = (f32x4){__builtin_bit_cast(float, hv.z << 16), __builtin_bit_cast(float, hv.z & 0xffff0000u), __builtin_bit_cast(float, hv.w << 16), __builtin_bit_cast(float, hv.w & 0xffff0000u)}; }
;                     const f32x4 o0 = b0 + acc[ai][bj][m][0], o1 = b1 + acc[ai][bj][m][1];
;                     s += ((o0[0] * o0[0] + o0[1] * o0[1]) + (o0[2] * o0[2] + o0[3] * o0[3])) + ((o1[0] * o1[0] + o1[1] * o1[1]) + (o1[2] * o1[2] + o1[3] * o1[3]));
;                     u32x4 w; w.x = cvt_pk_bf16(o0[0], o0[1]); w.y = cvt_pk_bf16(o0[2], o0[3]); w.z = cvt_pk_bf16(o1[0], o1[1]); w.w = cvt_pk_bf16(o1[2], o1[3]); *(u32x4*)(hb + off + bj * HALF) = w; }
;                 s += __shfl_xor(s, 16); s += __shfl_xor(s, 32);
;                 if (fq == 0) P[(wr * 64 + ai * HALF + m * 16 + fr) * 4 + wc] = s;
;                 asm volatile("" ::: "memory"); }
;         }
;         asm volatile("s_waitcnt lgkmcnt(0)" ::: "memory"); __builtin_amdgcn_s_barrier(); asm volatile("" ::: "memory");
;         { const int t = (wr * 4 + wc) * 64 + fq * 16 + fr; if (t < 256) { const f32x4 v = *(const PG8_LAS f32x4*)(P + t * 4); ssq[(size_t)(row_off + u.pm * BM + t) * 4 + u.pn] = (v[0] + v[1]) + (v[2] + v[3]); } }
.LBB0_706:
	s_waitcnt vmcnt(0)
	v_pk_add_f32 v[8:9], v[8:9], v[12:13]
	v_pk_add_f32 v[6:7], v[6:7], v[10:11]
	v_pk_add_f32 v[12:13], v[2:3], v[14:15]
	v_mul_f32_e32 v2, v7, v7
	v_mul_f32_e32 v3, v9, v9
	v_pk_add_f32 v[10:11], v[4:5], v[16:17]
	v_fmac_f32_e32 v2, v6, v6
	v_fmac_f32_e32 v3, v8, v8
	v_mul_f32_e32 v24, v33, v33
	v_mul_f32_e32 v25, v29, v29
	v_mul_f32_e32 v23, v23, v23
	v_mul_f32_e32 v21, v21, v21
	v_add_f32_e32 v2, v2, v3
	v_mul_f32_e32 v3, v13, v13
	v_mul_f32_e32 v4, v11, v11
	v_fmac_f32_e32 v24, v32, v32
	v_fmac_f32_e32 v25, v28, v28
	v_fmac_f32_e32 v23, v22, v22
	v_fmac_f32_e32 v21, v20, v20
	v_fmac_f32_e32 v3, v12, v12
	v_fmac_f32_e32 v4, v10, v10
	v_add_f32_e32 v24, v24, v25
	v_add_f32_e32 v20, v23, v21
	v_add_f32_e32 v3, v3, v4
	v_add_f32_e32 v20, v20, v24
	v_add_f32_e32 v2, v3, v2
	v_add_f32_e32 v2, v20, v2
	ds_bpermute_b32 v3, v164, v2
	v_cvt_pk_bf16_f32 v4, v6, v7
	v_cvt_pk_bf16_f32 v5, v8, v9
	v_cvt_pk_bf16_f32 v6, v12, v13
	v_cvt_pk_bf16_f32 v7, v10, v11
	s_waitcnt lgkmcnt(0)
	v_add_f32_e32 v2, v2, v3
	ds_bpermute_b32 v3, v165, v2
	global_store_dwordx4 v[18:19], v[4:7], off offset:256 sc1
	s_and_saveexec_b64 s[10:11], s[12:13]
	s_cbranch_execz .LBB0_708
	s_waitcnt lgkmcnt(0)
	v_add_f32_e32 v2, v2, v3
	ds_write_b32 v162, v2 offset:2816
.LBB0_708:
	s_or_b64 exec, exec, s[10:11]
	s_waitcnt lgkmcnt(0)
	s_barrier
	v_lshlrev_b32_e32 v2, 4, v206
	v_add3_u32 v2, s52, v205, v2
	v_cmp_gt_i32_e32 vcc, s91, v2
	s_and_saveexec_b64 s[10:11], vcc
	s_cbranch_execz .LBB0_710
	s_waitcnt lgkmcnt(0)
	v_lshl_add_u32 v3, v2, 4, 0
	v_add_u32_e32 v3, 0x20000, v3
	ds_read_b128 v[4:7], v3
	v_add_u32_e32 v2, s25, v2
	v_ashrrev_i32_e32 v3, 31, v2
	s_ashr_i32 s25, s24, 31
	v_lshl_add_u64 v[2:3], v[2:3], 4, s[16:17]
	s_waitcnt lgkmcnt(0)
	v_mov_b32_e32 v8, v5
	v_mov_b32_e32 v9, v6
	v_mov_b32_e32 v5, v7
	v_pk_add_f32 v[4:5], v[8:9], v[4:5]
	v_lshl_add_u64 v[2:3], s[24:25], 2, v[2:3]
	v_add_f32_e32 v4, v4, v5
	global_store_dword v[2:3], v4, off sc1

;     __device__ __forceinline__ void operator()(const f32x4 (&acc)[2][2][4][2], const Unit& u, int wr, int wc, int fr, int fq) const {
;     ...
;         float rsv[2][4];
; #pragma unroll
;         for (int ai = 0; ai < 2; ++ai)
; #pragma unroll
;             for (int m = 0; m < 4; ++m) rsv[ai][m] = row_rstd(ssq, row0 + ai * HALF + m * 16 + row_off) * sc;
.LBB0_815:
	v_add_u32_e32 v233, s40, v1
	v_lshlrev_b32_e32 v233, 4, v233
	v_add_u32_e32 v233, 0x21000, v233
	v_mov_b32_e32 v142, v1
	v_mov_b32_e32 v153, v143
	s_cmp_eq_u32 s4, -1
	s_cbranch_scc1 .LBB0_817
	s_lshl_b32 s5, s5, 8
	s_add_i32 s5, s5, s40
	v_add_u32_e32 v170, s5, v142
	v_ashrrev_i32_e32 v171, 31, v170
	ds_read_b128 v[154:157], v233
	v_add_u32_e32 v168, 16, v170
	v_ashrrev_i32_e32 v169, 31, v168
	v_add_u32_e32 v166, 32, v170
	v_ashrrev_i32_e32 v167, 31, v166
	v_add_u32_e32 v164, 48, v170
	v_ashrrev_i32_e32 v165, 31, v164
	v_add_u32_e32 v150, 0xa0, v170
	v_ashrrev_i32_e32 v151, 31, v150
	s_lshl_b32 s4, s4, 8
	s_or_b32 s4, s4, s41
	s_waitcnt lgkmcnt(0)
	v_mov_b32_e32 v146, v155
	v_mov_b32_e32 v147, v156
	v_mov_b32_e32 v155, v157
	v_pk_add_f32 v[146:147], v[146:147], v[154:155]
	s_nop 0
	v_add_f32_e32 v142, v146, v147
	ds_read_b128 v[154:157], v233 offset:256
	v_fmamk_f32 v142, v142, 0x3a800000, v175
	v_rsq_f32_e32 v162, v142
	s_waitcnt lgkmcnt(0)
	v_mov_b32_e32 v146, v155
	v_mov_b32_e32 v147, v156
	v_mov_b32_e32 v155, v157
	v_pk_add_f32 v[146:147], v[146:147], v[154:155]
	v_pk_mul_f32 v[128:129], v[128:129], v[162:163] op_sel_hi:[1,0]
	v_add_f32_e32 v142, v146, v147
	ds_read_b128 v[154:157], v233 offset:512
	v_fmamk_f32 v142, v142, 0x3a800000, v175
	v_rsq_f32_e32 v160, v142
	v_pk_mul_f32 v[126:127], v[126:127], v[162:163] op_sel_hi:[1,0]
	v_pk_mul_f32 v[120:121], v[120:121], v[162:163] op_sel_hi:[1,0]
	v_pk_mul_f32 v[118:119], v[118:119], v[162:163] op_sel_hi:[1,0]
	v_pk_mul_f32 v[114:115], v[114:115], v[160:161] op_sel_hi:[1,0]
	v_pk_mul_f32 v[104:105], v[104:105], v[160:161] op_sel_hi:[1,0]
	v_pk_mul_f32 v[102:103], v[102:103], v[160:161] op_sel_hi:[1,0]
	s_waitcnt lgkmcnt(0)
	v_mov_b32_e32 v146, v155
	v_mov_b32_e32 v147, v156
	v_mov_b32_e32 v155, v157
	v_pk_add_f32 v[146:147], v[146:147], v[154:155]
	s_nop 0
	v_add_f32_e32 v142, v146, v147
	ds_read_b128 v[156:159], v233 offset:768
	v_fmamk_f32 v142, v142, 0x3a800000, v175
	v_rsq_f32_e32 v154, v142
	s_waitcnt lgkmcnt(0)
	v_mov_b32_e32 v146, v157
	v_mov_b32_e32 v147, v158
	v_mov_b32_e32 v157, v159
	v_add_u32_e32 v158, 0x80, v170
	v_pk_add_f32 v[146:147], v[146:147], v[156:157]
	v_ashrrev_i32_e32 v159, 31, v158
	v_add_f32_e32 v142, v146, v147
	ds_read_b128 v[180:183], v233 offset:2048
	v_add_u32_e32 v156, 0x90, v170
	v_fmamk_f32 v142, v142, 0x3a800000, v175
	v_ashrrev_i32_e32 v157, 31, v156
	v_rsq_f32_e32 v152, v142
	s_waitcnt lgkmcnt(0)
	v_mov_b32_e32 v146, v181
	v_mov_b32_e32 v147, v182
	v_mov_b32_e32 v181, v183
	v_pk_add_f32 v[146:147], v[146:147], v[180:181]
	v_pk_mul_f32 v[82:83], v[82:83], v[152:153] op_sel_hi:[1,0]
	v_add_f32_e32 v142, v146, v147
	ds_read_b128 v[180:183], v233 offset:2304
	v_fmamk_f32 v142, v142, 0x3a800000, v175
	v_rsq_f32_e32 v148, v142
	v_pk_mul_f32 v[72:73], v[72:73], v[152:153] op_sel_hi:[1,0]
	v_pk_mul_f32 v[70:71], v[70:71], v[152:153] op_sel_hi:[1,0]
	v_pk_mul_f32 v[64:65], v[64:65], v[148:149] op_sel_hi:[1,0]
	v_pk_mul_f32 v[62:63], v[62:63], v[148:149] op_sel_hi:[1,0]
	v_pk_mul_f32 v[56:57], v[56:57], v[148:149] op_sel_hi:[1,0]
	v_pk_mul_f32 v[54:55], v[54:55], v[148:149] op_sel_hi:[1,0]
	s_waitcnt lgkmcnt(0)
	v_mov_b32_e32 v146, v181
	v_mov_b32_e32 v147, v182
	v_mov_b32_e32 v181, v183
	v_pk_add_f32 v[146:147], v[146:147], v[180:181]
	s_nop 0
	v_add_f32_e32 v142, v146, v147
	ds_read_b128 v[180:183], v233 offset:2560
	v_fmamk_f32 v142, v142, 0x3a800000, v175
	v_rsq_f32_e32 v144, v142
	s_waitcnt lgkmcnt(0)
	v_mov_b32_e32 v146, v181
	v_mov_b32_e32 v147, v182
	v_mov_b32_e32 v181, v183
	v_pk_add_f32 v[146:147], v[146:147], v[180:181]
	v_pk_mul_f32 v[50:51], v[50:51], v[144:145] op_sel_hi:[1,0]
	v_add_f32_e32 v142, v146, v147
	v_add_u32_e32 v146, 0xb0, v170
	v_ashrrev_i32_e32 v147, 31, v146
	ds_read_b128 v[180:183], v233 offset:2816
	v_lshlrev_b64 v[170:171], 12, v[170:171]
	v_fmamk_f32 v142, v142, 0x3a800000, v175
	v_rsq_f32_e32 v142, v142
	v_pk_mul_f32 v[40:41], v[40:41], v[144:145] op_sel_hi:[1,0]
	v_pk_mul_f32 v[38:39], v[38:39], v[144:145] op_sel_hi:[1,0]
	v_pk_mul_f32 v[34:35], v[34:35], v[142:143] op_sel_hi:[1,0]
	v_pk_mul_f32 v[24:25], v[24:25], v[142:143] op_sel_hi:[1,0]
	v_pk_mul_f32 v[22:23], v[22:23], v[142:143] op_sel_hi:[1,0]
	s_waitcnt lgkmcnt(0)
; __device__ __forceinline__ unsigned cvt_pk_bf16(float lo, float hi) { unsigned r; asm volatile("v_cvt_pk_bf16_f32 %0, %1, %2" : "=v"(r) : "v"(lo), "v"(hi)); return r; }
;     __device__ __forceinline__ void operator()(const f32x4 (&acc)[2][2][4][2], const Unit& u, int wr, int wc, int fr, int fq) const {
;     ...
; #pragma unroll
;         for (int ai = 0; ai < 2; ++ai)
; #pragma unroll
;             for (int m = 0; m < 4; ++m) { const int row = row0 + ai * HALF + m * 16; const float rs = rsv[ai][m]; bf16_t* rowp = base + (size_t)row * ldc + col0;
; #pragma unroll
;                 for (int bj = 0; bj < 2; ++bj) { const f32x4 v0 = acc[ai][bj][m][0] * rs, v1 = acc[ai][bj][m][1] * rs;
;                     u32x4 w; w.x = cvt_pk_bf16(v0[0], v0[1]); w.y = cvt_pk_bf16(v0[2], v0[3]); w.z = cvt_pk_bf16(v1[0], v1[1]); w.w = cvt_pk_bf16(v1[2], v1[3]);
;                     *(u32x4*)(rowp + bj * HALF) = w; } asm volatile("" ::: "memory"); }
	v_mov_b32_e32 v172, v181
	v_mov_b32_e32 v173, v182
	v_mov_b32_e32 v181, v183
	v_pk_add_f32 v[172:173], v[172:173], v[180:181]
	v_lshl_add_u32 v180, v153, 3, s4
	v_ashrrev_i32_e32 v181, 31, v180
	v_lshl_add_u64 v[180:181], v[180:181], 1, s[12:13]
	v_lshl_add_u64 v[170:171], v[180:181], 0, v[170:171]
	v_pk_mul_f32 v[182:183], v[124:125], v[162:163] op_sel_hi:[1,0]
	v_pk_mul_f32 v[124:125], v[122:123], v[162:163] op_sel_hi:[1,0]
	v_cvt_pk_bf16_f32 v122, v126, v127
	v_cvt_pk_bf16_f32 v123, v128, v129
	v_add_f32_e32 v155, v172, v173
	v_cvt_pk_bf16_f32 v124, v124, v125
	v_cvt_pk_bf16_f32 v125, v182, v183
	global_store_dwordx4 v[170:171], v[122:125], off sc1
	v_fmamk_f32 v155, v155, 0x3a800000, v175
	v_pk_mul_f32 v[98:99], v[98:99], v[154:155] op_sel_hi:[1,0]
	v_pk_mul_f32 v[122:123], v[112:113], v[162:163] op_sel_hi:[1,0]
	v_pk_mul_f32 v[112:113], v[110:111], v[162:163] op_sel_hi:[1,0]
	v_cvt_pk_bf16_f32 v110, v118, v119
	v_cvt_pk_bf16_f32 v111, v120, v121
	v_pk_mul_f32 v[88:89], v[88:89], v[154:155] op_sel_hi:[1,0]
	v_cvt_pk_bf16_f32 v112, v112, v113
	v_cvt_pk_bf16_f32 v113, v122, v123
	global_store_dwordx4 v[170:171], v[110:113], off offset:256 sc1
	v_pk_mul_f32 v[86:87], v[86:87], v[154:155] op_sel_hi:[1,0]
	v_rsq_f32_e32 v172, v155
	v_lshlrev_b64 v[110:111], 12, v[168:169]
	v_lshl_add_u64 v[110:111], v[180:181], 0, v[110:111]
	v_pk_mul_f32 v[112:113], v[116:117], v[160:161] op_sel_hi:[1,0]
	v_pk_mul_f32 v[116:117], v[108:109], v[160:161] op_sel_hi:[1,0]
	v_pk_mul_f32 v[108:109], v[106:107], v[160:161] op_sel_hi:[1,0]
	v_cvt_pk_bf16_f32 v106, v114, v115
	v_cvt_pk_bf16_f32 v107, v112, v113
	v_pk_mul_f32 v[18:19], v[18:19], v[172:173] op_sel_hi:[1,0]
	v_cvt_pk_bf16_f32 v108, v108, v109
	v_cvt_pk_bf16_f32 v109, v116, v117
	global_store_dwordx4 v[110:111], v[106:109], off sc1
	v_pk_mul_f32 v[8:9], v[8:9], v[172:173] op_sel_hi:[1,0]
	v_pk_mul_f32 v[6:7], v[6:7], v[172:173] op_sel_hi:[1,0]
	v_pk_mul_f32 v[106:107], v[96:97], v[160:161] op_sel_hi:[1,0]
	v_pk_mul_f32 v[96:97], v[94:95], v[160:161] op_sel_hi:[1,0]
	v_cvt_pk_bf16_f32 v94, v102, v103
	v_cvt_pk_bf16_f32 v95, v104, v105
	s_nop 0
	v_cvt_pk_bf16_f32 v96, v96, v97
	v_cvt_pk_bf16_f32 v97, v106, v107
	global_store_dwordx4 v[110:111], v[94:97], off offset:256 sc1
	s_nop 1
	v_lshlrev_b64 v[94:95], 12, v[166:167]
	v_lshl_add_u64 v[94:95], v[180:181], 0, v[94:95]
	v_pk_mul_f32 v[96:97], v[100:101], v[154:155] op_sel_hi:[1,0]
	v_pk_mul_f32 v[100:101], v[92:93], v[154:155] op_sel_hi:[1,0]
	v_pk_mul_f32 v[92:93], v[90:91], v[154:155] op_sel_hi:[1,0]
	v_cvt_pk_bf16_f32 v90, v98, v99
	v_cvt_pk_bf16_f32 v91, v96, v97
	s_nop 0
	v_cvt_pk_bf16_f32 v92, v92, v93
	v_cvt_pk_bf16_f32 v93, v100, v101
	global_store_dwordx4 v[94:95], v[90:93], off sc1
	s_nop 1
	v_pk_mul_f32 v[90:91], v[80:81], v[154:155] op_sel_hi:[1,0]
	v_pk_mul_f32 v[80:81], v[78:79], v[154:155] op_sel_hi:[1,0]
	v_cvt_pk_bf16_f32 v78, v86, v87
	v_cvt_pk_bf16_f32 v79, v88, v89
	s_nop 0
	v_cvt_pk_bf16_f32 v80, v80, v81
	v_cvt_pk_bf16_f32 v81, v90, v91
	global_store_dwordx4 v[94:95], v[78:81], off offset:256 sc1
	s_nop 1
	v_lshlrev_b64 v[78:79], 12, v[164:165]
	v_lshl_add_u64 v[78:79], v[180:181], 0, v[78:79]
	v_pk_mul_f32 v[80:81], v[84:85], v[152:153] op_sel_hi:[1,0]
	v_pk_mul_f32 v[84:85], v[76:77], v[152:153] op_sel_hi:[1,0]
	v_pk_mul_f32 v[76:77], v[74:75], v[152:153] op_sel_hi:[1,0]
	v_cvt_pk_bf16_f32 v74, v82, v83
	v_cvt_pk_bf16_f32 v75, v80, v81
	s_nop 0
	v_cvt_pk_bf16_f32 v76, v76, v77
	v_cvt_pk_bf16_f32 v77, v84, v85
	global_store_dwordx4 v[78:79], v[74:77], off sc1
	s_nop 1
	v_pk_mul_f32 v[74:75], v[68:69], v[152:153] op_sel_hi:[1,0]
	v_pk_mul_f32 v[68:69], v[66:67], v[152:153] op_sel_hi:[1,0]
	v_cvt_pk_bf16_f32 v66, v70, v71
	v_cvt_pk_bf16_f32 v67, v72, v73
	s_nop 0
	v_cvt_pk_bf16_f32 v68, v68, v69
	v_cvt_pk_bf16_f32 v69, v74, v75
	global_store_dwordx4 v[78:79], v[66:69], off offset:256 sc1
	s_nop 1
	v_lshlrev_b64 v[66:67], 12, v[158:159]
	v_lshl_add_u64 v[66:67], v[180:181], 0, v[66:67]
	v_pk_mul_f32 v[68:69], v[60:61], v[148:149] op_sel_hi:[1,0]
	v_pk_mul_f32 v[60:61], v[58:59], v[148:149] op_sel_hi:[1,0]
	v_cvt_pk_bf16_f32 v58, v62, v63
	v_cvt_pk_bf16_f32 v59, v64, v65
	s_nop 0
	v_cvt_pk_bf16_f32 v60, v60, v61
	v_cvt_pk_bf16_f32 v61, v68, v69
	global_store_dwordx4 v[66:67], v[58:61], off sc1
	s_nop 1
	v_pk_mul_f32 v[58:59], v[48:49], v[148:149] op_sel_hi:[1,0]
	v_pk_mul_f32 v[48:49], v[46:47], v[148:149] op_sel_hi:[1,0]
	v_cvt_pk_bf16_f32 v46, v54, v55
	v_cvt_pk_bf16_f32 v47, v56, v57
	s_nop 0
	v_cvt_pk_bf16_f32 v48, v48, v49
	v_cvt_pk_bf16_f32 v49, v58, v59
	global_store_dwordx4 v[66:67], v[46:49], off offset:256 sc1
	s_nop 1
	v_lshlrev_b64 v[46:47], 12, v[156:157]
	v_lshl_add_u64 v[46:47], v[180:181], 0, v[46:47]
	v_pk_mul_f32 v[48:49], v[52:53], v[144:145] op_sel_hi:[1,0]
	v_pk_mul_f32 v[52:53], v[44:45], v[144:145] op_sel_hi:[1,0]
	v_pk_mul_f32 v[44:45], v[42:43], v[144:145] op_sel_hi:[1,0]
	v_cvt_pk_bf16_f32 v42, v50, v51
	v_cvt_pk_bf16_f32 v43, v48, v49
	s_nop 0
	v_cvt_pk_bf16_f32 v44, v44, v45
	v_cvt_pk_bf16_f32 v45, v52, v53
	global_store_dwordx4 v[46:47], v[42:45], off sc1
	s_nop 1
	v_pk_mul_f32 v[42:43], v[32:33], v[144:145] op_sel_hi:[1,0]
	v_pk_mul_f32 v[32:33], v[30:31], v[144:145] op_sel_hi:[1,0]
	v_cvt_pk_bf16_f32 v30, v38, v39
	v_cvt_pk_bf16_f32 v31, v40, v41
	s_nop 0
	v_cvt_pk_bf16_f32 v32, v32, v33
	v_cvt_pk_bf16_f32 v33, v42, v43
	global_store_dwordx4 v[46:47], v[30:33], off offset:256 sc1
	s_nop 1
	v_lshlrev_b64 v[30:31], 12, v[150:151]
	v_lshl_add_u64 v[30:31], v[180:181], 0, v[30:31]
	v_pk_mul_f32 v[32:33], v[36:37], v[142:143] op_sel_hi:[1,0]
	v_pk_mul_f32 v[36:37], v[28:29], v[142:143] op_sel_hi:[1,0]
	v_pk_mul_f32 v[28:29], v[26:27], v[142:143] op_sel_hi:[1,0]
	v_cvt_pk_bf16_f32 v26, v34, v35
	v_cvt_pk_bf16_f32 v27, v32, v33
	s_nop 0
	v_cvt_pk_bf16_f32 v28, v28, v29
	v_cvt_pk_bf16_f32 v29, v36, v37
	global_store_dwordx4 v[30:31], v[26:29], off sc1
	s_nop 1
	v_pk_mul_f32 v[26:27], v[16:17], v[142:143] op_sel_hi:[1,0]
	v_pk_mul_f32 v[16:17], v[14:15], v[142:143] op_sel_hi:[1,0]
	v_cvt_pk_bf16_f32 v14, v22, v23
	v_cvt_pk_bf16_f32 v15, v24, v25
	s_nop 0
	v_cvt_pk_bf16_f32 v16, v16, v17
	v_cvt_pk_bf16_f32 v17, v26, v27
	global_store_dwordx4 v[30:31], v[14:17], off offset:256 sc1
	s_nop 1
	v_lshlrev_b64 v[14:15], 12, v[146:147]
	v_lshl_add_u64 v[14:15], v[180:181], 0, v[14:15]
	v_pk_mul_f32 v[16:17], v[20:21], v[172:173] op_sel_hi:[1,0]
	v_pk_mul_f32 v[20:21], v[12:13], v[172:173] op_sel_hi:[1,0]
	v_pk_mul_f32 v[12:13], v[10:11], v[172:173] op_sel_hi:[1,0]
	v_cvt_pk_bf16_f32 v10, v18, v19
	v_cvt_pk_bf16_f32 v11, v16, v17
	s_nop 0
	v_cvt_pk_bf16_f32 v12, v12, v13
	v_cvt_pk_bf16_f32 v13, v20, v21
	global_store_dwordx4 v[14:15], v[10:13], off sc1
	s_nop 1
	v_pk_mul_f32 v[10:11], v[4:5], v[172:173] op_sel_hi:[1,0]
	v_pk_mul_f32 v[4:5], v[2:3], v[172:173] op_sel_hi:[1,0]
	v_cvt_pk_bf16_f32 v2, v6, v7
	v_cvt_pk_bf16_f32 v3, v8, v9
	s_nop 0
	v_cvt_pk_bf16_f32 v4, v4, v5
	v_cvt_pk_bf16_f32 v5, v10, v11
	global_store_dwordx4 v[14:15], v[2:5], off offset:256 sc1

; __device__ __forceinline__ unsigned cvt_pk_bf16(float lo, float hi) { unsigned r; asm volatile("v_cvt_pk_bf16_f32 %0, %1, %2" : "=v"(r) : "v"(lo), "v"(hi)); return r; }
;     __device__ __forceinline__ void operator()(const f32x4 (&acc)[2][2][4][2], const Unit& u, int wr, int wc, int fr, int fq) const {
;     ...
;             for (int m = 0; m < 4; ++m) { const int row = row0 + ai * HALF + m * 16; const size_t off = (size_t)row * 1024 + col0; float s = 0.f;
; #pragma unroll
;                 for (int bj = 0; bj < 2; ++bj) { f32x4 b0, b1;
;                     if (base32) { b0 = *(const f32x4*)(base32 + off + bj * HALF); b1 = *(const f32x4*)(base32 + off + bj * HALF + 4); }
;                     else { const u32x4 hv = hv4[m][bj];
;                         b0 = (f32x4){__builtin_bit_cast(float, hv.x << 16), __builtin_bit_cast(float, hv.x & 0xffff0000u), __builtin_bit_cast(float, hv.y << 16), __builtin_bit_cast(float, hv.y & 0xffff0000u)};
;                         b1 = (f32x4){__builtin_bit_cast(float, hv.z << 16), __builtin_bit_cast(float, hv.z & 0xffff0000u), __builtin_bit_cast(float, hv.w << 16), __builtin_bit_cast(float, hv.w & 0xffff0000u)}; }
;                     const f32x4 o0 = b0 + acc[ai][bj][m][0], o1 = b1 + acc[ai][bj][m][1];
;                     s += ((o0[0] * o0[0] + o0[1] * o0[1]) + (o0[2] * o0[2] + o0[3] * o0[3])) + ((o1[0] * o1[0] + o1[1] * o1[1]) + (o1[2] * o1[2] + o1[3] * o1[3]));
;                     u32x4 w; w.x = cvt_pk_bf16(o0[0], o0[1]); w.y = cvt_pk_bf16(o0[2], o0[3]); w.z = cvt_pk_bf16(o1[0], o1[1]); w.w = cvt_pk_bf16(o1[2], o1[3]); *(u32x4*)(hb + off + bj * HALF) = w; }
.LBB0_1086:
	s_waitcnt vmcnt(0)
	v_pk_add_f32 v[196:197], v[160:161], v[164:165]
	v_pk_add_f32 v[200:201], v[158:159], v[162:163]
	v_pk_add_f32 v[164:165], v[156:157], v[168:169]
	v_pk_add_f32 v[166:167], v[154:155], v[166:167]
	v_lshl_add_u64 v[162:163], v[198:199], 1, s[14:15]
	s_and_b64 vcc, exec, s[8:9]
	v_cvt_pk_bf16_f32 v154, v200, v201
	v_cvt_pk_bf16_f32 v155, v196, v197
	v_cvt_pk_bf16_f32 v156, v166, v167
	v_cvt_pk_bf16_f32 v157, v164, v165
	global_store_dwordx4 v[162:163], v[154:157], off sc1
	s_cbranch_vccnz .LBB0_1156
	global_load_dwordx4 v[158:161], v[194:195], off offset:528
	global_load_dwordx4 v[154:157], v[194:195], off offset:512
	s_cbranch_execnz .LBB0_1089

; __device__ __forceinline__ unsigned cvt_pk_bf16(float lo, float hi) { unsigned r; asm volatile("v_cvt_pk_bf16_f32 %0, %1, %2" : "=v"(r) : "v"(lo), "v"(hi)); return r; }
;     __device__ __forceinline__ void operator()(const f32x4 (&acc)[2][2][4][2], const Unit& u, int wr, int wc, int fr, int fq) const {
;     ...
;             for (int m = 0; m < 4; ++m) { const int row = row0 + ai * HALF + m * 16; const size_t off = (size_t)row * 1024 + col0; float s = 0.f;
; #pragma unroll
;                 for (int bj = 0; bj < 2; ++bj) { f32x4 b0, b1;
;                     if (base32) { b0 = *(const f32x4*)(base32 + off + bj * HALF); b1 = *(const f32x4*)(base32 + off + bj * HALF + 4); }
;                     else { const u32x4 hv = hv4[m][bj];
;                         b0 = (f32x4){__builtin_bit_cast(float, hv.x << 16), __builtin_bit_cast(float, hv.x & 0xffff0000u), __builtin_bit_cast(float, hv.y << 16), __builtin_bit_cast(float, hv.y & 0xffff0000u)};
;                         b1 = (f32x4){__builtin_bit_cast(float, hv.z << 16), __builtin_bit_cast(float, hv.z & 0xffff0000u), __builtin_bit_cast(float, hv.w << 16), __builtin_bit_cast(float, hv.w & 0xffff0000u)}; }
;                     const f32x4 o0 = b0 + acc[ai][bj][m][0], o1 = b1 + acc[ai][bj][m][1];
;                     s += ((o0[0] * o0[0] + o0[1] * o0[1]) + (o0[2] * o0[2] + o0[3] * o0[3])) + ((o1[0] * o1[0] + o1[1] * o1[1]) + (o1[2] * o1[2] + o1[3] * o1[3]));
;                     u32x4 w; w.x = cvt_pk_bf16(o0[0], o0[1]); w.y = cvt_pk_bf16(o0[2], o0[3]); w.z = cvt_pk_bf16(o1[0], o1[1]); w.w = cvt_pk_bf16(o1[2], o1[3]); *(u32x4*)(hb + off + bj * HALF) = w; }
;                 s += __shfl_xor(s, 16); s += __shfl_xor(s, 32);
;                 if (fq == 0) P[(wr * 64 + ai * HALF + m * 16 + fr) * 4 + wc] = s;
;                 asm volatile("" ::: "memory"); }
.LBB0_1089:
	s_waitcnt vmcnt(0)
	v_pk_add_f32 v[152:153], v[152:153], v[156:157]
	v_pk_add_f32 v[150:151], v[150:151], v[154:155]
	v_pk_add_f32 v[156:157], v[146:147], v[158:159]
	v_mul_f32_e32 v146, v151, v151
	v_mul_f32_e32 v147, v153, v153
	v_pk_add_f32 v[154:155], v[148:149], v[160:161]
	v_fmac_f32_e32 v146, v150, v150
	v_fmac_f32_e32 v147, v152, v152
	v_add_f32_e32 v146, v146, v147
	v_mul_f32_e32 v147, v157, v157
	v_mul_f32_e32 v148, v155, v155
	v_fmac_f32_e32 v147, v156, v156
	v_fmac_f32_e32 v148, v154, v154
	v_mul_f32_e32 v168, v201, v201
	v_mul_f32_e32 v169, v197, v197
	v_mul_f32_e32 v167, v167, v167
	v_mul_f32_e32 v165, v165, v165
	v_add_f32_e32 v147, v147, v148
	v_and_b32_e32 v148, 64, v225
	v_fmac_f32_e32 v168, v200, v200
	v_fmac_f32_e32 v169, v196, v196
	v_fmac_f32_e32 v167, v166, v166
	v_fmac_f32_e32 v165, v164, v164
	v_add_f32_e32 v146, v147, v146
	v_xor_b32_e32 v147, 16, v225
	v_add_u32_e32 v158, 64, v148
	v_add_f32_e32 v168, v168, v169
	v_add_f32_e32 v164, v167, v165
	v_cmp_lt_i32_e32 vcc, v147, v158
	v_add_f32_e32 v164, v164, v168
	v_add_f32_e32 v146, v164, v146
	v_cndmask_b32_e32 v147, v225, v147, vcc
	v_lshlrev_b32_e32 v164, 2, v147
	ds_bpermute_b32 v147, v164, v146
	v_cmp_eq_u32_e64 s[10:11], 0, v206
	v_cvt_pk_bf16_f32 v148, v150, v151
	v_cvt_pk_bf16_f32 v149, v152, v153
	v_cvt_pk_bf16_f32 v150, v156, v157
	s_waitcnt lgkmcnt(0)
	v_add_f32_e32 v146, v146, v147
	v_xor_b32_e32 v147, 32, v225
	v_cmp_lt_i32_e32 vcc, v147, v158
	v_cvt_pk_bf16_f32 v151, v154, v155
	global_store_dwordx4 v[162:163], v[148:151], off offset:256 sc1
	v_lshl_add_u32 v162, v207, 4, s53
	v_cndmask_b32_e32 v147, v225, v147, vcc
	v_lshlrev_b32_e32 v165, 2, v147
	ds_bpermute_b32 v147, v165, v146
	s_and_saveexec_b64 s[36:37], s[10:11]
	s_cbranch_execz .LBB0_1091
	s_waitcnt lgkmcnt(0)
	v_add_f32_e32 v146, v146, v147
	ds_write_b32 v162, v146

; __device__ __forceinline__ unsigned cvt_pk_bf16(float lo, float hi) { unsigned r; asm volatile("v_cvt_pk_bf16_f32 %0, %1, %2" : "=v"(r) : "v"(lo), "v"(hi)); return r; }
;     __device__ __forceinline__ void operator()(const f32x4 (&acc)[2][2][4][2], const Unit& u, int wr, int wc, int fr, int fq) const {
;     ...
;             for (int m = 0; m < 4; ++m) { const int row = row0 + ai * HALF + m * 16; const size_t off = (size_t)row * 1024 + col0; float s = 0.f;
; #pragma unroll
;                 for (int bj = 0; bj < 2; ++bj) { f32x4 b0, b1;
;                     if (base32) { b0 = *(const f32x4*)(base32 + off + bj * HALF); b1 = *(const f32x4*)(base32 + off + bj * HALF + 4); }
;                     else { const u32x4 hv = hv4[m][bj];
;                         b0 = (f32x4){__builtin_bit_cast(float, hv.x << 16), __builtin_bit_cast(float, hv.x & 0xffff0000u), __builtin_bit_cast(float, hv.y << 16), __builtin_bit_cast(float, hv.y & 0xffff0000u)};
;                         b1 = (f32x4){__builtin_bit_cast(float, hv.z << 16), __builtin_bit_cast(float, hv.z & 0xffff0000u), __builtin_bit_cast(float, hv.w << 16), __builtin_bit_cast(float, hv.w & 0xffff0000u)}; }
;                     const f32x4 o0 = b0 + acc[ai][bj][m][0], o1 = b1 + acc[ai][bj][m][1];
;                     s += ((o0[0] * o0[0] + o0[1] * o0[1]) + (o0[2] * o0[2] + o0[3] * o0[3])) + ((o1[0] * o1[0] + o1[1] * o1[1]) + (o1[2] * o1[2] + o1[3] * o1[3]));
;                     u32x4 w; w.x = cvt_pk_bf16(o0[0], o0[1]); w.y = cvt_pk_bf16(o0[2], o0[3]); w.z = cvt_pk_bf16(o1[0], o1[1]); w.w = cvt_pk_bf16(o1[2], o1[3]); *(u32x4*)(hb + off + bj * HALF) = w; }
.LBB0_1094:
	s_waitcnt vmcnt(0)
	v_pk_add_f32 v[156:157], v[144:145], v[148:149]
	v_pk_add_f32 v[160:161], v[142:143], v[146:147]
	v_pk_add_f32 v[148:149], v[140:141], v[152:153]
	v_pk_add_f32 v[150:151], v[138:139], v[150:151]
	v_lshl_add_u64 v[146:147], v[158:159], 1, s[14:15]
	s_and_b64 vcc, exec, s[8:9]
	v_cvt_pk_bf16_f32 v138, v160, v161
	v_cvt_pk_bf16_f32 v139, v156, v157
	v_cvt_pk_bf16_f32 v140, v150, v151
	v_cvt_pk_bf16_f32 v141, v148, v149
	global_store_dwordx4 v[146:147], v[138:141], off sc1
	s_cbranch_vccnz .LBB0_1158
	global_load_dwordx4 v[142:145], v[154:155], off offset:528
	global_load_dwordx4 v[138:141], v[154:155], off offset:512
	s_cbranch_execnz .LBB0_1097

; __device__ __forceinline__ unsigned cvt_pk_bf16(float lo, float hi) { unsigned r; asm volatile("v_cvt_pk_bf16_f32 %0, %1, %2" : "=v"(r) : "v"(lo), "v"(hi)); return r; }
;     __device__ __forceinline__ void operator()(const f32x4 (&acc)[2][2][4][2], const Unit& u, int wr, int wc, int fr, int fq) const {
;     ...
;             for (int m = 0; m < 4; ++m) { const int row = row0 + ai * HALF + m * 16; const size_t off = (size_t)row * 1024 + col0; float s = 0.f;
; #pragma unroll
;                 for (int bj = 0; bj < 2; ++bj) { f32x4 b0, b1;
;                     if (base32) { b0 = *(const f32x4*)(base32 + off + bj * HALF); b1 = *(const f32x4*)(base32 + off + bj * HALF + 4); }
;                     else { const u32x4 hv = hv4[m][bj];
;                         b0 = (f32x4){__builtin_bit_cast(float, hv.x << 16), __builtin_bit_cast(float, hv.x & 0xffff0000u), __builtin_bit_cast(float, hv.y << 16), __builtin_bit_cast(float, hv.y & 0xffff0000u)};
;                         b1 = (f32x4){__builtin_bit_cast(float, hv.z << 16), __builtin_bit_cast(float, hv.z & 0xffff0000u), __builtin_bit_cast(float, hv.w << 16), __builtin_bit_cast(float, hv.w & 0xffff0000u)}; }
;                     const f32x4 o0 = b0 + acc[ai][bj][m][0], o1 = b1 + acc[ai][bj][m][1];
;                     s += ((o0[0] * o0[0] + o0[1] * o0[1]) + (o0[2] * o0[2] + o0[3] * o0[3])) + ((o1[0] * o1[0] + o1[1] * o1[1]) + (o1[2] * o1[2] + o1[3] * o1[3]));
;                     u32x4 w; w.x = cvt_pk_bf16(o0[0], o0[1]); w.y = cvt_pk_bf16(o0[2], o0[3]); w.z = cvt_pk_bf16(o1[0], o1[1]); w.w = cvt_pk_bf16(o1[2], o1[3]); *(u32x4*)(hb + off + bj * HALF) = w; }
;                 s += __shfl_xor(s, 16); s += __shfl_xor(s, 32);
;                 if (fq == 0) P[(wr * 64 + ai * HALF + m * 16 + fr) * 4 + wc] = s;
;                 asm volatile("" ::: "memory"); }
.LBB0_1097:
	s_waitcnt vmcnt(0)
	v_pk_add_f32 v[128:129], v[128:129], v[140:141]
	v_pk_add_f32 v[126:127], v[126:127], v[138:139]
	v_pk_add_f32 v[140:141], v[122:123], v[142:143]
	v_mul_f32_e32 v122, v127, v127
	v_mul_f32_e32 v123, v129, v129
	v_pk_add_f32 v[138:139], v[124:125], v[144:145]
	v_fmac_f32_e32 v122, v126, v126
	v_fmac_f32_e32 v123, v128, v128
	v_mul_f32_e32 v152, v161, v161
	v_mul_f32_e32 v153, v157, v157
	v_mul_f32_e32 v151, v151, v151
	v_mul_f32_e32 v149, v149, v149
	v_add_f32_e32 v122, v122, v123
	v_mul_f32_e32 v123, v141, v141
	v_mul_f32_e32 v124, v139, v139
	v_fmac_f32_e32 v152, v160, v160
	v_fmac_f32_e32 v153, v156, v156
	v_fmac_f32_e32 v151, v150, v150
	v_fmac_f32_e32 v149, v148, v148
	v_fmac_f32_e32 v123, v140, v140
	v_fmac_f32_e32 v124, v138, v138
	v_add_f32_e32 v152, v152, v153
	v_add_f32_e32 v148, v151, v149
	v_add_f32_e32 v123, v123, v124
	v_add_f32_e32 v148, v148, v152
	v_add_f32_e32 v122, v123, v122
	v_add_f32_e32 v122, v148, v122
	ds_bpermute_b32 v123, v164, v122
	v_cvt_pk_bf16_f32 v124, v126, v127
	v_cvt_pk_bf16_f32 v125, v128, v129
	v_cvt_pk_bf16_f32 v126, v140, v141
	v_cvt_pk_bf16_f32 v127, v138, v139
	s_waitcnt lgkmcnt(0)
	v_add_f32_e32 v122, v122, v123
	ds_bpermute_b32 v123, v165, v122
	global_store_dwordx4 v[146:147], v[124:127], off offset:256 sc1
	s_and_saveexec_b64 s[36:37], s[10:11]
	s_cbranch_execz .LBB0_1099
	s_waitcnt lgkmcnt(0)
	v_add_f32_e32 v122, v122, v123
	ds_write_b32 v162, v122 offset:256

; __device__ __forceinline__ unsigned cvt_pk_bf16(float lo, float hi) { unsigned r; asm volatile("v_cvt_pk_bf16_f32 %0, %1, %2" : "=v"(r) : "v"(lo), "v"(hi)); return r; }
;     __device__ __forceinline__ void operator()(const f32x4 (&acc)[2][2][4][2], const Unit& u, int wr, int wc, int fr, int fq) const {
;     ...
;             for (int m = 0; m < 4; ++m) { const int row = row0 + ai * HALF + m * 16; const size_t off = (size_t)row * 1024 + col0; float s = 0.f;
; #pragma unroll
;                 for (int bj = 0; bj < 2; ++bj) { f32x4 b0, b1;
;                     if (base32) { b0 = *(const f32x4*)(base32 + off + bj * HALF); b1 = *(const f32x4*)(base32 + off + bj * HALF + 4); }
;                     else { const u32x4 hv = hv4[m][bj];
;                         b0 = (f32x4){__builtin_bit_cast(float, hv.x << 16), __builtin_bit_cast(float, hv.x & 0xffff0000u), __builtin_bit_cast(float, hv.y << 16), __builtin_bit_cast(float, hv.y & 0xffff0000u)};
;                         b1 = (f32x4){__builtin_bit_cast(float, hv.z << 16), __builtin_bit_cast(float, hv.z & 0xffff0000u), __builtin_bit_cast(float, hv.w << 16), __builtin_bit_cast(float, hv.w & 0xffff0000u)}; }
;                     const f32x4 o0 = b0 + acc[ai][bj][m][0], o1 = b1 + acc[ai][bj][m][1];
;                     s += ((o0[0] * o0[0] + o0[1] * o0[1]) + (o0[2] * o0[2] + o0[3] * o0[3])) + ((o1[0] * o1[0] + o1[1] * o1[1]) + (o1[2] * o1[2] + o1[3] * o1[3]));
;                     u32x4 w; w.x = cvt_pk_bf16(o0[0], o0[1]); w.y = cvt_pk_bf16(o0[2], o0[3]); w.z = cvt_pk_bf16(o1[0], o1[1]); w.w = cvt_pk_bf16(o1[2], o1[3]); *(u32x4*)(hb + off + bj * HALF) = w; }
.LBB0_1102:
	s_waitcnt vmcnt(0)
	v_pk_add_f32 v[140:141], v[116:117], v[124:125]
	v_pk_add_f32 v[144:145], v[114:115], v[122:123]
	v_pk_add_f32 v[124:125], v[112:113], v[128:129]
	v_pk_add_f32 v[126:127], v[110:111], v[126:127]
	v_lshl_add_u64 v[122:123], v[142:143], 1, s[14:15]
	s_and_b64 vcc, exec, s[8:9]
	v_cvt_pk_bf16_f32 v110, v144, v145
	v_cvt_pk_bf16_f32 v111, v140, v141
	v_cvt_pk_bf16_f32 v112, v126, v127
	v_cvt_pk_bf16_f32 v113, v124, v125
	global_store_dwordx4 v[122:123], v[110:113], off sc1
	s_cbranch_vccnz .LBB0_1160
	global_load_dwordx4 v[114:117], v[138:139], off offset:528
	global_load_dwordx4 v[110:113], v[138:139], off offset:512
	s_cbranch_execnz .LBB0_1105

; __device__ __forceinline__ unsigned cvt_pk_bf16(float lo, float hi) { unsigned r; asm volatile("v_cvt_pk_bf16_f32 %0, %1, %2" : "=v"(r) : "v"(lo), "v"(hi)); return r; }
;     __device__ __forceinline__ void operator()(const f32x4 (&acc)[2][2][4][2], const Unit& u, int wr, int wc, int fr, int fq) const {
;     ...
;             for (int m = 0; m < 4; ++m) { const int row = row0 + ai * HALF + m * 16; const size_t off = (size_t)row * 1024 + col0; float s = 0.f;
; #pragma unroll
;                 for (int bj = 0; bj < 2; ++bj) { f32x4 b0, b1;
;                     if (base32) { b0 = *(const f32x4*)(base32 + off + bj * HALF); b1 = *(const f32x4*)(base32 + off + bj * HALF + 4); }
;                     else { const u32x4 hv = hv4[m][bj];
;                         b0 = (f32x4){__builtin_bit_cast(float, hv.x << 16), __builtin_bit_cast(float, hv.x & 0xffff0000u), __builtin_bit_cast(float, hv.y << 16), __builtin_bit_cast(float, hv.y & 0xffff0000u)};
;                         b1 = (f32x4){__builtin_bit_cast(float, hv.z << 16), __builtin_bit_cast(float, hv.z & 0xffff0000u), __builtin_bit_cast(float, hv.w << 16), __builtin_bit_cast(float, hv.w & 0xffff0000u)}; }
;                     const f32x4 o0 = b0 + acc[ai][bj][m][0], o1 = b1 + acc[ai][bj][m][1];
;                     s += ((o0[0] * o0[0] + o0[1] * o0[1]) + (o0[2] * o0[2] + o0[3] * o0[3])) + ((o1[0] * o1[0] + o1[1] * o1[1]) + (o1[2] * o1[2] + o1[3] * o1[3]));
;                     u32x4 w; w.x = cvt_pk_bf16(o0[0], o0[1]); w.y = cvt_pk_bf16(o0[2], o0[3]); w.z = cvt_pk_bf16(o1[0], o1[1]); w.w = cvt_pk_bf16(o1[2], o1[3]); *(u32x4*)(hb + off + bj * HALF) = w; }
;                 s += __shfl_xor(s, 16); s += __shfl_xor(s, 32);
;                 if (fq == 0) P[(wr * 64 + ai * HALF + m * 16 + fr) * 4 + wc] = s;
;                 asm volatile("" ::: "memory"); }
.LBB0_1105:
	s_waitcnt vmcnt(0)
	v_pk_add_f32 v[104:105], v[104:105], v[112:113]
	v_pk_add_f32 v[102:103], v[102:103], v[110:111]
	v_pk_add_f32 v[112:113], v[98:99], v[114:115]
	v_mul_f32_e32 v98, v103, v103
	v_mul_f32_e32 v99, v105, v105
	v_pk_add_f32 v[110:111], v[100:101], v[116:117]
	v_fmac_f32_e32 v98, v102, v102
	v_fmac_f32_e32 v99, v104, v104
	v_mul_f32_e32 v128, v145, v145
	v_mul_f32_e32 v129, v141, v141
	v_mul_f32_e32 v127, v127, v127
	v_mul_f32_e32 v125, v125, v125
	v_add_f32_e32 v98, v98, v99
	v_mul_f32_e32 v99, v113, v113
	v_mul_f32_e32 v100, v111, v111
	v_fmac_f32_e32 v128, v144, v144
	v_fmac_f32_e32 v129, v140, v140
	v_fmac_f32_e32 v127, v126, v126
	v_fmac_f32_e32 v125, v124, v124
	v_fmac_f32_e32 v99, v112, v112
	v_fmac_f32_e32 v100, v110, v110
	v_add_f32_e32 v128, v128, v129
	v_add_f32_e32 v124, v127, v125
	v_add_f32_e32 v99, v99, v100
	v_add_f32_e32 v124, v124, v128
	v_add_f32_e32 v98, v99, v98
	v_add_f32_e32 v98, v124, v98
	ds_bpermute_b32 v99, v164, v98
	v_cvt_pk_bf16_f32 v100, v102, v103
	v_cvt_pk_bf16_f32 v101, v104, v105
	v_cvt_pk_bf16_f32 v102, v112, v113
	v_cvt_pk_bf16_f32 v103, v110, v111
	s_waitcnt lgkmcnt(0)
	v_add_f32_e32 v98, v98, v99
	ds_bpermute_b32 v99, v165, v98
	global_store_dwordx4 v[122:123], v[100:103], off offset:256 sc1
	s_and_saveexec_b64 s[36:37], s[10:11]
	s_cbranch_execz .LBB0_1107
	s_waitcnt lgkmcnt(0)
	v_add_f32_e32 v98, v98, v99
	ds_write_b32 v162, v98 offset:512

; __device__ __forceinline__ unsigned cvt_pk_bf16(float lo, float hi) { unsigned r; asm volatile("v_cvt_pk_bf16_f32 %0, %1, %2" : "=v"(r) : "v"(lo), "v"(hi)); return r; }
;     __device__ __forceinline__ void operator()(const f32x4 (&acc)[2][2][4][2], const Unit& u, int wr, int wc, int fr, int fq) const {
;     ...
;             for (int m = 0; m < 4; ++m) { const int row = row0 + ai * HALF + m * 16; const size_t off = (size_t)row * 1024 + col0; float s = 0.f;
; #pragma unroll
;                 for (int bj = 0; bj < 2; ++bj) { f32x4 b0, b1;
;                     if (base32) { b0 = *(const f32x4*)(base32 + off + bj * HALF); b1 = *(const f32x4*)(base32 + off + bj * HALF + 4); }
;                     else { const u32x4 hv = hv4[m][bj];
;                         b0 = (f32x4){__builtin_bit_cast(float, hv.x << 16), __builtin_bit_cast(float, hv.x & 0xffff0000u), __builtin_bit_cast(float, hv.y << 16), __builtin_bit_cast(float, hv.y & 0xffff0000u)};
;                         b1 = (f32x4){__builtin_bit_cast(float, hv.z << 16), __builtin_bit_cast(float, hv.z & 0xffff0000u), __builtin_bit_cast(float, hv.w << 16), __builtin_bit_cast(float, hv.w & 0xffff0000u)}; }
;                     const f32x4 o0 = b0 + acc[ai][bj][m][0], o1 = b1 + acc[ai][bj][m][1];
;                     s += ((o0[0] * o0[0] + o0[1] * o0[1]) + (o0[2] * o0[2] + o0[3] * o0[3])) + ((o1[0] * o1[0] + o1[1] * o1[1]) + (o1[2] * o1[2] + o1[3] * o1[3]));
;                     u32x4 w; w.x = cvt_pk_bf16(o0[0], o0[1]); w.y = cvt_pk_bf16(o0[2], o0[3]); w.z = cvt_pk_bf16(o1[0], o1[1]); w.w = cvt_pk_bf16(o1[2], o1[3]); *(u32x4*)(hb + off + bj * HALF) = w; }
.LBB0_1110:
	s_waitcnt vmcnt(0)
	v_pk_add_f32 v[112:113], v[92:93], v[100:101]
	v_pk_add_f32 v[116:117], v[90:91], v[98:99]
	v_pk_add_f32 v[100:101], v[88:89], v[104:105]
	v_pk_add_f32 v[102:103], v[86:87], v[102:103]
	v_lshl_add_u64 v[98:99], v[114:115], 1, s[14:15]
	s_and_b64 vcc, exec, s[8:9]
	v_cvt_pk_bf16_f32 v86, v116, v117
	v_cvt_pk_bf16_f32 v87, v112, v113
	v_cvt_pk_bf16_f32 v88, v102, v103
	v_cvt_pk_bf16_f32 v89, v100, v101
	global_store_dwordx4 v[98:99], v[86:89], off sc1
	s_cbranch_vccnz .LBB0_1162
	global_load_dwordx4 v[90:93], v[110:111], off offset:528
	global_load_dwordx4 v[86:89], v[110:111], off offset:512
	s_cbranch_execnz .LBB0_1113

; __device__ __forceinline__ unsigned cvt_pk_bf16(float lo, float hi) { unsigned r; asm volatile("v_cvt_pk_bf16_f32 %0, %1, %2" : "=v"(r) : "v"(lo), "v"(hi)); return r; }
;     __device__ __forceinline__ void operator()(const f32x4 (&acc)[2][2][4][2], const Unit& u, int wr, int wc, int fr, int fq) const {
;     ...
;             for (int m = 0; m < 4; ++m) { const int row = row0 + ai * HALF + m * 16; const size_t off = (size_t)row * 1024 + col0; float s = 0.f;
; #pragma unroll
;                 for (int bj = 0; bj < 2; ++bj) { f32x4 b0, b1;
;                     if (base32) { b0 = *(const f32x4*)(base32 + off + bj * HALF); b1 = *(const f32x4*)(base32 + off + bj * HALF + 4); }
;                     else { const u32x4 hv = hv4[m][bj];
;                         b0 = (f32x4){__builtin_bit_cast(float, hv.x << 16), __builtin_bit_cast(float, hv.x & 0xffff0000u), __builtin_bit_cast(float, hv.y << 16), __builtin_bit_cast(float, hv.y & 0xffff0000u)};
;                         b1 = (f32x4){__builtin_bit_cast(float, hv.z << 16), __builtin_bit_cast(float, hv.z & 0xffff0000u), __builtin_bit_cast(float, hv.w << 16), __builtin_bit_cast(float, hv.w & 0xffff0000u)}; }
;                     const f32x4 o0 = b0 + acc[ai][bj][m][0], o1 = b1 + acc[ai][bj][m][1];
;                     s += ((o0[0] * o0[0] + o0[1] * o0[1]) + (o0[2] * o0[2] + o0[3] * o0[3])) + ((o1[0] * o1[0] + o1[1] * o1[1]) + (o1[2] * o1[2] + o1[3] * o1[3]));
;                     u32x4 w; w.x = cvt_pk_bf16(o0[0], o0[1]); w.y = cvt_pk_bf16(o0[2], o0[3]); w.z = cvt_pk_bf16(o1[0], o1[1]); w.w = cvt_pk_bf16(o1[2], o1[3]); *(u32x4*)(hb + off + bj * HALF) = w; }
;                 s += __shfl_xor(s, 16); s += __shfl_xor(s, 32);
;                 if (fq == 0) P[(wr * 64 + ai * HALF + m * 16 + fr) * 4 + wc] = s;
;                 asm volatile("" ::: "memory"); }
.LBB0_1113:
	s_waitcnt vmcnt(0)
	v_pk_add_f32 v[80:81], v[80:81], v[88:89]
	v_pk_add_f32 v[78:79], v[78:79], v[86:87]
	v_pk_add_f32 v[88:89], v[74:75], v[90:91]
	v_mul_f32_e32 v74, v79, v79
	v_mul_f32_e32 v75, v81, v81
	v_pk_add_f32 v[86:87], v[76:77], v[92:93]
	v_fmac_f32_e32 v74, v78, v78
	v_fmac_f32_e32 v75, v80, v80
	v_mul_f32_e32 v104, v117, v117
	v_mul_f32_e32 v105, v113, v113
	v_mul_f32_e32 v103, v103, v103
	v_mul_f32_e32 v101, v101, v101
	v_add_f32_e32 v74, v74, v75
	v_mul_f32_e32 v75, v89, v89
	v_mul_f32_e32 v76, v87, v87
	v_fmac_f32_e32 v104, v116, v116
	v_fmac_f32_e32 v105, v112, v112
	v_fmac_f32_e32 v103, v102, v102
	v_fmac_f32_e32 v101, v100, v100
	v_fmac_f32_e32 v75, v88, v88
	v_fmac_f32_e32 v76, v86, v86
	v_add_f32_e32 v104, v104, v105
	v_add_f32_e32 v100, v103, v101
	v_add_f32_e32 v75, v75, v76
	v_add_f32_e32 v100, v100, v104
	v_add_f32_e32 v74, v75, v74
	v_add_f32_e32 v74, v100, v74
	ds_bpermute_b32 v75, v164, v74
	v_cvt_pk_bf16_f32 v76, v78, v79
	v_cvt_pk_bf16_f32 v77, v80, v81
	v_cvt_pk_bf16_f32 v78, v88, v89
	v_cvt_pk_bf16_f32 v79, v86, v87
	s_waitcnt lgkmcnt(0)
	v_add_f32_e32 v74, v74, v75
	ds_bpermute_b32 v75, v165, v74
	global_store_dwordx4 v[98:99], v[76:79], off offset:256 sc1
	s_and_saveexec_b64 s[36:37], s[10:11]
	s_cbranch_execz .LBB0_1115
	s_waitcnt lgkmcnt(0)
	v_add_f32_e32 v74, v74, v75
	ds_write_b32 v162, v74 offset:768

; __device__ __forceinline__ unsigned cvt_pk_bf16(float lo, float hi) { unsigned r; asm volatile("v_cvt_pk_bf16_f32 %0, %1, %2" : "=v"(r) : "v"(lo), "v"(hi)); return r; }
;     __device__ __forceinline__ void operator()(const f32x4 (&acc)[2][2][4][2], const Unit& u, int wr, int wc, int fr, int fq) const {
;     ...
;             for (int m = 0; m < 4; ++m) { const int row = row0 + ai * HALF + m * 16; const size_t off = (size_t)row * 1024 + col0; float s = 0.f;
; #pragma unroll
;                 for (int bj = 0; bj < 2; ++bj) { f32x4 b0, b1;
;                     if (base32) { b0 = *(const f32x4*)(base32 + off + bj * HALF); b1 = *(const f32x4*)(base32 + off + bj * HALF + 4); }
;                     else { const u32x4 hv = hv4[m][bj];
;                         b0 = (f32x4){__builtin_bit_cast(float, hv.x << 16), __builtin_bit_cast(float, hv.x & 0xffff0000u), __builtin_bit_cast(float, hv.y << 16), __builtin_bit_cast(float, hv.y & 0xffff0000u)};
;                         b1 = (f32x4){__builtin_bit_cast(float, hv.z << 16), __builtin_bit_cast(float, hv.z & 0xffff0000u), __builtin_bit_cast(float, hv.w << 16), __builtin_bit_cast(float, hv.w & 0xffff0000u)}; }
;                     const f32x4 o0 = b0 + acc[ai][bj][m][0], o1 = b1 + acc[ai][bj][m][1];
;                     s += ((o0[0] * o0[0] + o0[1] * o0[1]) + (o0[2] * o0[2] + o0[3] * o0[3])) + ((o1[0] * o1[0] + o1[1] * o1[1]) + (o1[2] * o1[2] + o1[3] * o1[3]));
;                     u32x4 w; w.x = cvt_pk_bf16(o0[0], o0[1]); w.y = cvt_pk_bf16(o0[2], o0[3]); w.z = cvt_pk_bf16(o1[0], o1[1]); w.w = cvt_pk_bf16(o1[2], o1[3]); *(u32x4*)(hb + off + bj * HALF) = w; }
.LBB0_1121:
	s_waitcnt vmcnt(0)
	v_pk_add_f32 v[88:89], v[64:65], v[76:77]
	v_pk_add_f32 v[92:93], v[62:63], v[74:75]
	v_pk_add_f32 v[76:77], v[60:61], v[80:81]
	v_pk_add_f32 v[78:79], v[58:59], v[78:79]
	v_lshl_add_u64 v[74:75], v[90:91], 1, s[14:15]
	s_and_b64 vcc, exec, s[8:9]
	v_cvt_pk_bf16_f32 v58, v92, v93
	v_cvt_pk_bf16_f32 v59, v88, v89
	v_cvt_pk_bf16_f32 v60, v78, v79
	v_cvt_pk_bf16_f32 v61, v76, v77
	global_store_dwordx4 v[74:75], v[58:61], off sc1
	s_cbranch_vccnz .LBB0_1165
	global_load_dwordx4 v[62:65], v[86:87], off offset:528
	global_load_dwordx4 v[58:61], v[86:87], off offset:512
	s_cbranch_execnz .LBB0_1124

; __device__ __forceinline__ unsigned cvt_pk_bf16(float lo, float hi) { unsigned r; asm volatile("v_cvt_pk_bf16_f32 %0, %1, %2" : "=v"(r) : "v"(lo), "v"(hi)); return r; }
;     __device__ __forceinline__ void operator()(const f32x4 (&acc)[2][2][4][2], const Unit& u, int wr, int wc, int fr, int fq) const {
;     ...
;             for (int m = 0; m < 4; ++m) { const int row = row0 + ai * HALF + m * 16; const size_t off = (size_t)row * 1024 + col0; float s = 0.f;
; #pragma unroll
;                 for (int bj = 0; bj < 2; ++bj) { f32x4 b0, b1;
;                     if (base32) { b0 = *(const f32x4*)(base32 + off + bj * HALF); b1 = *(const f32x4*)(base32 + off + bj * HALF + 4); }
;                     else { const u32x4 hv = hv4[m][bj];
;                         b0 = (f32x4){__builtin_bit_cast(float, hv.x << 16), __builtin_bit_cast(float, hv.x & 0xffff0000u), __builtin_bit_cast(float, hv.y << 16), __builtin_bit_cast(float, hv.y & 0xffff0000u)};
;                         b1 = (f32x4){__builtin_bit_cast(float, hv.z << 16), __builtin_bit_cast(float, hv.z & 0xffff0000u), __builtin_bit_cast(float, hv.w << 16), __builtin_bit_cast(float, hv.w & 0xffff0000u)}; }
;                     const f32x4 o0 = b0 + acc[ai][bj][m][0], o1 = b1 + acc[ai][bj][m][1];
;                     s += ((o0[0] * o0[0] + o0[1] * o0[1]) + (o0[2] * o0[2] + o0[3] * o0[3])) + ((o1[0] * o1[0] + o1[1] * o1[1]) + (o1[2] * o1[2] + o1[3] * o1[3]));
;                     u32x4 w; w.x = cvt_pk_bf16(o0[0], o0[1]); w.y = cvt_pk_bf16(o0[2], o0[3]); w.z = cvt_pk_bf16(o1[0], o1[1]); w.w = cvt_pk_bf16(o1[2], o1[3]); *(u32x4*)(hb + off + bj * HALF) = w; }
;                 s += __shfl_xor(s, 16); s += __shfl_xor(s, 32);
;                 if (fq == 0) P[(wr * 64 + ai * HALF + m * 16 + fr) * 4 + wc] = s;
;                 asm volatile("" ::: "memory"); }
.LBB0_1124:
	s_waitcnt vmcnt(0)
	v_pk_add_f32 v[56:57], v[56:57], v[60:61]
	v_pk_add_f32 v[54:55], v[54:55], v[58:59]
	v_pk_add_f32 v[60:61], v[50:51], v[62:63]
	v_mul_f32_e32 v50, v55, v55
	v_mul_f32_e32 v51, v57, v57
	v_pk_add_f32 v[58:59], v[52:53], v[64:65]
	v_fmac_f32_e32 v50, v54, v54
	v_fmac_f32_e32 v51, v56, v56
	v_mul_f32_e32 v80, v93, v93
	v_mul_f32_e32 v81, v89, v89
	v_mul_f32_e32 v79, v79, v79
	v_mul_f32_e32 v77, v77, v77
	v_add_f32_e32 v50, v50, v51
	v_mul_f32_e32 v51, v61, v61
	v_mul_f32_e32 v52, v59, v59
	v_fmac_f32_e32 v80, v92, v92
	v_fmac_f32_e32 v81, v88, v88
	v_fmac_f32_e32 v79, v78, v78
	v_fmac_f32_e32 v77, v76, v76
	v_fmac_f32_e32 v51, v60, v60
	v_fmac_f32_e32 v52, v58, v58
	v_add_f32_e32 v80, v80, v81
	v_add_f32_e32 v76, v79, v77
	v_add_f32_e32 v51, v51, v52
	v_add_f32_e32 v76, v76, v80
	v_add_f32_e32 v50, v51, v50
	v_add_f32_e32 v50, v76, v50
	ds_bpermute_b32 v51, v164, v50
	v_cvt_pk_bf16_f32 v52, v54, v55
	v_cvt_pk_bf16_f32 v53, v56, v57
	v_cvt_pk_bf16_f32 v54, v60, v61
	v_cvt_pk_bf16_f32 v55, v58, v59
	s_waitcnt lgkmcnt(0)
	v_add_f32_e32 v50, v50, v51
	ds_bpermute_b32 v51, v165, v50
	global_store_dwordx4 v[74:75], v[52:55], off offset:256 sc1
	s_and_saveexec_b64 s[36:37], s[10:11]
	s_cbranch_execz .LBB0_1126
	s_waitcnt lgkmcnt(0)
	v_add_f32_e32 v50, v50, v51
	ds_write_b32 v162, v50 offset:2048

; __device__ __forceinline__ unsigned cvt_pk_bf16(float lo, float hi) { unsigned r; asm volatile("v_cvt_pk_bf16_f32 %0, %1, %2" : "=v"(r) : "v"(lo), "v"(hi)); return r; }
;     __device__ __forceinline__ void operator()(const f32x4 (&acc)[2][2][4][2], const Unit& u, int wr, int wc, int fr, int fq) const {
;     ...
;             for (int m = 0; m < 4; ++m) { const int row = row0 + ai * HALF + m * 16; const size_t off = (size_t)row * 1024 + col0; float s = 0.f;
; #pragma unroll
;                 for (int bj = 0; bj < 2; ++bj) { f32x4 b0, b1;
;                     if (base32) { b0 = *(const f32x4*)(base32 + off + bj * HALF); b1 = *(const f32x4*)(base32 + off + bj * HALF + 4); }
;                     else { const u32x4 hv = hv4[m][bj];
;                         b0 = (f32x4){__builtin_bit_cast(float, hv.x << 16), __builtin_bit_cast(float, hv.x & 0xffff0000u), __builtin_bit_cast(float, hv.y << 16), __builtin_bit_cast(float, hv.y & 0xffff0000u)};
;                         b1 = (f32x4){__builtin_bit_cast(float, hv.z << 16), __builtin_bit_cast(float, hv.z & 0xffff0000u), __builtin_bit_cast(float, hv.w << 16), __builtin_bit_cast(float, hv.w & 0xffff0000u)}; }
;                     const f32x4 o0 = b0 + acc[ai][bj][m][0], o1 = b1 + acc[ai][bj][m][1];
;                     s += ((o0[0] * o0[0] + o0[1] * o0[1]) + (o0[2] * o0[2] + o0[3] * o0[3])) + ((o1[0] * o1[0] + o1[1] * o1[1]) + (o1[2] * o1[2] + o1[3] * o1[3]));
;                     u32x4 w; w.x = cvt_pk_bf16(o0[0], o0[1]); w.y = cvt_pk_bf16(o0[2], o0[3]); w.z = cvt_pk_bf16(o1[0], o1[1]); w.w = cvt_pk_bf16(o1[2], o1[3]); *(u32x4*)(hb + off + bj * HALF) = w; }
.LBB0_1129:
	s_waitcnt vmcnt(0)
	v_pk_add_f32 v[60:61], v[48:49], v[52:53]
	v_pk_add_f32 v[64:65], v[46:47], v[50:51]
	v_pk_add_f32 v[52:53], v[44:45], v[56:57]
	v_pk_add_f32 v[54:55], v[42:43], v[54:55]
	v_lshl_add_u64 v[50:51], v[62:63], 1, s[14:15]
	s_and_b64 vcc, exec, s[8:9]
	v_cvt_pk_bf16_f32 v42, v64, v65
	v_cvt_pk_bf16_f32 v43, v60, v61
	v_cvt_pk_bf16_f32 v44, v54, v55
	v_cvt_pk_bf16_f32 v45, v52, v53
	global_store_dwordx4 v[50:51], v[42:45], off sc1
	s_cbranch_vccnz .LBB0_1167
	global_load_dwordx4 v[46:49], v[58:59], off offset:528
	global_load_dwordx4 v[42:45], v[58:59], off offset:512
	s_cbranch_execnz .LBB0_1132

; __device__ __forceinline__ unsigned cvt_pk_bf16(float lo, float hi) { unsigned r; asm volatile("v_cvt_pk_bf16_f32 %0, %1, %2" : "=v"(r) : "v"(lo), "v"(hi)); return r; }
;     __device__ __forceinline__ void operator()(const f32x4 (&acc)[2][2][4][2], const Unit& u, int wr, int wc, int fr, int fq) const {
;     ...
;             for (int m = 0; m < 4; ++m) { const int row = row0 + ai * HALF + m * 16; const size_t off = (size_t)row * 1024 + col0; float s = 0.f;
; #pragma unroll
;                 for (int bj = 0; bj < 2; ++bj) { f32x4 b0, b1;
;                     if (base32) { b0 = *(const f32x4*)(base32 + off + bj * HALF); b1 = *(const f32x4*)(base32 + off + bj * HALF + 4); }
;                     else { const u32x4 hv = hv4[m][bj];
;                         b0 = (f32x4){__builtin_bit_cast(float, hv.x << 16), __builtin_bit_cast(float, hv.x & 0xffff0000u), __builtin_bit_cast(float, hv.y << 16), __builtin_bit_cast(float, hv.y & 0xffff0000u)};
;                         b1 = (f32x4){__builtin_bit_cast(float, hv.z << 16), __builtin_bit_cast(float, hv.z & 0xffff0000u), __builtin_bit_cast(float, hv.w << 16), __builtin_bit_cast(float, hv.w & 0xffff0000u)}; }
;                     const f32x4 o0 = b0 + acc[ai][bj][m][0], o1 = b1 + acc[ai][bj][m][1];
;                     s += ((o0[0] * o0[0] + o0[1] * o0[1]) + (o0[2] * o0[2] + o0[3] * o0[3])) + ((o1[0] * o1[0] + o1[1] * o1[1]) + (o1[2] * o1[2] + o1[3] * o1[3]));
;                     u32x4 w; w.x = cvt_pk_bf16(o0[0], o0[1]); w.y = cvt_pk_bf16(o0[2], o0[3]); w.z = cvt_pk_bf16(o1[0], o1[1]); w.w = cvt_pk_bf16(o1[2], o1[3]); *(u32x4*)(hb + off + bj * HALF) = w; }
;                 s += __shfl_xor(s, 16); s += __shfl_xor(s, 32);
;                 if (fq == 0) P[(wr * 64 + ai * HALF + m * 16 + fr) * 4 + wc] = s;
;                 asm volatile("" ::: "memory"); }
.LBB0_1132:
	s_waitcnt vmcnt(0)
	v_pk_add_f32 v[40:41], v[40:41], v[44:45]
	v_pk_add_f32 v[38:39], v[38:39], v[42:43]
	v_pk_add_f32 v[44:45], v[34:35], v[46:47]
	v_mul_f32_e32 v34, v39, v39
	v_mul_f32_e32 v35, v41, v41
	v_pk_add_f32 v[42:43], v[36:37], v[48:49]
	v_fmac_f32_e32 v34, v38, v38
	v_fmac_f32_e32 v35, v40, v40
	v_mul_f32_e32 v56, v65, v65
	v_mul_f32_e32 v57, v61, v61
	v_mul_f32_e32 v55, v55, v55
	v_mul_f32_e32 v53, v53, v53
	v_add_f32_e32 v34, v34, v35
	v_mul_f32_e32 v35, v45, v45
	v_mul_f32_e32 v36, v43, v43
	v_fmac_f32_e32 v56, v64, v64
	v_fmac_f32_e32 v57, v60, v60
	v_fmac_f32_e32 v55, v54, v54
	v_fmac_f32_e32 v53, v52, v52
	v_fmac_f32_e32 v35, v44, v44
	v_fmac_f32_e32 v36, v42, v42
	v_add_f32_e32 v56, v56, v57
	v_add_f32_e32 v52, v55, v53
	v_add_f32_e32 v35, v35, v36
	v_add_f32_e32 v52, v52, v56
	v_add_f32_e32 v34, v35, v34
	v_add_f32_e32 v34, v52, v34
	ds_bpermute_b32 v35, v164, v34
	v_cvt_pk_bf16_f32 v36, v38, v39
	v_cvt_pk_bf16_f32 v37, v40, v41
	v_cvt_pk_bf16_f32 v38, v44, v45
	v_cvt_pk_bf16_f32 v39, v42, v43
	s_waitcnt lgkmcnt(0)
	v_add_f32_e32 v34, v34, v35
	ds_bpermute_b32 v35, v165, v34
	global_store_dwordx4 v[50:51], v[36:39], off offset:256 sc1
	s_and_saveexec_b64 s[36:37], s[10:11]
	s_cbranch_execz .LBB0_1134
	s_waitcnt lgkmcnt(0)
	v_add_f32_e32 v34, v34, v35
	ds_write_b32 v162, v34 offset:2304

; __device__ __forceinline__ unsigned cvt_pk_bf16(float lo, float hi) { unsigned r; asm volatile("v_cvt_pk_bf16_f32 %0, %1, %2" : "=v"(r) : "v"(lo), "v"(hi)); return r; }
;     __device__ __forceinline__ void operator()(const f32x4 (&acc)[2][2][4][2], const Unit& u, int wr, int wc, int fr, int fq) const {
;     ...
;             for (int m = 0; m < 4; ++m) { const int row = row0 + ai * HALF + m * 16; const size_t off = (size_t)row * 1024 + col0; float s = 0.f;
; #pragma unroll
;                 for (int bj = 0; bj < 2; ++bj) { f32x4 b0, b1;
;                     if (base32) { b0 = *(const f32x4*)(base32 + off + bj * HALF); b1 = *(const f32x4*)(base32 + off + bj * HALF + 4); }
;                     else { const u32x4 hv = hv4[m][bj];
;                         b0 = (f32x4){__builtin_bit_cast(float, hv.x << 16), __builtin_bit_cast(float, hv.x & 0xffff0000u), __builtin_bit_cast(float, hv.y << 16), __builtin_bit_cast(float, hv.y & 0xffff0000u)};
;                         b1 = (f32x4){__builtin_bit_cast(float, hv.z << 16), __builtin_bit_cast(float, hv.z & 0xffff0000u), __builtin_bit_cast(float, hv.w << 16), __builtin_bit_cast(float, hv.w & 0xffff0000u)}; }
;                     const f32x4 o0 = b0 + acc[ai][bj][m][0], o1 = b1 + acc[ai][bj][m][1];
;                     s += ((o0[0] * o0[0] + o0[1] * o0[1]) + (o0[2] * o0[2] + o0[3] * o0[3])) + ((o1[0] * o1[0] + o1[1] * o1[1]) + (o1[2] * o1[2] + o1[3] * o1[3]));
;                     u32x4 w; w.x = cvt_pk_bf16(o0[0], o0[1]); w.y = cvt_pk_bf16(o0[2], o0[3]); w.z = cvt_pk_bf16(o1[0], o1[1]); w.w = cvt_pk_bf16(o1[2], o1[3]); *(u32x4*)(hb + off + bj * HALF) = w; }
.LBB0_1137:
	s_waitcnt vmcnt(0)
	v_pk_add_f32 v[44:45], v[32:33], v[36:37]
	v_pk_add_f32 v[48:49], v[30:31], v[34:35]
	v_pk_add_f32 v[36:37], v[28:29], v[40:41]
	v_pk_add_f32 v[38:39], v[26:27], v[38:39]
	v_lshl_add_u64 v[34:35], v[46:47], 1, s[14:15]
	s_and_b64 vcc, exec, s[8:9]
	v_cvt_pk_bf16_f32 v26, v48, v49
	v_cvt_pk_bf16_f32 v27, v44, v45
	v_cvt_pk_bf16_f32 v28, v38, v39
	v_cvt_pk_bf16_f32 v29, v36, v37
	global_store_dwordx4 v[34:35], v[26:29], off sc1
	s_cbranch_vccnz .LBB0_1169
	global_load_dwordx4 v[30:33], v[42:43], off offset:528
	global_load_dwordx4 v[26:29], v[42:43], off offset:512
	s_cbranch_execnz .LBB0_1140

; __device__ __forceinline__ unsigned cvt_pk_bf16(float lo, float hi) { unsigned r; asm volatile("v_cvt_pk_bf16_f32 %0, %1, %2" : "=v"(r) : "v"(lo), "v"(hi)); return r; }
;     __device__ __forceinline__ void operator()(const f32x4 (&acc)[2][2][4][2], const Unit& u, int wr, int wc, int fr, int fq) const {
;     ...
;             for (int m = 0; m < 4; ++m) { const int row = row0 + ai * HALF + m * 16; const size_t off = (size_t)row * 1024 + col0; float s = 0.f;
; #pragma unroll
;                 for (int bj = 0; bj < 2; ++bj) { f32x4 b0, b1;
;                     if (base32) { b0 = *(const f32x4*)(base32 + off + bj * HALF); b1 = *(const f32x4*)(base32 + off + bj * HALF + 4); }
;                     else { const u32x4 hv = hv4[m][bj];
;                         b0 = (f32x4){__builtin_bit_cast(float, hv.x << 16), __builtin_bit_cast(float, hv.x & 0xffff0000u), __builtin_bit_cast(float, hv.y << 16), __builtin_bit_cast(float, hv.y & 0xffff0000u)};
;                         b1 = (f32x4){__builtin_bit_cast(float, hv.z << 16), __builtin_bit_cast(float, hv.z & 0xffff0000u), __builtin_bit_cast(float, hv.w << 16), __builtin_bit_cast(float, hv.w & 0xffff0000u)}; }
;                     const f32x4 o0 = b0 + acc[ai][bj][m][0], o1 = b1 + acc[ai][bj][m][1];
;                     s += ((o0[0] * o0[0] + o0[1] * o0[1]) + (o0[2] * o0[2] + o0[3] * o0[3])) + ((o1[0] * o1[0] + o1[1] * o1[1]) + (o1[2] * o1[2] + o1[3] * o1[3]));
;                     u32x4 w; w.x = cvt_pk_bf16(o0[0], o0[1]); w.y = cvt_pk_bf16(o0[2], o0[3]); w.z = cvt_pk_bf16(o1[0], o1[1]); w.w = cvt_pk_bf16(o1[2], o1[3]); *(u32x4*)(hb + off + bj * HALF) = w; }
;                 s += __shfl_xor(s, 16); s += __shfl_xor(s, 32);
;                 if (fq == 0) P[(wr * 64 + ai * HALF + m * 16 + fr) * 4 + wc] = s;
;                 asm volatile("" ::: "memory"); }
.LBB0_1140:
	s_waitcnt vmcnt(0)
	v_pk_add_f32 v[24:25], v[24:25], v[28:29]
	v_pk_add_f32 v[22:23], v[22:23], v[26:27]
	v_pk_add_f32 v[28:29], v[18:19], v[30:31]
	v_mul_f32_e32 v18, v23, v23
	v_mul_f32_e32 v19, v25, v25
	v_pk_add_f32 v[26:27], v[20:21], v[32:33]
	v_fmac_f32_e32 v18, v22, v22
	v_fmac_f32_e32 v19, v24, v24
	v_mul_f32_e32 v40, v49, v49
	v_mul_f32_e32 v41, v45, v45
	v_mul_f32_e32 v39, v39, v39
	v_mul_f32_e32 v37, v37, v37
	v_add_f32_e32 v18, v18, v19
	v_mul_f32_e32 v19, v29, v29
	v_mul_f32_e32 v20, v27, v27
	v_fmac_f32_e32 v40, v48, v48
	v_fmac_f32_e32 v41, v44, v44
	v_fmac_f32_e32 v39, v38, v38
	v_fmac_f32_e32 v37, v36, v36
	v_fmac_f32_e32 v19, v28, v28
	v_fmac_f32_e32 v20, v26, v26
	v_add_f32_e32 v40, v40, v41
	v_add_f32_e32 v36, v39, v37
	v_add_f32_e32 v19, v19, v20
	v_add_f32_e32 v36, v36, v40
	v_add_f32_e32 v18, v19, v18
	v_add_f32_e32 v18, v36, v18
	ds_bpermute_b32 v19, v164, v18
	v_cvt_pk_bf16_f32 v20, v22, v23
	v_cvt_pk_bf16_f32 v21, v24, v25
	v_cvt_pk_bf16_f32 v22, v28, v29
	v_cvt_pk_bf16_f32 v23, v26, v27
	s_waitcnt lgkmcnt(0)
	v_add_f32_e32 v18, v18, v19
	ds_bpermute_b32 v19, v165, v18
	global_store_dwordx4 v[34:35], v[20:23], off offset:256 sc1
	s_and_saveexec_b64 s[36:37], s[10:11]
	s_cbranch_execz .LBB0_1142
	s_waitcnt lgkmcnt(0)
	v_add_f32_e32 v18, v18, v19
	ds_write_b32 v162, v18 offset:2560

; __device__ __forceinline__ unsigned cvt_pk_bf16(float lo, float hi) { unsigned r; asm volatile("v_cvt_pk_bf16_f32 %0, %1, %2" : "=v"(r) : "v"(lo), "v"(hi)); return r; }
;     __device__ __forceinline__ void operator()(const f32x4 (&acc)[2][2][4][2], const Unit& u, int wr, int wc, int fr, int fq) const {
;     ...
;             for (int m = 0; m < 4; ++m) { const int row = row0 + ai * HALF + m * 16; const size_t off = (size_t)row * 1024 + col0; float s = 0.f;
; #pragma unroll
;                 for (int bj = 0; bj < 2; ++bj) { f32x4 b0, b1;
;                     if (base32) { b0 = *(const f32x4*)(base32 + off + bj * HALF); b1 = *(const f32x4*)(base32 + off + bj * HALF + 4); }
;                     else { const u32x4 hv = hv4[m][bj];
;                         b0 = (f32x4){__builtin_bit_cast(float, hv.x << 16), __builtin_bit_cast(float, hv.x & 0xffff0000u), __builtin_bit_cast(float, hv.y << 16), __builtin_bit_cast(float, hv.y & 0xffff0000u)};
;                         b1 = (f32x4){__builtin_bit_cast(float, hv.z << 16), __builtin_bit_cast(float, hv.z & 0xffff0000u), __builtin_bit_cast(float, hv.w << 16), __builtin_bit_cast(float, hv.w & 0xffff0000u)}; }
;                     const f32x4 o0 = b0 + acc[ai][bj][m][0], o1 = b1 + acc[ai][bj][m][1];
;                     s += ((o0[0] * o0[0] + o0[1] * o0[1]) + (o0[2] * o0[2] + o0[3] * o0[3])) + ((o1[0] * o1[0] + o1[1] * o1[1]) + (o1[2] * o1[2] + o1[3] * o1[3]));
;                     u32x4 w; w.x = cvt_pk_bf16(o0[0], o0[1]); w.y = cvt_pk_bf16(o0[2], o0[3]); w.z = cvt_pk_bf16(o1[0], o1[1]); w.w = cvt_pk_bf16(o1[2], o1[3]); *(u32x4*)(hb + off + bj * HALF) = w; }
.LBB0_1145:
	s_waitcnt vmcnt(0)
	v_pk_add_f32 v[28:29], v[16:17], v[20:21]
	v_pk_add_f32 v[32:33], v[14:15], v[18:19]
	v_pk_add_f32 v[20:21], v[12:13], v[24:25]
	v_pk_add_f32 v[22:23], v[10:11], v[22:23]
	v_lshl_add_u64 v[18:19], v[30:31], 1, s[14:15]
	s_and_b64 vcc, exec, s[8:9]
	v_cvt_pk_bf16_f32 v10, v32, v33
	v_cvt_pk_bf16_f32 v11, v28, v29
	v_cvt_pk_bf16_f32 v12, v22, v23
	v_cvt_pk_bf16_f32 v13, v20, v21
	global_store_dwordx4 v[18:19], v[10:13], off sc1
	s_cbranch_vccnz .LBB0_1171
	global_load_dwordx4 v[14:17], v[26:27], off offset:528
	global_load_dwordx4 v[10:13], v[26:27], off offset:512
	s_cbranch_execnz .LBB0_1148

; #define PG8_LAS __attribute__((address_space(3)))
; __device__ __forceinline__ unsigned cvt_pk_bf16(float lo, float hi) { unsigned r; asm volatile("v_cvt_pk_bf16_f32 %0, %1, %2" : "=v"(r) : "v"(lo), "v"(hi)); return r; }
;     __device__ __forceinline__ void operator()(const f32x4 (&acc)[2][2][4][2], const Unit& u, int wr, int wc, int fr, int fq) const {
;     ...
;             for (int m = 0; m < 4; ++m) { const int row = row0 + ai * HALF + m * 16; const size_t off = (size_t)row * 1024 + col0; float s = 0.f;
; #pragma unroll
;                 for (int bj = 0; bj < 2; ++bj) { f32x4 b0, b1;
;                     if (base32) { b0 = *(const f32x4*)(base32 + off + bj * HALF); b1 = *(const f32x4*)(base32 + off + bj * HALF + 4); }
;                     else { const u32x4 hv = hv4[m][bj];
;                         b0 = (f32x4){__builtin_bit_cast(float, hv.x << 16), __builtin_bit_cast(float, hv.x & 0xffff0000u), __builtin_bit_cast(float, hv.y << 16), __builtin_bit_cast(float, hv.y & 0xffff0000u)};
;                         b1 = (f32x4){__builtin_bit_cast(float, hv.z << 16), __builtin_bit_cast(float, hv.z & 0xffff0000u), __builtin_bit_cast(float, hv.w << 16), __builtin_bit_cast(float, hv.w & 0xffff0000u)}; }
;                     const f32x4 o0 = b0 + acc[ai][bj][m][0], o1 = b1 + acc[ai][bj][m][1];
;                     s += ((o0[0] * o0[0] + o0[1] * o0[1]) + (o0[2] * o0[2] + o0[3] * o0[3])) + ((o1[0] * o1[0] + o1[1] * o1[1]) + (o1[2] * o1[2] + o1[3] * o1[3]));
;                     u32x4 w; w.x = cvt_pk_bf16(o0[0], o0[1]); w.y = cvt_pk_bf16(o0[2], o0[3]); w.z = cvt_pk_bf16(o1[0], o1[1]); w.w = cvt_pk_bf16(o1[2], o1[3]); *(u32x4*)(hb + off + bj * HALF) = w; }
;                 s += __shfl_xor(s, 16); s += __shfl_xor(s, 32);
;                 if (fq == 0) P[(wr * 64 + ai * HALF + m * 16 + fr) * 4 + wc] = s;
;                 asm volatile("" ::: "memory"); }
;         }
;         asm volatile("s_waitcnt lgkmcnt(0)" ::: "memory"); __builtin_amdgcn_s_barrier(); asm volatile("" ::: "memory");
;         { const int t = (wr * 4 + wc) * 64 + fq * 16 + fr; if (t < 256) { const f32x4 v = *(const PG8_LAS f32x4*)(P + t * 4); ssq[(size_t)(row_off + u.pm * BM + t) * 4 + u.pn] = (v[0] + v[1]) + (v[2] + v[3]); } }
.LBB0_1148:
	s_waitcnt vmcnt(0)
	v_pk_add_f32 v[8:9], v[8:9], v[12:13]
	v_pk_add_f32 v[6:7], v[6:7], v[10:11]
	v_pk_add_f32 v[12:13], v[2:3], v[14:15]
	v_mul_f32_e32 v2, v7, v7
	v_mul_f32_e32 v3, v9, v9
	v_pk_add_f32 v[10:11], v[4:5], v[16:17]
	v_fmac_f32_e32 v2, v6, v6
	v_fmac_f32_e32 v3, v8, v8
	v_mul_f32_e32 v24, v33, v33
	v_mul_f32_e32 v25, v29, v29
	v_mul_f32_e32 v23, v23, v23
	v_mul_f32_e32 v21, v21, v21
	v_add_f32_e32 v2, v2, v3
	v_mul_f32_e32 v3, v13, v13
	v_mul_f32_e32 v4, v11, v11
	v_fmac_f32_e32 v24, v32, v32
	v_fmac_f32_e32 v25, v28, v28
	v_fmac_f32_e32 v23, v22, v22
	v_fmac_f32_e32 v21, v20, v20
	v_fmac_f32_e32 v3, v12, v12
	v_fmac_f32_e32 v4, v10, v10
	v_add_f32_e32 v24, v24, v25
	v_add_f32_e32 v20, v23, v21
	v_add_f32_e32 v3, v3, v4
	v_add_f32_e32 v20, v20, v24
	v_add_f32_e32 v2, v3, v2
	v_add_f32_e32 v2, v20, v2
	ds_bpermute_b32 v3, v164, v2
	v_cvt_pk_bf16_f32 v4, v6, v7
	v_cvt_pk_bf16_f32 v5, v8, v9
	v_cvt_pk_bf16_f32 v6, v12, v13
	v_cvt_pk_bf16_f32 v7, v10, v11
	s_waitcnt lgkmcnt(0)
	v_add_f32_e32 v2, v2, v3
	ds_bpermute_b32 v3, v165, v2
	global_store_dwordx4 v[18:19], v[4:7], off offset:256 sc1
	s_and_saveexec_b64 s[8:9], s[10:11]
	s_cbranch_execz .LBB0_1150
	s_waitcnt lgkmcnt(0)
	v_add_f32_e32 v2, v2, v3
	ds_write_b32 v162, v2 offset:2816
.LBB0_1150:
	s_or_b64 exec, exec, s[8:9]
	s_waitcnt lgkmcnt(0)
	s_barrier
	v_lshlrev_b32_e32 v2, 4, v206
	v_add3_u32 v2, s52, v205, v2
	v_cmp_gt_i32_e32 vcc, s91, v2
	s_and_saveexec_b64 s[8:9], vcc
	s_cbranch_execz .LBB0_1152
	s_waitcnt lgkmcnt(0)
	v_lshl_add_u32 v3, v2, 4, 0
	v_add_u32_e32 v3, 0x20000, v3
	ds_read_b128 v[4:7], v3
	v_add_u32_e32 v2, s25, v2
	v_ashrrev_i32_e32 v3, 31, v2
	s_ashr_i32 s25, s24, 31
	v_lshl_add_u64 v[2:3], v[2:3], 4, s[16:17]
	s_waitcnt lgkmcnt(0)
	v_mov_b32_e32 v8, v5
	v_mov_b32_e32 v9, v6
	v_mov_b32_e32 v5, v7
	v_pk_add_f32 v[4:5], v[8:9], v[4:5]
	v_lshl_add_u64 v[2:3], s[24:25], 2, v[2:3]
	v_add_f32_e32 v4, v4, v5
	global_store_dword v[2:3], v4, off sc1

; __device__ __forceinline__ unsigned cvt_pk_bf16(float lo, float hi) { unsigned r; asm volatile("v_cvt_pk_bf16_f32 %0, %1, %2" : "=v"(r) : "v"(lo), "v"(hi)); return r; }
;     __device__ __forceinline__ void operator()(const f32x4 (&acc)[2][2][4][2], const Unit& u, int wr, int wc, int fr, int fq) const {
;     ...
;         const int row0 = row_off + u.pm * BM + wr * 64 + fr, col0 = u.pn * BM + wc * 32 + 8 * fq;
; #pragma unroll
;         for (int ai = 0; ai < 2; ++ai) {
;             u32x4 hv4[4][2];
;             if (!base32) {
; #pragma unroll
;                 for (int m = 0; m < 4; ++m)
; #pragma unroll
;                     for (int bj = 0; bj < 2; ++bj) hv4[m][bj] = *(const u32x4*)(hb + (size_t)(row0 + ai * HALF + m * 16) * 1024 + col0 + bj * HALF);
;             }
; #pragma unroll
;             for (int m = 0; m < 4; ++m) { const int row = row0 + ai * HALF + m * 16; const size_t off = (size_t)row * 1024 + col0; float s = 0.f;
; #pragma unroll
;                 for (int bj = 0; bj < 2; ++bj) { f32x4 b0, b1;
;                     if (base32) { b0 = *(const f32x4*)(base32 + off + bj * HALF); b1 = *(const f32x4*)(base32 + off + bj * HALF + 4); }
;                     else { const u32x4 hv = hv4[m][bj];
;                         b0 = (f32x4){__builtin_bit_cast(float, hv.x << 16), __builtin_bit_cast(float, hv.x & 0xffff0000u), __builtin_bit_cast(float, hv.y << 16), __builtin_bit_cast(float, hv.y & 0xffff0000u)};
;                         b1 = (f32x4){__builtin_bit_cast(float, hv.z << 16), __builtin_bit_cast(float, hv.z & 0xffff0000u), __builtin_bit_cast(float, hv.w << 16), __builtin_bit_cast(float, hv.w & 0xffff0000u)}; }
;                     const f32x4 o0 = b0 + acc[ai][bj][m][0], o1 = b1 + acc[ai][bj][m][1];
;                     s += ((o0[0] * o0[0] + o0[1] * o0[1]) + (o0[2] * o0[2] + o0[3] * o0[3])) + ((o1[0] * o1[0] + o1[1] * o1[1]) + (o1[2] * o1[2] + o1[3] * o1[3]));
;                     u32x4 w; w.x = cvt_pk_bf16(o0[0], o0[1]); w.y = cvt_pk_bf16(o0[2], o0[3]); w.z = cvt_pk_bf16(o1[0], o1[1]); w.w = cvt_pk_bf16(o1[2], o1[3]); *(u32x4*)(hb + off + bj * HALF) = w; }
;                 s += __shfl_xor(s, 16); s += __shfl_xor(s, 32);
;                 if (fq == 0) P[(wr * 64 + ai * HALF + m * 16 + fr) * 4 + wc] = s;
;                 asm volatile("" ::: "memory"); }
.LBB0_1363:
	s_lshl_b32 s8, s16, 8
	v_mov_b32_e32 v187, v184
	v_mov_b32_e32 v188, v1
	s_or_b32 s8, s8, s40
	s_lshl_b32 s17, s17, 8
	v_add_u32_e32 v189, s39, v187
	v_lshl_add_u32 v166, v188, 3, s8
	v_add_u32_e32 v170, s17, v189
	v_ashrrev_i32_e32 v167, 31, v166
	v_lshlrev_b64 v[198:199], 1, v[166:167]
	v_ashrrev_i32_e32 v171, 31, v170
	v_lshl_add_u64 v[168:169], s[10:11], 0, v[198:199]
	v_lshlrev_b64 v[200:201], 11, v[170:171]
	v_lshl_add_u64 v[114:115], v[168:169], 0, v[200:201]
	global_load_dwordx4 v[190:193], v[114:115], off
	global_load_dwordx4 v[194:197], v[114:115], off offset:256
	v_lshl_add_u64 v[182:183], v[200:201], 0, s[66:67]
	s_mov_b64 s[8:9], 0x10000
	v_lshl_add_u64 v[114:115], v[168:169], 0, v[182:183]
	v_lshl_add_u64 v[180:181], v[200:201], 0, s[8:9]
	s_mov_b64 s[8:9], 0x18000
	global_load_dwordx4 v[150:153], v[114:115], off
	global_load_dwordx4 v[146:149], v[114:115], off offset:256
	v_lshl_add_u64 v[114:115], v[168:169], 0, v[180:181]
	v_lshl_add_u64 v[172:173], v[200:201], 0, s[8:9]
	global_load_dwordx4 v[134:137], v[114:115], off
	global_load_dwordx4 v[122:125], v[114:115], off offset:256
	v_lshl_add_u64 v[114:115], v[168:169], 0, v[172:173]
	global_load_dwordx4 v[118:121], v[114:115], off
	s_nop 0
	global_load_dwordx4 v[114:117], v[114:115], off offset:256
	v_cmp_eq_u32_e32 vcc, 0, v188
	s_waitcnt vmcnt(0)
	v_lshlrev_b32_e32 v202, 16, v190
	v_and_b32_e32 v203, 0xffff0000, v190
	v_lshlrev_b32_e32 v190, 16, v191
	v_and_b32_e32 v191, 0xffff0000, v191
	v_lshlrev_b32_e32 v204, 16, v192
	v_and_b32_e32 v205, 0xffff0000, v192
	v_lshlrev_b32_e32 v192, 16, v193
	v_and_b32_e32 v193, 0xffff0000, v193
	v_pk_add_f32 v[144:145], v[144:145], v[190:191]
	v_pk_add_f32 v[142:143], v[142:143], v[202:203]
	v_pk_add_f32 v[190:191], v[140:141], v[192:193]
	v_pk_add_f32 v[140:141], v[138:139], v[204:205]
	v_mul_f32_e32 v138, v143, v143
	v_mul_f32_e32 v139, v145, v145
	v_fmac_f32_e32 v138, v142, v142
	v_fmac_f32_e32 v139, v144, v144
	v_add_f32_e32 v138, v138, v139
	v_mul_f32_e32 v139, v141, v141
	v_mul_f32_e32 v192, v191, v191
	v_fmac_f32_e32 v139, v140, v140
	v_fmac_f32_e32 v192, v190, v190
	v_add_f32_e32 v139, v139, v192
	v_add_f32_e32 v192, v138, v139
	v_cvt_pk_bf16_f32 v138, v142, v143
	v_lshl_add_u64 v[142:143], s[10:11], 0, v[200:201]
	v_cvt_pk_bf16_f32 v139, v144, v145
	v_cvt_pk_bf16_f32 v140, v140, v141
	v_cvt_pk_bf16_f32 v141, v190, v191
	v_lshl_add_u64 v[142:143], v[142:143], 0, v[198:199]
	global_store_dwordx4 v[142:143], v[138:141], off sc1
	v_lshlrev_b32_e32 v144, 16, v196
	v_and_b32_e32 v145, 0xffff0000, v196
	v_lshlrev_b32_e32 v138, 16, v194
	v_and_b32_e32 v139, 0xffff0000, v194
	v_lshlrev_b32_e32 v140, 16, v195
	v_and_b32_e32 v141, 0xffff0000, v195
	v_lshlrev_b32_e32 v190, 16, v197
	v_and_b32_e32 v191, 0xffff0000, v197
	v_pk_add_f32 v[132:133], v[132:133], v[140:141]
	v_pk_add_f32 v[130:131], v[130:131], v[138:139]
	v_pk_add_f32 v[138:139], v[128:129], v[190:191]
	v_pk_add_f32 v[128:129], v[126:127], v[144:145]
	v_mul_f32_e32 v126, v131, v131
	v_mul_f32_e32 v127, v133, v133
	v_fmac_f32_e32 v126, v130, v130
	v_fmac_f32_e32 v127, v132, v132
	v_add_f32_e32 v126, v126, v127
	v_mul_f32_e32 v127, v129, v129
	v_mul_f32_e32 v140, v139, v139
	v_fmac_f32_e32 v127, v128, v128
	v_fmac_f32_e32 v140, v138, v138
	v_add_f32_e32 v127, v127, v140
	v_add_f32_e32 v126, v126, v127
	v_add_f32_e32 v140, v192, v126
	v_cvt_pk_bf16_f32 v126, v130, v131
	v_cvt_pk_bf16_f32 v127, v132, v133
	v_cvt_pk_bf16_f32 v128, v128, v129
	v_cvt_pk_bf16_f32 v129, v138, v139
	global_store_dwordx4 v[142:143], v[126:129], off offset:256 sc1
	s_nop 1
	v_and_b32_e32 v127, 64, v225
	v_xor_b32_e32 v126, 16, v225
	v_add_u32_e32 v127, 64, v127
	v_cmp_lt_i32_e64 s[8:9], v126, v127
	s_nop 1
	v_cndmask_b32_e64 v126, v225, v126, s[8:9]
	v_lshlrev_b32_e32 v126, 2, v126
	ds_bpermute_b32 v128, v126, v140
	s_waitcnt lgkmcnt(0)
	v_add_f32_e32 v129, v140, v128
	v_xor_b32_e32 v128, 32, v225
	v_cmp_lt_i32_e64 s[8:9], v128, v127
	s_nop 1
	v_cndmask_b32_e64 v127, v225, v128, s[8:9]
	v_lshlrev_b32_e32 v127, 2, v127
	ds_bpermute_b32 v130, v127, v129
	v_lshl_add_u32 v128, v189, 4, s44
	s_and_saveexec_b64 s[8:9], vcc
	s_cbranch_execz .LBB0_1365
	s_waitcnt lgkmcnt(0)
	v_add_f32_e32 v129, v129, v130
	ds_write_b32 v128, v129
.LBB0_1365:
	s_or_b64 exec, exec, s[8:9]
	s_waitcnt lgkmcnt(0)
	v_lshlrev_b32_e32 v130, 16, v150
	v_and_b32_e32 v131, 0xffff0000, v150
	v_lshlrev_b32_e32 v132, 16, v151
	v_and_b32_e32 v133, 0xffff0000, v151
	v_lshlrev_b32_e32 v138, 16, v152
	v_and_b32_e32 v139, 0xffff0000, v152
	v_lshlrev_b32_e32 v140, 16, v153
	v_and_b32_e32 v141, 0xffff0000, v153
	v_pk_add_f32 v[112:113], v[112:113], v[132:133]
	v_pk_add_f32 v[110:111], v[110:111], v[130:131]
	v_pk_add_f32 v[130:131], v[108:109], v[140:141]
	v_pk_add_f32 v[108:109], v[106:107], v[138:139]
	v_mul_f32_e32 v106, v111, v111
	v_mul_f32_e32 v107, v113, v113
	v_fmac_f32_e32 v106, v110, v110
	v_fmac_f32_e32 v107, v112, v112
	v_add_f32_e32 v106, v106, v107
	v_mul_f32_e32 v107, v109, v109
	v_mul_f32_e32 v129, v131, v131
	v_fmac_f32_e32 v107, v108, v108
	v_fmac_f32_e32 v129, v130, v130
	v_add_f32_e32 v107, v107, v129
	v_add_f32_e32 v129, v106, v107
	v_cvt_pk_bf16_f32 v106, v110, v111
	v_cvt_pk_bf16_f32 v107, v112, v113
	v_lshlrev_b32_e32 v110, 16, v146
	v_and_b32_e32 v111, 0xffff0000, v146
	v_lshlrev_b32_e32 v112, 16, v147
	v_and_b32_e32 v113, 0xffff0000, v147
	v_cvt_pk_bf16_f32 v108, v108, v109
	v_cvt_pk_bf16_f32 v109, v130, v131
	v_lshlrev_b32_e32 v130, 16, v148
	v_and_b32_e32 v131, 0xffff0000, v148
	v_pk_add_f32 v[104:105], v[104:105], v[112:113]
	v_pk_add_f32 v[102:103], v[102:103], v[110:111]
	v_lshlrev_b32_e32 v132, 16, v149
	v_and_b32_e32 v133, 0xffff0000, v149
	v_pk_add_f32 v[112:113], v[98:99], v[130:131]
	v_mul_f32_e32 v98, v103, v103
	v_mul_f32_e32 v99, v105, v105
	v_pk_add_f32 v[110:111], v[100:101], v[132:133]
	v_fmac_f32_e32 v98, v102, v102
	v_fmac_f32_e32 v99, v104, v104
	v_add_f32_e32 v98, v98, v99
	v_mul_f32_e32 v99, v113, v113
	v_mul_f32_e32 v100, v111, v111
	v_fmac_f32_e32 v99, v112, v112
	v_fmac_f32_e32 v100, v110, v110
	v_add_f32_e32 v99, v99, v100
	v_add_f32_e32 v98, v98, v99
	v_add_f32_e32 v101, v129, v98
	ds_bpermute_b32 v129, v126, v101
	v_lshl_add_u64 v[98:99], s[10:11], 0, v[182:183]
	v_lshl_add_u64 v[130:131], v[166:167], 1, v[98:99]
	global_store_dwordx4 v[130:131], v[106:109], off sc1
	v_cvt_pk_bf16_f32 v100, v102, v103
	s_waitcnt lgkmcnt(0)
	v_add_f32_e32 v98, v101, v129
	ds_bpermute_b32 v99, v127, v98
	v_cvt_pk_bf16_f32 v101, v104, v105
	v_cvt_pk_bf16_f32 v102, v112, v113
	v_cvt_pk_bf16_f32 v103, v110, v111
	global_store_dwordx4 v[130:131], v[100:103], off offset:256 sc1
	s_and_saveexec_b64 s[8:9], vcc
	s_cbranch_execz .LBB0_1367
	s_waitcnt lgkmcnt(0)
	v_add_f32_e32 v98, v98, v99
	ds_write_b32 v128, v98 offset:256
; __device__ __forceinline__ unsigned cvt_pk_bf16(float lo, float hi) { unsigned r; asm volatile("v_cvt_pk_bf16_f32 %0, %1, %2" : "=v"(r) : "v"(lo), "v"(hi)); return r; }
;     __device__ __forceinline__ void operator()(const f32x4 (&acc)[2][2][4][2], const Unit& u, int wr, int wc, int fr, int fq) const {
;     ...
;             for (int m = 0; m < 4; ++m) { const int row = row0 + ai * HALF + m * 16; const size_t off = (size_t)row * 1024 + col0; float s = 0.f;
; #pragma unroll
;                 for (int bj = 0; bj < 2; ++bj) { f32x4 b0, b1;
;                     if (base32) { b0 = *(const f32x4*)(base32 + off + bj * HALF); b1 = *(const f32x4*)(base32 + off + bj * HALF + 4); }
;                     else { const u32x4 hv = hv4[m][bj];
;                         b0 = (f32x4){__builtin_bit_cast(float, hv.x << 16), __builtin_bit_cast(float, hv.x & 0xffff0000u), __builtin_bit_cast(float, hv.y << 16), __builtin_bit_cast(float, hv.y & 0xffff0000u)};
;                         b1 = (f32x4){__builtin_bit_cast(float, hv.z << 16), __builtin_bit_cast(float, hv.z & 0xffff0000u), __builtin_bit_cast(float, hv.w << 16), __builtin_bit_cast(float, hv.w & 0xffff0000u)}; }
;                     const f32x4 o0 = b0 + acc[ai][bj][m][0], o1 = b1 + acc[ai][bj][m][1];
;                     s += ((o0[0] * o0[0] + o0[1] * o0[1]) + (o0[2] * o0[2] + o0[3] * o0[3])) + ((o1[0] * o1[0] + o1[1] * o1[1]) + (o1[2] * o1[2] + o1[3] * o1[3]));
;                     u32x4 w; w.x = cvt_pk_bf16(o0[0], o0[1]); w.y = cvt_pk_bf16(o0[2], o0[3]); w.z = cvt_pk_bf16(o1[0], o1[1]); w.w = cvt_pk_bf16(o1[2], o1[3]); *(u32x4*)(hb + off + bj * HALF) = w; }
;                 s += __shfl_xor(s, 16); s += __shfl_xor(s, 32);
;                 if (fq == 0) P[(wr * 64 + ai * HALF + m * 16 + fr) * 4 + wc] = s;
;                 asm volatile("" ::: "memory"); }
.LBB0_1367:
	s_or_b64 exec, exec, s[8:9]
	v_lshlrev_b32_e32 v98, 16, v134
	s_waitcnt lgkmcnt(0)
	v_and_b32_e32 v99, 0xffff0000, v134
	v_lshlrev_b32_e32 v100, 16, v135
	v_and_b32_e32 v101, 0xffff0000, v135
	v_lshlrev_b32_e32 v102, 16, v136
	v_and_b32_e32 v103, 0xffff0000, v136
	v_lshlrev_b32_e32 v104, 16, v137
	v_and_b32_e32 v105, 0xffff0000, v137
	v_pk_add_f32 v[96:97], v[96:97], v[100:101]
	v_pk_add_f32 v[94:95], v[94:95], v[98:99]
	v_pk_add_f32 v[98:99], v[92:93], v[104:105]
	v_pk_add_f32 v[92:93], v[90:91], v[102:103]
	v_mul_f32_e32 v90, v95, v95
	v_mul_f32_e32 v91, v97, v97
	v_fmac_f32_e32 v90, v94, v94
	v_fmac_f32_e32 v91, v96, v96
	v_add_f32_e32 v90, v90, v91
	v_mul_f32_e32 v91, v93, v93
	v_mul_f32_e32 v100, v99, v99
	v_fmac_f32_e32 v91, v92, v92
	v_fmac_f32_e32 v100, v98, v98
	v_add_f32_e32 v91, v91, v100
	v_add_f32_e32 v102, v90, v91
	v_cvt_pk_bf16_f32 v90, v94, v95
	v_cvt_pk_bf16_f32 v91, v96, v97
	v_lshlrev_b32_e32 v94, 16, v122
	v_and_b32_e32 v95, 0xffff0000, v122
	v_lshlrev_b32_e32 v96, 16, v123
	v_and_b32_e32 v97, 0xffff0000, v123
	v_cvt_pk_bf16_f32 v92, v92, v93
	v_cvt_pk_bf16_f32 v93, v98, v99
	v_lshlrev_b32_e32 v98, 16, v124
	v_and_b32_e32 v99, 0xffff0000, v124
	v_pk_add_f32 v[88:89], v[88:89], v[96:97]
	v_pk_add_f32 v[86:87], v[86:87], v[94:95]
	v_lshlrev_b32_e32 v100, 16, v125
	v_and_b32_e32 v101, 0xffff0000, v125
	v_pk_add_f32 v[96:97], v[82:83], v[98:99]
	v_mul_f32_e32 v82, v87, v87
	v_mul_f32_e32 v83, v89, v89
	v_pk_add_f32 v[94:95], v[84:85], v[100:101]
	v_fmac_f32_e32 v82, v86, v86
	v_fmac_f32_e32 v83, v88, v88
	v_add_f32_e32 v82, v82, v83
	v_mul_f32_e32 v83, v97, v97
	v_mul_f32_e32 v84, v95, v95
	v_fmac_f32_e32 v83, v96, v96
	v_fmac_f32_e32 v84, v94, v94
	v_add_f32_e32 v83, v83, v84
	v_add_f32_e32 v82, v82, v83
	v_add_f32_e32 v85, v102, v82
	ds_bpermute_b32 v100, v126, v85
	v_lshl_add_u64 v[82:83], s[10:11], 0, v[180:181]
	v_lshl_add_u64 v[98:99], v[166:167], 1, v[82:83]
	global_store_dwordx4 v[98:99], v[90:93], off sc1
	v_cvt_pk_bf16_f32 v84, v86, v87
	s_waitcnt lgkmcnt(0)
	v_add_f32_e32 v82, v85, v100
	ds_bpermute_b32 v83, v127, v82
	v_cvt_pk_bf16_f32 v85, v88, v89
	v_cvt_pk_bf16_f32 v86, v96, v97
	v_cvt_pk_bf16_f32 v87, v94, v95
	global_store_dwordx4 v[98:99], v[84:87], off offset:256 sc1
	s_and_saveexec_b64 s[8:9], vcc
	s_cbranch_execz .LBB0_1369
	s_waitcnt lgkmcnt(0)
	v_add_f32_e32 v82, v82, v83
	ds_write_b32 v128, v82 offset:512
.LBB0_1369:
	s_or_b64 exec, exec, s[8:9]
	v_lshlrev_b32_e32 v82, 16, v118
	s_waitcnt lgkmcnt(0)
	v_and_b32_e32 v83, 0xffff0000, v118
	v_lshlrev_b32_e32 v84, 16, v119
	v_and_b32_e32 v85, 0xffff0000, v119
	v_lshlrev_b32_e32 v86, 16, v120
	v_and_b32_e32 v87, 0xffff0000, v120
	v_lshlrev_b32_e32 v88, 16, v121
	v_and_b32_e32 v89, 0xffff0000, v121
	v_pk_add_f32 v[80:81], v[80:81], v[84:85]
	v_pk_add_f32 v[78:79], v[78:79], v[82:83]
	v_pk_add_f32 v[82:83], v[76:77], v[88:89]
	v_pk_add_f32 v[76:77], v[74:75], v[86:87]
	v_mul_f32_e32 v74, v79, v79
	v_mul_f32_e32 v75, v81, v81
	v_fmac_f32_e32 v74, v78, v78
	v_fmac_f32_e32 v75, v80, v80
	v_add_f32_e32 v74, v74, v75
	v_mul_f32_e32 v75, v77, v77
	v_mul_f32_e32 v84, v83, v83
	v_fmac_f32_e32 v75, v76, v76
	v_fmac_f32_e32 v84, v82, v82
	v_add_f32_e32 v75, v75, v84
	v_add_f32_e32 v86, v74, v75
	v_cvt_pk_bf16_f32 v74, v78, v79
	v_cvt_pk_bf16_f32 v75, v80, v81
	v_lshlrev_b32_e32 v78, 16, v114
	v_and_b32_e32 v79, 0xffff0000, v114
	v_lshlrev_b32_e32 v80, 16, v115
	v_and_b32_e32 v81, 0xffff0000, v115
	v_cvt_pk_bf16_f32 v76, v76, v77
	v_cvt_pk_bf16_f32 v77, v82, v83
	v_lshlrev_b32_e32 v82, 16, v116
	v_and_b32_e32 v83, 0xffff0000, v116
	v_pk_add_f32 v[72:73], v[72:73], v[80:81]
	v_pk_add_f32 v[70:71], v[70:71], v[78:79]
	v_lshlrev_b32_e32 v84, 16, v117
	v_and_b32_e32 v85, 0xffff0000, v117
	v_pk_add_f32 v[80:81], v[66:67], v[82:83]
	v_mul_f32_e32 v66, v71, v71
	v_mul_f32_e32 v67, v73, v73
	v_pk_add_f32 v[78:79], v[68:69], v[84:85]
	v_fmac_f32_e32 v66, v70, v70
	v_fmac_f32_e32 v67, v72, v72
	v_add_f32_e32 v66, v66, v67
	v_mul_f32_e32 v67, v81, v81
	v_mul_f32_e32 v68, v79, v79
	v_fmac_f32_e32 v67, v80, v80
	v_fmac_f32_e32 v68, v78, v78
	v_add_f32_e32 v67, v67, v68
	v_add_f32_e32 v66, v66, v67
	v_add_f32_e32 v69, v86, v66
	ds_bpermute_b32 v84, v126, v69
	v_lshl_add_u64 v[66:67], s[10:11], 0, v[172:173]
	v_lshl_add_u64 v[82:83], v[166:167], 1, v[66:67]
	global_store_dwordx4 v[82:83], v[74:77], off sc1
	v_cvt_pk_bf16_f32 v68, v70, v71
	s_waitcnt lgkmcnt(0)
	v_add_f32_e32 v66, v69, v84
	ds_bpermute_b32 v67, v127, v66
	v_cvt_pk_bf16_f32 v69, v72, v73
	v_cvt_pk_bf16_f32 v70, v80, v81
	v_cvt_pk_bf16_f32 v71, v78, v79
	global_store_dwordx4 v[82:83], v[68:71], off offset:256 sc1
	s_and_saveexec_b64 s[8:9], vcc
	s_cbranch_execz .LBB0_1371
	s_waitcnt lgkmcnt(0)
	v_add_f32_e32 v66, v66, v67
	ds_write_b32 v128, v66 offset:768
; __device__ __forceinline__ unsigned cvt_pk_bf16(float lo, float hi) { unsigned r; asm volatile("v_cvt_pk_bf16_f32 %0, %1, %2" : "=v"(r) : "v"(lo), "v"(hi)); return r; }
;     __device__ __forceinline__ void operator()(const f32x4 (&acc)[2][2][4][2], const Unit& u, int wr, int wc, int fr, int fq) const {
;     ...
;         for (int ai = 0; ai < 2; ++ai) {
;             u32x4 hv4[4][2];
;             if (!base32) {
; #pragma unroll
;                 for (int m = 0; m < 4; ++m)
; #pragma unroll
;                     for (int bj = 0; bj < 2; ++bj) hv4[m][bj] = *(const u32x4*)(hb + (size_t)(row0 + ai * HALF + m * 16) * 1024 + col0 + bj * HALF);
;             }
; #pragma unroll
;             for (int m = 0; m < 4; ++m) { const int row = row0 + ai * HALF + m * 16; const size_t off = (size_t)row * 1024 + col0; float s = 0.f;
; #pragma unroll
;                 for (int bj = 0; bj < 2; ++bj) { f32x4 b0, b1;
;                     if (base32) { b0 = *(const f32x4*)(base32 + off + bj * HALF); b1 = *(const f32x4*)(base32 + off + bj * HALF + 4); }
;                     else { const u32x4 hv = hv4[m][bj];
;                         b0 = (f32x4){__builtin_bit_cast(float, hv.x << 16), __builtin_bit_cast(float, hv.x & 0xffff0000u), __builtin_bit_cast(float, hv.y << 16), __builtin_bit_cast(float, hv.y & 0xffff0000u)};
;                         b1 = (f32x4){__builtin_bit_cast(float, hv.z << 16), __builtin_bit_cast(float, hv.z & 0xffff0000u), __builtin_bit_cast(float, hv.w << 16), __builtin_bit_cast(float, hv.w & 0xffff0000u)}; }
;                     const f32x4 o0 = b0 + acc[ai][bj][m][0], o1 = b1 + acc[ai][bj][m][1];
;                     s += ((o0[0] * o0[0] + o0[1] * o0[1]) + (o0[2] * o0[2] + o0[3] * o0[3])) + ((o1[0] * o1[0] + o1[1] * o1[1]) + (o1[2] * o1[2] + o1[3] * o1[3]));
;                     u32x4 w; w.x = cvt_pk_bf16(o0[0], o0[1]); w.y = cvt_pk_bf16(o0[2], o0[3]); w.z = cvt_pk_bf16(o1[0], o1[1]); w.w = cvt_pk_bf16(o1[2], o1[3]); *(u32x4*)(hb + off + bj * HALF) = w; }
;                 s += __shfl_xor(s, 16); s += __shfl_xor(s, 32);
;                 if (fq == 0) P[(wr * 64 + ai * HALF + m * 16 + fr) * 4 + wc] = s;
;                 asm volatile("" ::: "memory"); }
.LBB0_1371:
	s_or_b64 exec, exec, s[8:9]
	s_waitcnt lgkmcnt(0)
	v_lshlrev_b64 v[66:67], 11, v[170:171]
	s_mov_b64 s[8:9], 0x40000
	v_lshl_add_u64 v[104:105], v[66:67], 0, s[8:9]
	v_lshl_add_u64 v[68:69], v[168:169], 0, v[104:105]
	global_load_dwordx4 v[96:99], v[68:69], off
	global_load_dwordx4 v[100:103], v[68:69], off offset:256
	s_mov_b64 s[8:9], 0x48000
	v_lshl_add_u64 v[94:95], v[66:67], 0, s[8:9]
	s_mov_b64 s[8:9], 0x50000
	v_lshl_add_u64 v[92:93], v[66:67], 0, s[8:9]
	s_mov_b64 s[8:9], 0x58000
	v_lshl_add_u64 v[68:69], v[168:169], 0, v[94:95]
	v_lshl_add_u64 v[90:91], v[66:67], 0, s[8:9]
	global_load_dwordx4 v[86:89], v[68:69], off
	global_load_dwordx4 v[82:85], v[68:69], off offset:256
	v_lshl_add_u64 v[68:69], v[168:169], 0, v[92:93]
	v_lshl_add_u64 v[66:67], v[168:169], 0, v[90:91]
	global_load_dwordx4 v[78:81], v[68:69], off
	global_load_dwordx4 v[74:77], v[68:69], off offset:256
	global_load_dwordx4 v[70:73], v[66:67], off
	s_nop 0
	global_load_dwordx4 v[66:69], v[66:67], off offset:256
	s_waitcnt vmcnt(7)
	v_lshlrev_b32_e32 v106, 16, v96
	v_and_b32_e32 v107, 0xffff0000, v96
	v_lshlrev_b32_e32 v96, 16, v97
	v_and_b32_e32 v97, 0xffff0000, v97
	v_lshlrev_b32_e32 v108, 16, v98
	v_and_b32_e32 v109, 0xffff0000, v98
	v_lshlrev_b32_e32 v98, 16, v99
	v_and_b32_e32 v99, 0xffff0000, v99
	v_pk_add_f32 v[64:65], v[64:65], v[96:97]
	v_pk_add_f32 v[62:63], v[62:63], v[106:107]
	v_pk_add_f32 v[96:97], v[60:61], v[98:99]
	v_mul_f32_e32 v60, v63, v63
	v_mul_f32_e32 v61, v65, v65
	v_pk_add_f32 v[58:59], v[58:59], v[108:109]
	v_fmac_f32_e32 v60, v62, v62
	v_fmac_f32_e32 v61, v64, v64
	v_add_f32_e32 v60, v60, v61
	v_mul_f32_e32 v61, v59, v59
	v_mul_f32_e32 v98, v97, v97
	v_fmac_f32_e32 v61, v58, v58
	v_fmac_f32_e32 v98, v96, v96
	v_add_f32_e32 v61, v61, v98
	v_add_f32_e32 v98, v60, v61
	v_cvt_pk_bf16_f32 v60, v62, v63
	v_cvt_pk_bf16_f32 v61, v64, v65
	v_cvt_pk_bf16_f32 v62, v58, v59
	v_lshl_add_u64 v[58:59], s[10:11], 0, v[104:105]
	v_cvt_pk_bf16_f32 v63, v96, v97
	v_lshl_add_u64 v[58:59], v[166:167], 1, v[58:59]
	global_store_dwordx4 v[58:59], v[60:63], off sc1
	s_waitcnt vmcnt(7)
	v_lshlrev_b32_e32 v64, 16, v102
	v_and_b32_e32 v65, 0xffff0000, v102
	v_lshlrev_b32_e32 v60, 16, v100
	v_and_b32_e32 v61, 0xffff0000, v100
	v_lshlrev_b32_e32 v62, 16, v101
	v_and_b32_e32 v63, 0xffff0000, v101
	v_lshlrev_b32_e32 v96, 16, v103
	v_and_b32_e32 v97, 0xffff0000, v103
	v_pk_add_f32 v[56:57], v[56:57], v[62:63]
	v_pk_add_f32 v[54:55], v[54:55], v[60:61]
	v_pk_add_f32 v[60:61], v[52:53], v[96:97]
	v_pk_add_f32 v[52:53], v[50:51], v[64:65]
	v_mul_f32_e32 v50, v55, v55
	v_mul_f32_e32 v51, v57, v57
	v_fmac_f32_e32 v50, v54, v54
	v_fmac_f32_e32 v51, v56, v56
	v_add_f32_e32 v50, v50, v51
	v_mul_f32_e32 v51, v53, v53
	v_mul_f32_e32 v62, v61, v61
	v_fmac_f32_e32 v51, v52, v52
	v_fmac_f32_e32 v62, v60, v60
	v_add_f32_e32 v51, v51, v62
	v_add_f32_e32 v50, v50, v51
	v_add_f32_e32 v62, v98, v50
	v_cvt_pk_bf16_f32 v50, v54, v55
	v_cvt_pk_bf16_f32 v51, v56, v57
	v_cvt_pk_bf16_f32 v52, v52, v53
	v_cvt_pk_bf16_f32 v53, v60, v61
	global_store_dwordx4 v[58:59], v[50:53], off offset:256 sc1
	ds_bpermute_b32 v50, v126, v62
	s_waitcnt lgkmcnt(0)
	v_add_f32_e32 v50, v62, v50
	ds_bpermute_b32 v51, v127, v50
	s_and_saveexec_b64 s[8:9], vcc
	s_cbranch_execz .LBB0_1373
	s_waitcnt lgkmcnt(0)
	v_add_f32_e32 v50, v50, v51
	ds_write_b32 v128, v50 offset:2048
.LBB0_1373:
	s_or_b64 exec, exec, s[8:9]
	s_waitcnt vmcnt(7)
	v_lshlrev_b32_e32 v50, 16, v86
	s_waitcnt lgkmcnt(0)
	v_and_b32_e32 v51, 0xffff0000, v86
	v_lshlrev_b32_e32 v52, 16, v87
	v_and_b32_e32 v53, 0xffff0000, v87
	v_lshlrev_b32_e32 v54, 16, v88
	v_and_b32_e32 v55, 0xffff0000, v88
	v_lshlrev_b32_e32 v56, 16, v89
	v_and_b32_e32 v57, 0xffff0000, v89
	v_pk_add_f32 v[48:49], v[48:49], v[52:53]
	v_pk_add_f32 v[46:47], v[46:47], v[50:51]
	v_pk_add_f32 v[50:51], v[44:45], v[56:57]
	v_pk_add_f32 v[44:45], v[42:43], v[54:55]
	v_mul_f32_e32 v42, v47, v47
	v_mul_f32_e32 v43, v49, v49
	v_fmac_f32_e32 v42, v46, v46
	v_fmac_f32_e32 v43, v48, v48
	v_add_f32_e32 v42, v42, v43
	v_mul_f32_e32 v43, v45, v45
	v_mul_f32_e32 v52, v51, v51
	v_fmac_f32_e32 v43, v44, v44
	v_fmac_f32_e32 v52, v50, v50
	v_add_f32_e32 v43, v43, v52
	v_add_f32_e32 v54, v42, v43
	v_cvt_pk_bf16_f32 v42, v46, v47
	v_cvt_pk_bf16_f32 v43, v48, v49
	s_waitcnt vmcnt(6)
	v_lshlrev_b32_e32 v46, 16, v82
	v_and_b32_e32 v47, 0xffff0000, v82
	v_lshlrev_b32_e32 v48, 16, v83
	v_and_b32_e32 v49, 0xffff0000, v83
	v_cvt_pk_bf16_f32 v44, v44, v45
	v_cvt_pk_bf16_f32 v45, v50, v51
	v_lshlrev_b32_e32 v50, 16, v84
	v_and_b32_e32 v51, 0xffff0000, v84
	v_pk_add_f32 v[40:41], v[40:41], v[48:49]
	v_pk_add_f32 v[38:39], v[38:39], v[46:47]
	v_lshlrev_b32_e32 v52, 16, v85
	v_and_b32_e32 v53, 0xffff0000, v85
	v_pk_add_f32 v[48:49], v[34:35], v[50:51]
	v_mul_f32_e32 v34, v39, v39
	v_mul_f32_e32 v35, v41, v41
	v_pk_add_f32 v[46:47], v[36:37], v[52:53]
	v_fmac_f32_e32 v34, v38, v38
	v_fmac_f32_e32 v35, v40, v40
	v_add_f32_e32 v34, v34, v35
	v_mul_f32_e32 v35, v49, v49
	v_mul_f32_e32 v36, v47, v47
	v_fmac_f32_e32 v35, v48, v48
	v_fmac_f32_e32 v36, v46, v46
	v_add_f32_e32 v35, v35, v36
	v_add_f32_e32 v34, v34, v35
	v_add_f32_e32 v37, v54, v34
	ds_bpermute_b32 v52, v126, v37
	v_lshl_add_u64 v[34:35], s[10:11], 0, v[94:95]
	v_lshl_add_u64 v[50:51], v[166:167], 1, v[34:35]
	global_store_dwordx4 v[50:51], v[42:45], off sc1
	v_cvt_pk_bf16_f32 v36, v38, v39
	s_waitcnt lgkmcnt(0)
	v_add_f32_e32 v34, v37, v52
	ds_bpermute_b32 v35, v127, v34
	v_cvt_pk_bf16_f32 v37, v40, v41
	v_cvt_pk_bf16_f32 v38, v48, v49
	v_cvt_pk_bf16_f32 v39, v46, v47
	global_store_dwordx4 v[50:51], v[36:39], off offset:256 sc1
	s_and_saveexec_b64 s[8:9], vcc
	s_cbranch_execz .LBB0_1375
	s_waitcnt lgkmcnt(0)
	v_add_f32_e32 v34, v34, v35
	ds_write_b32 v128, v34 offset:2304
; #define PG8_LAS __attribute__((address_space(3)))
; __device__ __forceinline__ unsigned cvt_pk_bf16(float lo, float hi) { unsigned r; asm volatile("v_cvt_pk_bf16_f32 %0, %1, %2" : "=v"(r) : "v"(lo), "v"(hi)); return r; }
;     __device__ __forceinline__ void operator()(const f32x4 (&acc)[2][2][4][2], const Unit& u, int wr, int wc, int fr, int fq) const {
;     ...
;             for (int m = 0; m < 4; ++m) { const int row = row0 + ai * HALF + m * 16; const size_t off = (size_t)row * 1024 + col0; float s = 0.f;
; #pragma unroll
;                 for (int bj = 0; bj < 2; ++bj) { f32x4 b0, b1;
;                     if (base32) { b0 = *(const f32x4*)(base32 + off + bj * HALF); b1 = *(const f32x4*)(base32 + off + bj * HALF + 4); }
;                     else { const u32x4 hv = hv4[m][bj];
;                         b0 = (f32x4){__builtin_bit_cast(float, hv.x << 16), __builtin_bit_cast(float, hv.x & 0xffff0000u), __builtin_bit_cast(float, hv.y << 16), __builtin_bit_cast(float, hv.y & 0xffff0000u)};
;                         b1 = (f32x4){__builtin_bit_cast(float, hv.z << 16), __builtin_bit_cast(float, hv.z & 0xffff0000u), __builtin_bit_cast(float, hv.w << 16), __builtin_bit_cast(float, hv.w & 0xffff0000u)}; }
;                     const f32x4 o0 = b0 + acc[ai][bj][m][0], o1 = b1 + acc[ai][bj][m][1];
;                     s += ((o0[0] * o0[0] + o0[1] * o0[1]) + (o0[2] * o0[2] + o0[3] * o0[3])) + ((o1[0] * o1[0] + o1[1] * o1[1]) + (o1[2] * o1[2] + o1[3] * o1[3]));
;                     u32x4 w; w.x = cvt_pk_bf16(o0[0], o0[1]); w.y = cvt_pk_bf16(o0[2], o0[3]); w.z = cvt_pk_bf16(o1[0], o1[1]); w.w = cvt_pk_bf16(o1[2], o1[3]); *(u32x4*)(hb + off + bj * HALF) = w; }
;                 s += __shfl_xor(s, 16); s += __shfl_xor(s, 32);
;                 if (fq == 0) P[(wr * 64 + ai * HALF + m * 16 + fr) * 4 + wc] = s;
;                 asm volatile("" ::: "memory"); }
;         }
;         asm volatile("s_waitcnt lgkmcnt(0)" ::: "memory"); __builtin_amdgcn_s_barrier(); asm volatile("" ::: "memory");
;         { const int t = (wr * 4 + wc) * 64 + fq * 16 + fr; if (t < 256) { const f32x4 v = *(const PG8_LAS f32x4*)(P + t * 4); ssq[(size_t)(row_off + u.pm * BM + t) * 4 + u.pn] = (v[0] + v[1]) + (v[2] + v[3]); } }
.LBB0_1375:
	s_or_b64 exec, exec, s[8:9]
	s_waitcnt vmcnt(7)
	v_lshlrev_b32_e32 v34, 16, v78
	s_waitcnt lgkmcnt(0)
	v_and_b32_e32 v35, 0xffff0000, v78
	v_lshlrev_b32_e32 v36, 16, v79
	v_and_b32_e32 v37, 0xffff0000, v79
	v_lshlrev_b32_e32 v38, 16, v80
	v_and_b32_e32 v39, 0xffff0000, v80
	v_lshlrev_b32_e32 v40, 16, v81
	v_and_b32_e32 v41, 0xffff0000, v81
	v_pk_add_f32 v[32:33], v[32:33], v[36:37]
	v_pk_add_f32 v[30:31], v[30:31], v[34:35]
	v_pk_add_f32 v[34:35], v[28:29], v[40:41]
	v_pk_add_f32 v[28:29], v[26:27], v[38:39]
	v_mul_f32_e32 v26, v31, v31
	v_mul_f32_e32 v27, v33, v33
	v_fmac_f32_e32 v26, v30, v30
	v_fmac_f32_e32 v27, v32, v32
	v_add_f32_e32 v26, v26, v27
	v_mul_f32_e32 v27, v29, v29
	v_mul_f32_e32 v36, v35, v35
	v_fmac_f32_e32 v27, v28, v28
	v_fmac_f32_e32 v36, v34, v34
	v_add_f32_e32 v27, v27, v36
	v_add_f32_e32 v38, v26, v27
	v_cvt_pk_bf16_f32 v26, v30, v31
	v_cvt_pk_bf16_f32 v27, v32, v33
	s_waitcnt vmcnt(6)
	v_lshlrev_b32_e32 v30, 16, v74
	v_and_b32_e32 v31, 0xffff0000, v74
	v_lshlrev_b32_e32 v32, 16, v75
	v_and_b32_e32 v33, 0xffff0000, v75
	v_cvt_pk_bf16_f32 v28, v28, v29
	v_cvt_pk_bf16_f32 v29, v34, v35
	v_lshlrev_b32_e32 v34, 16, v76
	v_and_b32_e32 v35, 0xffff0000, v76
	v_pk_add_f32 v[24:25], v[24:25], v[32:33]
	v_pk_add_f32 v[22:23], v[22:23], v[30:31]
	v_lshlrev_b32_e32 v36, 16, v77
	v_and_b32_e32 v37, 0xffff0000, v77
	v_pk_add_f32 v[32:33], v[18:19], v[34:35]
	v_mul_f32_e32 v18, v23, v23
	v_mul_f32_e32 v19, v25, v25
	v_pk_add_f32 v[30:31], v[20:21], v[36:37]
	v_fmac_f32_e32 v18, v22, v22
	v_fmac_f32_e32 v19, v24, v24
	v_add_f32_e32 v18, v18, v19
	v_mul_f32_e32 v19, v33, v33
	v_mul_f32_e32 v20, v31, v31
	v_fmac_f32_e32 v19, v32, v32
	v_fmac_f32_e32 v20, v30, v30
	v_add_f32_e32 v19, v19, v20
	v_add_f32_e32 v18, v18, v19
	v_add_f32_e32 v21, v38, v18
	ds_bpermute_b32 v36, v126, v21
	v_lshl_add_u64 v[18:19], s[10:11], 0, v[92:93]
	v_lshl_add_u64 v[34:35], v[166:167], 1, v[18:19]
	global_store_dwordx4 v[34:35], v[26:29], off sc1
	v_cvt_pk_bf16_f32 v20, v22, v23
	s_waitcnt lgkmcnt(0)
	v_add_f32_e32 v18, v21, v36
	ds_bpermute_b32 v19, v127, v18
	v_cvt_pk_bf16_f32 v21, v24, v25
	v_cvt_pk_bf16_f32 v22, v32, v33
	v_cvt_pk_bf16_f32 v23, v30, v31
	global_store_dwordx4 v[34:35], v[20:23], off offset:256 sc1
	s_and_saveexec_b64 s[8:9], vcc
	s_cbranch_execz .LBB0_1377
	s_waitcnt lgkmcnt(0)
	v_add_f32_e32 v18, v18, v19
	ds_write_b32 v128, v18 offset:2560
.LBB0_1377:
	s_or_b64 exec, exec, s[8:9]
	s_waitcnt vmcnt(7)
	v_lshlrev_b32_e32 v18, 16, v70
	s_waitcnt lgkmcnt(0)
	v_and_b32_e32 v19, 0xffff0000, v70
	v_lshlrev_b32_e32 v20, 16, v71
	v_and_b32_e32 v21, 0xffff0000, v71
	v_lshlrev_b32_e32 v22, 16, v72
	v_and_b32_e32 v23, 0xffff0000, v72
	v_lshlrev_b32_e32 v24, 16, v73
	v_and_b32_e32 v25, 0xffff0000, v73
	v_pk_add_f32 v[16:17], v[16:17], v[20:21]
	v_pk_add_f32 v[14:15], v[14:15], v[18:19]
	v_pk_add_f32 v[18:19], v[12:13], v[24:25]
	v_pk_add_f32 v[12:13], v[10:11], v[22:23]
	v_mul_f32_e32 v10, v15, v15
	v_mul_f32_e32 v11, v17, v17
	v_fmac_f32_e32 v10, v14, v14
	v_fmac_f32_e32 v11, v16, v16
	v_add_f32_e32 v10, v10, v11
	v_mul_f32_e32 v11, v13, v13
	v_mul_f32_e32 v20, v19, v19
	v_fmac_f32_e32 v11, v12, v12
	v_fmac_f32_e32 v20, v18, v18
	v_add_f32_e32 v11, v11, v20
	v_add_f32_e32 v22, v10, v11
	v_cvt_pk_bf16_f32 v10, v14, v15
	v_cvt_pk_bf16_f32 v11, v16, v17
	s_waitcnt vmcnt(6)
	v_lshlrev_b32_e32 v14, 16, v66
	v_and_b32_e32 v15, 0xffff0000, v66
	v_lshlrev_b32_e32 v16, 16, v67
	v_and_b32_e32 v17, 0xffff0000, v67
	v_cvt_pk_bf16_f32 v12, v12, v13
	v_cvt_pk_bf16_f32 v13, v18, v19
	v_lshlrev_b32_e32 v18, 16, v68
	v_and_b32_e32 v19, 0xffff0000, v68
	v_pk_add_f32 v[8:9], v[8:9], v[16:17]
	v_pk_add_f32 v[6:7], v[6:7], v[14:15]
	v_lshlrev_b32_e32 v20, 16, v69
	v_and_b32_e32 v21, 0xffff0000, v69
	v_pk_add_f32 v[16:17], v[2:3], v[18:19]
	v_mul_f32_e32 v2, v7, v7
	v_mul_f32_e32 v3, v9, v9
	v_pk_add_f32 v[14:15], v[4:5], v[20:21]
	v_fmac_f32_e32 v2, v6, v6
	v_fmac_f32_e32 v3, v8, v8
	v_add_f32_e32 v2, v2, v3
	v_mul_f32_e32 v3, v17, v17
	v_mul_f32_e32 v4, v15, v15
	v_fmac_f32_e32 v3, v16, v16
	v_fmac_f32_e32 v4, v14, v14
	v_add_f32_e32 v3, v3, v4
	v_add_f32_e32 v2, v2, v3
	v_add_f32_e32 v5, v22, v2
	ds_bpermute_b32 v20, v126, v5
	v_lshl_add_u64 v[2:3], s[10:11], 0, v[90:91]
	v_lshl_add_u64 v[18:19], v[166:167], 1, v[2:3]
	global_store_dwordx4 v[18:19], v[10:13], off sc1
	v_cvt_pk_bf16_f32 v4, v6, v7
	s_waitcnt lgkmcnt(0)
	v_add_f32_e32 v2, v5, v20
	ds_bpermute_b32 v3, v127, v2
	v_cvt_pk_bf16_f32 v5, v8, v9
	v_cvt_pk_bf16_f32 v6, v16, v17
	v_cvt_pk_bf16_f32 v7, v14, v15
	global_store_dwordx4 v[18:19], v[4:7], off offset:256 sc1
	s_and_saveexec_b64 s[8:9], vcc
	s_cbranch_execz .LBB0_1379
	s_waitcnt lgkmcnt(0)
	v_add_f32_e32 v2, v2, v3
	ds_write_b32 v128, v2 offset:2816
.LBB0_1379:
	s_or_b64 exec, exec, s[8:9]
	s_waitcnt lgkmcnt(0)
	s_barrier
	v_lshlrev_b32_e32 v2, 4, v188
	v_add3_u32 v2, s43, v187, v2
	v_cmp_gt_i32_e32 vcc, s91, v2
	s_and_saveexec_b64 s[8:9], vcc
	s_cbranch_execz .LBB0_1381
	s_waitcnt lgkmcnt(0)
	v_lshl_add_u32 v3, v2, 4, 0
	v_add_u32_e32 v3, 0x20000, v3
	ds_read_b128 v[4:7], v3
	v_add_u32_e32 v2, s17, v2
	v_ashrrev_i32_e32 v3, 31, v2
	s_ashr_i32 s17, s16, 31
	v_lshl_add_u64 v[2:3], v[2:3], 4, s[12:13]
	s_waitcnt lgkmcnt(0)
	v_mov_b32_e32 v8, v5
	v_mov_b32_e32 v9, v6
	v_mov_b32_e32 v5, v7
	v_pk_add_f32 v[4:5], v[8:9], v[4:5]
	v_lshl_add_u64 v[2:3], s[16:17], 2, v[2:3]
	v_add_f32_e32 v4, v4, v5
	global_store_dword v[2:3], v4, off sc1
